# static s_setprio 1 at entry for one block of each co-resident pair ((b>>8)^(b>>3))&1; removed symmetric setprio toggles around outproj
# speedup vs baseline: 1.0161x; 1.0139x over previous
_Z14fwd_megakernel6Params:
	s_load_dwordx16 s[36:51], s[0:1], 0x80
	s_load_dword s3, s[0:1], 0xc0
	s_add_u32 s4, s0, 0xc0
	s_addc_u32 s5, s1, 0
	s_getreg_b32 s6, hwreg(HW_REG_XCC_ID, 0, 4)
	s_waitcnt lgkmcnt(0)
	s_lshr_b32 s7, s2, 5
	s_xor_b32 s7, s7, s2
	s_bitcmp1_b32 s7, 3
	s_cbranch_scc0 .Lmy_prio_skip
	s_setprio 1
.Lmy_prio_skip:
	s_add_u32 s96, s50, 0x1180000
	s_addc_u32 s97, s51, 0
	s_and_b32 s6, s6, 15
	v_and_b32_e32 v131, 0x3ff, v0
	v_writelane_b32 v247, s6, 0
	v_cmp_eq_u32_e64 s[8:9], 0, v131
	s_mov_b64 s[6:7], exec
	s_nop 0
	v_writelane_b32 v247, s8, 1
	s_nop 1
	v_writelane_b32 v247, s9, 2
	s_and_b64 s[8:9], s[6:7], s[8:9]
	s_mov_b64 exec, s[8:9]
	s_cbranch_execz .LBB0_3
	s_mov_b64 s[10:11], src_shared_base
	v_mov_b32_e32 v2, 0x10010
	v_mov_b32_e32 v3, s11
	v_mov_b32_e32 v1, 0
	s_mov_b64 s[8:9], exec
	flat_store_dword v[2:3], v1 sc0 sc1
	s_waitcnt vmcnt(0)
	v_mov_b32_e32 v2, 0x10014
	flat_store_dword v[2:3], v1 sc0 sc1
	s_waitcnt vmcnt(0)
	v_mbcnt_lo_u32_b32 v1, s8, 0
	v_mbcnt_hi_u32_b32 v1, s9, v1
	v_cmp_eq_u32_e32 vcc, 0, v1
	s_and_b64 s[10:11], exec, vcc
	s_mov_b64 exec, s[10:11]
	s_cbranch_execz .LBB0_3
	v_readlane_b32 s10, v247, 0
	s_lshl_b32 s10, s10, 8
	s_bcnt1_i32_b64 s8, s[8:9]
	v_mov_b32_e32 v1, s10
	v_mov_b32_e32 v2, s8
	global_atomic_add v1, v2, s[96:97] offset:1024

.LBB0_171:
	s_lshr_b32 s88, s75, 3
	s_lshl_b32 s88, s88, 4
	s_and_b32 s90, s75, 7
	s_or_b32 s88, s88, s90
	s_lshl_b32 s90, s89, 3
	s_add_i32 s88, s88, s90
	s_ashr_i32 s1, s88, 31
	s_lshr_b32 s1, s1, 23
	s_add_i32 s1, s88, s1
	s_ashr_i32 s1, s1, 9
	s_and_b32 s0, s88, 7
	s_lshl_b32 s1, s1, 3
	s_or_b32 s34, s1, s0
	s_mul_hi_i32 s0, s34, 0x92492493
	s_add_i32 s0, s0, s34
	s_lshr_b32 s1, s0, 31
	s_ashr_i32 s70, s0, 2
	s_add_i32 s70, s70, s1
	s_lshl_b32 s0, s70, 3
	s_bfe_u32 s1, s88, 0x30003
	s_or_b32 s66, s0, s1
	s_mul_i32 s0, s70, 7
	s_sub_i32 s77, s34, s0
	s_lshl_b32 s0, s77, 3
	s_bfe_u32 s76, s88, 0x30006
	s_or_b32 s0, s0, s76
	s_ashr_i32 s67, s66, 31
	s_ashr_i32 s1, s0, 31
	s_lshl_b64 s[4:5], s[0:1], 18
	s_lshl_b64 s[6:7], s[66:67], 18
	s_cmp_lg_u32 s89, 0
	s_cbranch_scc1 .Lmy_ip0_pass2
	s_barrier
	s_lshl_b64 s[64:65], s[66:67], 17
	s_add_u32 s84, s50, 0x3a00000
	s_addc_u32 s85, s51, 0
	s_add_u32 s84, s84, s6
	s_addc_u32 s85, s85, s7
	s_add_u32 s92, s84, 0x40000
	s_addc_u32 s93, s85, 0
	s_add_u32 s86, s50, 0x1a00000
	s_addc_u32 s87, s51, 0
	s_add_u32 s86, s86, s4
	s_addc_u32 s87, s87, s5
	v_readfirstlane_b32 s1, v129
	v_and_b32_e32 v200, 15, v131
	v_bfe_u32 v201, v131, 4, 2
	v_and_b32_e32 v202, 63, v131
	v_lshlrev_b32_e32 v202, 4, v202
	v_lshrrev_b32_e32 v203, 6, v131
	v_lshl_add_u32 v142, v203, 16, v202
	v_add_u32_e32 v150, 0x8000, v142
	v_bfe_u32 v202, v131, 1, 3
	v_xor_b32_e32 v202, v201, v202
	v_lshlrev_b32_e32 v202, 4, v202
	v_lshl_or_b32 v212, v200, 7, v202
	v_xor_b32_e32 v213, 64, v212
	v_bfe_u32 v200, v131, 4, 3
	v_and_b32_e32 v201, 7, v131
	v_xor_b32_e32 v200, v200, v201
	v_lshlrev_b32_e32 v200, 4, v200
	v_lshrrev_b32_e32 v201, 3, v131
	v_lshl_or_b32 v151, v201, 11, v200
	v_add_u32_e32 v156, 65536, v151
	v_add_u32_e32 v158, 131072, v151
	v_add_u32_e32 v159, 196608, v151
	s_add_u32 m0, s1, 0
	s_nop 0
	global_load_lds_dwordx4 v151, s[86:87]
	s_add_u32 m0, s1, 4096
	s_nop 0
	global_load_lds_dwordx4 v156, s[86:87]
	s_add_u32 m0, s1, 8192
	s_nop 0
	global_load_lds_dwordx4 v158, s[86:87]
	s_add_u32 m0, s1, 12288
	s_nop 0
	global_load_lds_dwordx4 v159, s[86:87]
	s_add_u32 s86, s86, 128
	s_addc_u32 s87, s87, 0
	global_load_dwordx4 v[64:67], v142, s[84:85] offset:0
	global_load_dwordx4 v[68:71], v150, s[84:85] offset:0
	global_load_dwordx4 v[72:75], v142, s[92:93] offset:0
	global_load_dwordx4 v[76:79], v150, s[92:93] offset:0
	global_load_dwordx4 v[80:83], v142, s[84:85] offset:1024
	global_load_dwordx4 v[84:87], v150, s[84:85] offset:1024
	global_load_dwordx4 v[88:91], v142, s[92:93] offset:1024
	global_load_dwordx4 v[92:95], v150, s[92:93] offset:1024
	s_add_u32 s84, s84, 0x800
	s_addc_u32 s85, s85, 0
	s_add_u32 s92, s92, 0x800
	s_addc_u32 s93, s93, 0
	s_add_u32 m0, s1, 16384
	s_nop 0
	global_load_lds_dwordx4 v151, s[86:87]
	s_add_u32 m0, s1, 20480
	s_nop 0
	global_load_lds_dwordx4 v156, s[86:87]
	s_add_u32 m0, s1, 24576
	s_nop 0
	global_load_lds_dwordx4 v158, s[86:87]
	s_add_u32 m0, s1, 28672
	s_nop 0
	global_load_lds_dwordx4 v159, s[86:87]
	s_add_u32 s86, s86, 128
	s_addc_u32 s87, s87, 0
	s_add_u32 m0, s1, 32768
	s_nop 0
	global_load_lds_dwordx4 v151, s[86:87]
	s_add_u32 m0, s1, 36864
	s_nop 0
	global_load_lds_dwordx4 v156, s[86:87]
	s_add_u32 m0, s1, 40960
	s_nop 0
	global_load_lds_dwordx4 v158, s[86:87]
	s_add_u32 m0, s1, 45056
	s_nop 0
	global_load_lds_dwordx4 v159, s[86:87]
	s_add_u32 s86, s86, 128
	s_addc_u32 s87, s87, 0
	s_waitcnt vmcnt(12)
	s_barrier
	ds_read_b128 v[160:163], v212 offset:0
	ds_read_b128 v[176:179], v212 offset:2048
	ds_read_b128 v[180:183], v212 offset:4096
	ds_read_b128 v[188:191], v212 offset:6144
	ds_read_b128 v[192:195], v212 offset:8192
	ds_read_b128 v[196:199], v212 offset:10240
	global_load_dwordx4 v[96:99], v142, s[84:85] offset:0
	s_waitcnt lgkmcnt(5)
	v_mfma_f32_16x16x32_bf16 v[0:3], v[64:67], v[160:163], 0
	v_mfma_f32_16x16x32_bf16 v[32:35], v[68:71], v[160:163], 0
	v_mfma_f32_16x16x32_bf16 v[144:147], v[72:75], v[160:163], 0
	v_mfma_f32_16x16x32_bf16 v[252:255], v[76:79], v[160:163], 0
	ds_read_b128 v[160:163], v212 offset:12288
	global_load_dwordx4 v[164:167], v150, s[84:85] offset:0
	s_waitcnt lgkmcnt(5)
	v_mfma_f32_16x16x32_bf16 v[4:7], v[64:67], v[176:179], 0
	v_mfma_f32_16x16x32_bf16 v[36:39], v[68:71], v[176:179], 0
	v_mfma_f32_16x16x32_bf16 v[184:187], v[72:75], v[176:179], 0
	v_mfma_f32_16x16x32_bf16 v[100:103], v[76:79], v[176:179], 0
	ds_read_b128 v[176:179], v212 offset:14336
	global_load_dwordx4 v[168:171], v142, s[92:93] offset:0
	s_waitcnt lgkmcnt(5)
	v_mfma_f32_16x16x32_bf16 v[8:11], v[64:67], v[180:183], 0
	v_mfma_f32_16x16x32_bf16 v[40:43], v[68:71], v[180:183], 0
	v_mfma_f32_16x16x32_bf16 v[204:207], v[72:75], v[180:183], 0
	v_mfma_f32_16x16x32_bf16 v[104:107], v[76:79], v[180:183], 0
	ds_read_b128 v[180:183], v213 offset:0
	global_load_dwordx4 v[172:175], v150, s[92:93] offset:0
	s_waitcnt lgkmcnt(5)
	v_mfma_f32_16x16x32_bf16 v[12:15], v[64:67], v[188:191], 0
	v_mfma_f32_16x16x32_bf16 v[44:47], v[68:71], v[188:191], 0
	v_mfma_f32_16x16x32_bf16 v[208:211], v[72:75], v[188:191], 0
	v_mfma_f32_16x16x32_bf16 v[108:111], v[76:79], v[188:191], 0
	ds_read_b128 v[188:191], v213 offset:2048
	s_waitcnt lgkmcnt(5)
	v_mfma_f32_16x16x32_bf16 v[16:19], v[64:67], v[192:195], 0
	v_mfma_f32_16x16x32_bf16 v[48:51], v[68:71], v[192:195], 0
	v_mfma_f32_16x16x32_bf16 v[232:235], v[72:75], v[192:195], 0
	v_mfma_f32_16x16x32_bf16 v[112:115], v[76:79], v[192:195], 0
	ds_read_b128 v[192:195], v213 offset:4096
	s_waitcnt lgkmcnt(5)
	v_mfma_f32_16x16x32_bf16 v[20:23], v[64:67], v[196:199], 0
	v_mfma_f32_16x16x32_bf16 v[52:55], v[68:71], v[196:199], 0
	v_mfma_f32_16x16x32_bf16 v[236:239], v[72:75], v[196:199], 0
	v_mfma_f32_16x16x32_bf16 v[116:119], v[76:79], v[196:199], 0
	ds_read_b128 v[196:199], v213 offset:6144
	s_waitcnt lgkmcnt(5)
	v_mfma_f32_16x16x32_bf16 v[24:27], v[64:67], v[160:163], 0
	v_mfma_f32_16x16x32_bf16 v[56:59], v[68:71], v[160:163], 0
	v_mfma_f32_16x16x32_bf16 v[240:243], v[72:75], v[160:163], 0
	v_mfma_f32_16x16x32_bf16 v[120:123], v[76:79], v[160:163], 0
	ds_read_b128 v[160:163], v213 offset:8192
	s_waitcnt lgkmcnt(5)
	v_mfma_f32_16x16x32_bf16 v[28:31], v[64:67], v[176:179], 0
	v_mfma_f32_16x16x32_bf16 v[60:63], v[68:71], v[176:179], 0
	v_mfma_f32_16x16x32_bf16 v[248:251], v[72:75], v[176:179], 0
	v_mfma_f32_16x16x32_bf16 v[124:127], v[76:79], v[176:179], 0
	s_waitcnt vmcnt(8)
	s_barrier
	s_waitcnt vmcnt(12)
	ds_read_b128 v[176:179], v213 offset:10240
	global_load_dwordx4 v[64:67], v142, s[84:85] offset:1024
	s_waitcnt lgkmcnt(5)
	v_mfma_f32_16x16x32_bf16 v[0:3], v[80:83], v[180:183], v[0:3]
	v_mfma_f32_16x16x32_bf16 v[32:35], v[84:87], v[180:183], v[32:35]
	v_mfma_f32_16x16x32_bf16 v[144:147], v[88:91], v[180:183], v[144:147]
	v_mfma_f32_16x16x32_bf16 v[252:255], v[92:95], v[180:183], v[252:255]
	ds_read_b128 v[180:183], v213 offset:12288
	global_load_dwordx4 v[68:71], v150, s[84:85] offset:1024
	s_waitcnt lgkmcnt(5)
	v_mfma_f32_16x16x32_bf16 v[4:7], v[80:83], v[188:191], v[4:7]
	v_mfma_f32_16x16x32_bf16 v[36:39], v[84:87], v[188:191], v[36:39]
	v_mfma_f32_16x16x32_bf16 v[184:187], v[88:91], v[188:191], v[184:187]
	v_mfma_f32_16x16x32_bf16 v[100:103], v[92:95], v[188:191], v[100:103]
	ds_read_b128 v[188:191], v213 offset:14336
	global_load_dwordx4 v[72:75], v142, s[92:93] offset:1024
	s_waitcnt lgkmcnt(5)
	v_mfma_f32_16x16x32_bf16 v[8:11], v[80:83], v[192:195], v[8:11]
	v_mfma_f32_16x16x32_bf16 v[40:43], v[84:87], v[192:195], v[40:43]
	v_mfma_f32_16x16x32_bf16 v[204:207], v[88:91], v[192:195], v[204:207]
	v_mfma_f32_16x16x32_bf16 v[104:107], v[92:95], v[192:195], v[104:107]
	ds_read_b128 v[192:195], v212 offset:16384
	global_load_dwordx4 v[76:79], v150, s[92:93] offset:1024
	s_add_u32 s84, s84, 0x800
	s_addc_u32 s85, s85, 0
	s_add_u32 s92, s92, 0x800
	s_addc_u32 s93, s93, 0
	s_waitcnt lgkmcnt(5)
	v_mfma_f32_16x16x32_bf16 v[12:15], v[80:83], v[196:199], v[12:15]
	v_mfma_f32_16x16x32_bf16 v[44:47], v[84:87], v[196:199], v[44:47]
	v_mfma_f32_16x16x32_bf16 v[208:211], v[88:91], v[196:199], v[208:211]
	v_mfma_f32_16x16x32_bf16 v[108:111], v[92:95], v[196:199], v[108:111]
	ds_read_b128 v[196:199], v212 offset:18432
	s_add_u32 m0, s1, 49152
	s_nop 0
	global_load_lds_dwordx4 v151, s[86:87]
	s_waitcnt lgkmcnt(5)
	v_mfma_f32_16x16x32_bf16 v[16:19], v[80:83], v[160:163], v[16:19]
	v_mfma_f32_16x16x32_bf16 v[48:51], v[84:87], v[160:163], v[48:51]
	v_mfma_f32_16x16x32_bf16 v[232:235], v[88:91], v[160:163], v[232:235]
	v_mfma_f32_16x16x32_bf16 v[112:115], v[92:95], v[160:163], v[112:115]
	ds_read_b128 v[160:163], v212 offset:20480
	s_add_u32 m0, s1, 53248
	s_nop 0
	global_load_lds_dwordx4 v156, s[86:87]
	s_waitcnt lgkmcnt(5)
	v_mfma_f32_16x16x32_bf16 v[20:23], v[80:83], v[176:179], v[20:23]
	v_mfma_f32_16x16x32_bf16 v[52:55], v[84:87], v[176:179], v[52:55]
	v_mfma_f32_16x16x32_bf16 v[236:239], v[88:91], v[176:179], v[236:239]
	v_mfma_f32_16x16x32_bf16 v[116:119], v[92:95], v[176:179], v[116:119]
	ds_read_b128 v[176:179], v212 offset:22528
	s_add_u32 m0, s1, 57344
	s_nop 0
	global_load_lds_dwordx4 v158, s[86:87]
	s_waitcnt lgkmcnt(5)
	v_mfma_f32_16x16x32_bf16 v[24:27], v[80:83], v[180:183], v[24:27]
	v_mfma_f32_16x16x32_bf16 v[56:59], v[84:87], v[180:183], v[56:59]
	v_mfma_f32_16x16x32_bf16 v[240:243], v[88:91], v[180:183], v[240:243]
	v_mfma_f32_16x16x32_bf16 v[120:123], v[92:95], v[180:183], v[120:123]
	ds_read_b128 v[180:183], v212 offset:24576
	s_add_u32 m0, s1, 61440
	s_nop 0
	global_load_lds_dwordx4 v159, s[86:87]
	s_add_u32 s86, s86, 128
	s_addc_u32 s87, s87, 0
	s_waitcnt lgkmcnt(5)
	v_mfma_f32_16x16x32_bf16 v[28:31], v[80:83], v[188:191], v[28:31]
	v_mfma_f32_16x16x32_bf16 v[60:63], v[84:87], v[188:191], v[60:63]
	v_mfma_f32_16x16x32_bf16 v[248:251], v[88:91], v[188:191], v[248:251]
	v_mfma_f32_16x16x32_bf16 v[124:127], v[92:95], v[188:191], v[124:127]
	s_waitcnt vmcnt(8)
	ds_read_b128 v[188:191], v212 offset:26624
	global_load_dwordx4 v[80:83], v142, s[84:85] offset:0
	s_waitcnt lgkmcnt(5)
	v_mfma_f32_16x16x32_bf16 v[0:3], v[96:99], v[192:195], v[0:3]
	v_mfma_f32_16x16x32_bf16 v[32:35], v[164:167], v[192:195], v[32:35]
	v_mfma_f32_16x16x32_bf16 v[144:147], v[168:171], v[192:195], v[144:147]
	v_mfma_f32_16x16x32_bf16 v[252:255], v[172:175], v[192:195], v[252:255]
	ds_read_b128 v[192:195], v212 offset:28672
	global_load_dwordx4 v[84:87], v150, s[84:85] offset:0
	s_waitcnt lgkmcnt(5)
	v_mfma_f32_16x16x32_bf16 v[4:7], v[96:99], v[196:199], v[4:7]
	v_mfma_f32_16x16x32_bf16 v[36:39], v[164:167], v[196:199], v[36:39]
	v_mfma_f32_16x16x32_bf16 v[184:187], v[168:171], v[196:199], v[184:187]
	v_mfma_f32_16x16x32_bf16 v[100:103], v[172:175], v[196:199], v[100:103]
	ds_read_b128 v[196:199], v212 offset:30720
	global_load_dwordx4 v[88:91], v142, s[92:93] offset:0
	s_waitcnt lgkmcnt(5)
	v_mfma_f32_16x16x32_bf16 v[8:11], v[96:99], v[160:163], v[8:11]
	v_mfma_f32_16x16x32_bf16 v[40:43], v[164:167], v[160:163], v[40:43]
	v_mfma_f32_16x16x32_bf16 v[204:207], v[168:171], v[160:163], v[204:207]
	v_mfma_f32_16x16x32_bf16 v[104:107], v[172:175], v[160:163], v[104:107]
	ds_read_b128 v[160:163], v213 offset:16384
	global_load_dwordx4 v[92:95], v150, s[92:93] offset:0
	s_waitcnt lgkmcnt(5)
	v_mfma_f32_16x16x32_bf16 v[12:15], v[96:99], v[176:179], v[12:15]
	v_mfma_f32_16x16x32_bf16 v[44:47], v[164:167], v[176:179], v[44:47]
	v_mfma_f32_16x16x32_bf16 v[208:211], v[168:171], v[176:179], v[208:211]
	v_mfma_f32_16x16x32_bf16 v[108:111], v[172:175], v[176:179], v[108:111]
	ds_read_b128 v[176:179], v213 offset:18432
	s_waitcnt lgkmcnt(5)
	v_mfma_f32_16x16x32_bf16 v[16:19], v[96:99], v[180:183], v[16:19]
	v_mfma_f32_16x16x32_bf16 v[48:51], v[164:167], v[180:183], v[48:51]
	v_mfma_f32_16x16x32_bf16 v[232:235], v[168:171], v[180:183], v[232:235]
	v_mfma_f32_16x16x32_bf16 v[112:115], v[172:175], v[180:183], v[112:115]
	ds_read_b128 v[180:183], v213 offset:20480
	s_waitcnt lgkmcnt(5)
	v_mfma_f32_16x16x32_bf16 v[20:23], v[96:99], v[188:191], v[20:23]
	v_mfma_f32_16x16x32_bf16 v[52:55], v[164:167], v[188:191], v[52:55]
	v_mfma_f32_16x16x32_bf16 v[236:239], v[168:171], v[188:191], v[236:239]
	v_mfma_f32_16x16x32_bf16 v[116:119], v[172:175], v[188:191], v[116:119]
	ds_read_b128 v[188:191], v213 offset:22528
	s_waitcnt lgkmcnt(5)
	v_mfma_f32_16x16x32_bf16 v[24:27], v[96:99], v[192:195], v[24:27]
	v_mfma_f32_16x16x32_bf16 v[56:59], v[164:167], v[192:195], v[56:59]
	v_mfma_f32_16x16x32_bf16 v[240:243], v[168:171], v[192:195], v[240:243]
	v_mfma_f32_16x16x32_bf16 v[120:123], v[172:175], v[192:195], v[120:123]
	ds_read_b128 v[192:195], v213 offset:24576
	s_waitcnt lgkmcnt(5)
	v_mfma_f32_16x16x32_bf16 v[28:31], v[96:99], v[196:199], v[28:31]
	v_mfma_f32_16x16x32_bf16 v[60:63], v[164:167], v[196:199], v[60:63]
	v_mfma_f32_16x16x32_bf16 v[248:251], v[168:171], v[196:199], v[248:251]
	v_mfma_f32_16x16x32_bf16 v[124:127], v[172:175], v[196:199], v[124:127]
	s_waitcnt vmcnt(16)
	s_barrier
	s_waitcnt vmcnt(8)
	ds_read_b128 v[196:199], v213 offset:26624
	global_load_dwordx4 v[96:99], v142, s[84:85] offset:1024
	s_waitcnt lgkmcnt(5)
	v_mfma_f32_16x16x32_bf16 v[0:3], v[64:67], v[160:163], v[0:3]
	v_mfma_f32_16x16x32_bf16 v[32:35], v[68:71], v[160:163], v[32:35]
	v_mfma_f32_16x16x32_bf16 v[144:147], v[72:75], v[160:163], v[144:147]
	v_mfma_f32_16x16x32_bf16 v[252:255], v[76:79], v[160:163], v[252:255]
	ds_read_b128 v[160:163], v213 offset:28672
	global_load_dwordx4 v[164:167], v150, s[84:85] offset:1024
	s_waitcnt lgkmcnt(5)
	v_mfma_f32_16x16x32_bf16 v[4:7], v[64:67], v[176:179], v[4:7]
	v_mfma_f32_16x16x32_bf16 v[36:39], v[68:71], v[176:179], v[36:39]
	v_mfma_f32_16x16x32_bf16 v[184:187], v[72:75], v[176:179], v[184:187]
	v_mfma_f32_16x16x32_bf16 v[100:103], v[76:79], v[176:179], v[100:103]
	ds_read_b128 v[176:179], v213 offset:30720
	global_load_dwordx4 v[168:171], v142, s[92:93] offset:1024
	s_waitcnt lgkmcnt(5)
	v_mfma_f32_16x16x32_bf16 v[8:11], v[64:67], v[180:183], v[8:11]
	v_mfma_f32_16x16x32_bf16 v[40:43], v[68:71], v[180:183], v[40:43]
	v_mfma_f32_16x16x32_bf16 v[204:207], v[72:75], v[180:183], v[204:207]
	v_mfma_f32_16x16x32_bf16 v[104:107], v[76:79], v[180:183], v[104:107]
	ds_read_b128 v[180:183], v212 offset:32768
	global_load_dwordx4 v[172:175], v150, s[92:93] offset:1024
	s_add_u32 s84, s84, 0x800
	s_addc_u32 s85, s85, 0
	s_add_u32 s92, s92, 0x800
	s_addc_u32 s93, s93, 0
	s_waitcnt lgkmcnt(5)
	v_mfma_f32_16x16x32_bf16 v[12:15], v[64:67], v[188:191], v[12:15]
	v_mfma_f32_16x16x32_bf16 v[44:47], v[68:71], v[188:191], v[44:47]
	v_mfma_f32_16x16x32_bf16 v[208:211], v[72:75], v[188:191], v[208:211]
	v_mfma_f32_16x16x32_bf16 v[108:111], v[76:79], v[188:191], v[108:111]
	ds_read_b128 v[188:191], v212 offset:34816
	s_add_u32 m0, s1, 0
	s_nop 0
	global_load_lds_dwordx4 v151, s[86:87]
	s_waitcnt lgkmcnt(5)
	v_mfma_f32_16x16x32_bf16 v[16:19], v[64:67], v[192:195], v[16:19]
	v_mfma_f32_16x16x32_bf16 v[48:51], v[68:71], v[192:195], v[48:51]
	v_mfma_f32_16x16x32_bf16 v[232:235], v[72:75], v[192:195], v[232:235]
	v_mfma_f32_16x16x32_bf16 v[112:115], v[76:79], v[192:195], v[112:115]
	ds_read_b128 v[192:195], v212 offset:36864
	s_add_u32 m0, s1, 4096
	s_nop 0
	global_load_lds_dwordx4 v156, s[86:87]
	s_waitcnt lgkmcnt(5)
	v_mfma_f32_16x16x32_bf16 v[20:23], v[64:67], v[196:199], v[20:23]
	v_mfma_f32_16x16x32_bf16 v[52:55], v[68:71], v[196:199], v[52:55]
	v_mfma_f32_16x16x32_bf16 v[236:239], v[72:75], v[196:199], v[236:239]
	v_mfma_f32_16x16x32_bf16 v[116:119], v[76:79], v[196:199], v[116:119]
	ds_read_b128 v[196:199], v212 offset:38912
	s_add_u32 m0, s1, 8192
	s_nop 0
	global_load_lds_dwordx4 v158, s[86:87]
	s_waitcnt lgkmcnt(5)
	v_mfma_f32_16x16x32_bf16 v[24:27], v[64:67], v[160:163], v[24:27]
	v_mfma_f32_16x16x32_bf16 v[56:59], v[68:71], v[160:163], v[56:59]
	v_mfma_f32_16x16x32_bf16 v[240:243], v[72:75], v[160:163], v[240:243]
	v_mfma_f32_16x16x32_bf16 v[120:123], v[76:79], v[160:163], v[120:123]
	ds_read_b128 v[160:163], v212 offset:40960
	s_add_u32 m0, s1, 12288
	s_nop 0
	global_load_lds_dwordx4 v159, s[86:87]
	s_add_u32 s86, s86, 128
	s_addc_u32 s87, s87, 0
	s_waitcnt lgkmcnt(5)
	v_mfma_f32_16x16x32_bf16 v[28:31], v[64:67], v[176:179], v[28:31]
	v_mfma_f32_16x16x32_bf16 v[60:63], v[68:71], v[176:179], v[60:63]
	v_mfma_f32_16x16x32_bf16 v[248:251], v[72:75], v[176:179], v[248:251]
	v_mfma_f32_16x16x32_bf16 v[124:127], v[76:79], v[176:179], v[124:127]
	s_waitcnt vmcnt(8)
	ds_read_b128 v[176:179], v212 offset:43008
	global_load_dwordx4 v[64:67], v142, s[84:85] offset:0
	s_waitcnt lgkmcnt(5)
	v_mfma_f32_16x16x32_bf16 v[0:3], v[80:83], v[180:183], v[0:3]
	v_mfma_f32_16x16x32_bf16 v[32:35], v[84:87], v[180:183], v[32:35]
	v_mfma_f32_16x16x32_bf16 v[144:147], v[88:91], v[180:183], v[144:147]
	v_mfma_f32_16x16x32_bf16 v[252:255], v[92:95], v[180:183], v[252:255]
	ds_read_b128 v[180:183], v212 offset:45056
	global_load_dwordx4 v[68:71], v150, s[84:85] offset:0
	s_waitcnt lgkmcnt(5)
	v_mfma_f32_16x16x32_bf16 v[4:7], v[80:83], v[188:191], v[4:7]
	v_mfma_f32_16x16x32_bf16 v[36:39], v[84:87], v[188:191], v[36:39]
	v_mfma_f32_16x16x32_bf16 v[184:187], v[88:91], v[188:191], v[184:187]
	v_mfma_f32_16x16x32_bf16 v[100:103], v[92:95], v[188:191], v[100:103]
	ds_read_b128 v[188:191], v212 offset:47104
	global_load_dwordx4 v[72:75], v142, s[92:93] offset:0
	s_waitcnt lgkmcnt(5)
	v_mfma_f32_16x16x32_bf16 v[8:11], v[80:83], v[192:195], v[8:11]
	v_mfma_f32_16x16x32_bf16 v[40:43], v[84:87], v[192:195], v[40:43]
	v_mfma_f32_16x16x32_bf16 v[204:207], v[88:91], v[192:195], v[204:207]
	v_mfma_f32_16x16x32_bf16 v[104:107], v[92:95], v[192:195], v[104:107]
	ds_read_b128 v[192:195], v213 offset:32768
	global_load_dwordx4 v[76:79], v150, s[92:93] offset:0
	s_waitcnt lgkmcnt(5)
	v_mfma_f32_16x16x32_bf16 v[12:15], v[80:83], v[196:199], v[12:15]
	v_mfma_f32_16x16x32_bf16 v[44:47], v[84:87], v[196:199], v[44:47]
	v_mfma_f32_16x16x32_bf16 v[208:211], v[88:91], v[196:199], v[208:211]
	v_mfma_f32_16x16x32_bf16 v[108:111], v[92:95], v[196:199], v[108:111]
	ds_read_b128 v[196:199], v213 offset:34816
	s_waitcnt lgkmcnt(5)
	v_mfma_f32_16x16x32_bf16 v[16:19], v[80:83], v[160:163], v[16:19]
	v_mfma_f32_16x16x32_bf16 v[48:51], v[84:87], v[160:163], v[48:51]
	v_mfma_f32_16x16x32_bf16 v[232:235], v[88:91], v[160:163], v[232:235]
	v_mfma_f32_16x16x32_bf16 v[112:115], v[92:95], v[160:163], v[112:115]
	ds_read_b128 v[160:163], v213 offset:36864
	s_waitcnt lgkmcnt(5)
	v_mfma_f32_16x16x32_bf16 v[20:23], v[80:83], v[176:179], v[20:23]
	v_mfma_f32_16x16x32_bf16 v[52:55], v[84:87], v[176:179], v[52:55]
	v_mfma_f32_16x16x32_bf16 v[236:239], v[88:91], v[176:179], v[236:239]
	v_mfma_f32_16x16x32_bf16 v[116:119], v[92:95], v[176:179], v[116:119]
	ds_read_b128 v[176:179], v213 offset:38912
	s_waitcnt lgkmcnt(5)
	v_mfma_f32_16x16x32_bf16 v[24:27], v[80:83], v[180:183], v[24:27]
	v_mfma_f32_16x16x32_bf16 v[56:59], v[84:87], v[180:183], v[56:59]
	v_mfma_f32_16x16x32_bf16 v[240:243], v[88:91], v[180:183], v[240:243]
	v_mfma_f32_16x16x32_bf16 v[120:123], v[92:95], v[180:183], v[120:123]
	ds_read_b128 v[180:183], v213 offset:40960
	s_waitcnt lgkmcnt(5)
	v_mfma_f32_16x16x32_bf16 v[28:31], v[80:83], v[188:191], v[28:31]
	v_mfma_f32_16x16x32_bf16 v[60:63], v[84:87], v[188:191], v[60:63]
	v_mfma_f32_16x16x32_bf16 v[248:251], v[88:91], v[188:191], v[248:251]
	v_mfma_f32_16x16x32_bf16 v[124:127], v[92:95], v[188:191], v[124:127]
	s_waitcnt vmcnt(16)
	s_barrier
	s_waitcnt vmcnt(8)
	ds_read_b128 v[188:191], v213 offset:43008
	global_load_dwordx4 v[80:83], v142, s[84:85] offset:1024
	s_waitcnt lgkmcnt(5)
	v_mfma_f32_16x16x32_bf16 v[0:3], v[96:99], v[192:195], v[0:3]
	v_mfma_f32_16x16x32_bf16 v[32:35], v[164:167], v[192:195], v[32:35]
	v_mfma_f32_16x16x32_bf16 v[144:147], v[168:171], v[192:195], v[144:147]
	v_mfma_f32_16x16x32_bf16 v[252:255], v[172:175], v[192:195], v[252:255]
	ds_read_b128 v[192:195], v213 offset:45056
	global_load_dwordx4 v[84:87], v150, s[84:85] offset:1024
	s_waitcnt lgkmcnt(5)
	v_mfma_f32_16x16x32_bf16 v[4:7], v[96:99], v[196:199], v[4:7]
	v_mfma_f32_16x16x32_bf16 v[36:39], v[164:167], v[196:199], v[36:39]
	v_mfma_f32_16x16x32_bf16 v[184:187], v[168:171], v[196:199], v[184:187]
	v_mfma_f32_16x16x32_bf16 v[100:103], v[172:175], v[196:199], v[100:103]
	ds_read_b128 v[196:199], v213 offset:47104
	global_load_dwordx4 v[88:91], v142, s[92:93] offset:1024
	s_waitcnt lgkmcnt(5)
	v_mfma_f32_16x16x32_bf16 v[8:11], v[96:99], v[160:163], v[8:11]
	v_mfma_f32_16x16x32_bf16 v[40:43], v[164:167], v[160:163], v[40:43]
	v_mfma_f32_16x16x32_bf16 v[204:207], v[168:171], v[160:163], v[204:207]
	v_mfma_f32_16x16x32_bf16 v[104:107], v[172:175], v[160:163], v[104:107]
	ds_read_b128 v[160:163], v212 offset:49152
	global_load_dwordx4 v[92:95], v150, s[92:93] offset:1024
	s_add_u32 s84, s84, 0x800
	s_addc_u32 s85, s85, 0
	s_add_u32 s92, s92, 0x800
	s_addc_u32 s93, s93, 0
	s_waitcnt lgkmcnt(5)
	v_mfma_f32_16x16x32_bf16 v[12:15], v[96:99], v[176:179], v[12:15]
	v_mfma_f32_16x16x32_bf16 v[44:47], v[164:167], v[176:179], v[44:47]
	v_mfma_f32_16x16x32_bf16 v[208:211], v[168:171], v[176:179], v[208:211]
	v_mfma_f32_16x16x32_bf16 v[108:111], v[172:175], v[176:179], v[108:111]
	ds_read_b128 v[176:179], v212 offset:51200
	s_add_u32 m0, s1, 16384
	s_nop 0
	global_load_lds_dwordx4 v151, s[86:87]
	s_waitcnt lgkmcnt(5)
	v_mfma_f32_16x16x32_bf16 v[16:19], v[96:99], v[180:183], v[16:19]
	v_mfma_f32_16x16x32_bf16 v[48:51], v[164:167], v[180:183], v[48:51]
	v_mfma_f32_16x16x32_bf16 v[232:235], v[168:171], v[180:183], v[232:235]
	v_mfma_f32_16x16x32_bf16 v[112:115], v[172:175], v[180:183], v[112:115]
	ds_read_b128 v[180:183], v212 offset:53248
	s_add_u32 m0, s1, 20480
	s_nop 0
	global_load_lds_dwordx4 v156, s[86:87]
	s_waitcnt lgkmcnt(5)
	v_mfma_f32_16x16x32_bf16 v[20:23], v[96:99], v[188:191], v[20:23]
	v_mfma_f32_16x16x32_bf16 v[52:55], v[164:167], v[188:191], v[52:55]
	v_mfma_f32_16x16x32_bf16 v[236:239], v[168:171], v[188:191], v[236:239]
	v_mfma_f32_16x16x32_bf16 v[116:119], v[172:175], v[188:191], v[116:119]
	ds_read_b128 v[188:191], v212 offset:55296
	s_add_u32 m0, s1, 24576
	s_nop 0
	global_load_lds_dwordx4 v158, s[86:87]
	s_waitcnt lgkmcnt(5)
	v_mfma_f32_16x16x32_bf16 v[24:27], v[96:99], v[192:195], v[24:27]
	v_mfma_f32_16x16x32_bf16 v[56:59], v[164:167], v[192:195], v[56:59]
	v_mfma_f32_16x16x32_bf16 v[240:243], v[168:171], v[192:195], v[240:243]
	v_mfma_f32_16x16x32_bf16 v[120:123], v[172:175], v[192:195], v[120:123]
	ds_read_b128 v[192:195], v212 offset:57344
	s_add_u32 m0, s1, 28672
	s_nop 0
	global_load_lds_dwordx4 v159, s[86:87]
	s_add_u32 s86, s86, 128
	s_addc_u32 s87, s87, 0
	s_waitcnt lgkmcnt(5)
	v_mfma_f32_16x16x32_bf16 v[28:31], v[96:99], v[196:199], v[28:31]
	v_mfma_f32_16x16x32_bf16 v[60:63], v[164:167], v[196:199], v[60:63]
	v_mfma_f32_16x16x32_bf16 v[248:251], v[168:171], v[196:199], v[248:251]
	v_mfma_f32_16x16x32_bf16 v[124:127], v[172:175], v[196:199], v[124:127]
	s_waitcnt vmcnt(8)
	ds_read_b128 v[196:199], v212 offset:59392
	global_load_dwordx4 v[96:99], v142, s[84:85] offset:0
	s_waitcnt lgkmcnt(5)
	v_mfma_f32_16x16x32_bf16 v[0:3], v[64:67], v[160:163], v[0:3]
	v_mfma_f32_16x16x32_bf16 v[32:35], v[68:71], v[160:163], v[32:35]
	v_mfma_f32_16x16x32_bf16 v[144:147], v[72:75], v[160:163], v[144:147]
	v_mfma_f32_16x16x32_bf16 v[252:255], v[76:79], v[160:163], v[252:255]
	ds_read_b128 v[160:163], v212 offset:61440
	global_load_dwordx4 v[164:167], v150, s[84:85] offset:0
	s_waitcnt lgkmcnt(5)
	v_mfma_f32_16x16x32_bf16 v[4:7], v[64:67], v[176:179], v[4:7]
	v_mfma_f32_16x16x32_bf16 v[36:39], v[68:71], v[176:179], v[36:39]
	v_mfma_f32_16x16x32_bf16 v[184:187], v[72:75], v[176:179], v[184:187]
	v_mfma_f32_16x16x32_bf16 v[100:103], v[76:79], v[176:179], v[100:103]
	ds_read_b128 v[176:179], v212 offset:63488
	global_load_dwordx4 v[168:171], v142, s[92:93] offset:0
	s_waitcnt lgkmcnt(5)
	v_mfma_f32_16x16x32_bf16 v[8:11], v[64:67], v[180:183], v[8:11]
	v_mfma_f32_16x16x32_bf16 v[40:43], v[68:71], v[180:183], v[40:43]
	v_mfma_f32_16x16x32_bf16 v[204:207], v[72:75], v[180:183], v[204:207]
	v_mfma_f32_16x16x32_bf16 v[104:107], v[76:79], v[180:183], v[104:107]
	ds_read_b128 v[180:183], v213 offset:49152
	global_load_dwordx4 v[172:175], v150, s[92:93] offset:0
	s_waitcnt lgkmcnt(5)
	v_mfma_f32_16x16x32_bf16 v[12:15], v[64:67], v[188:191], v[12:15]
	v_mfma_f32_16x16x32_bf16 v[44:47], v[68:71], v[188:191], v[44:47]
	v_mfma_f32_16x16x32_bf16 v[208:211], v[72:75], v[188:191], v[208:211]
	v_mfma_f32_16x16x32_bf16 v[108:111], v[76:79], v[188:191], v[108:111]
	ds_read_b128 v[188:191], v213 offset:51200
	s_waitcnt lgkmcnt(5)
	v_mfma_f32_16x16x32_bf16 v[16:19], v[64:67], v[192:195], v[16:19]
	v_mfma_f32_16x16x32_bf16 v[48:51], v[68:71], v[192:195], v[48:51]
	v_mfma_f32_16x16x32_bf16 v[232:235], v[72:75], v[192:195], v[232:235]
	v_mfma_f32_16x16x32_bf16 v[112:115], v[76:79], v[192:195], v[112:115]
	ds_read_b128 v[192:195], v213 offset:53248
	s_waitcnt lgkmcnt(5)
	v_mfma_f32_16x16x32_bf16 v[20:23], v[64:67], v[196:199], v[20:23]
	v_mfma_f32_16x16x32_bf16 v[52:55], v[68:71], v[196:199], v[52:55]
	v_mfma_f32_16x16x32_bf16 v[236:239], v[72:75], v[196:199], v[236:239]
	v_mfma_f32_16x16x32_bf16 v[116:119], v[76:79], v[196:199], v[116:119]
	ds_read_b128 v[196:199], v213 offset:55296
	s_waitcnt lgkmcnt(5)
	v_mfma_f32_16x16x32_bf16 v[24:27], v[64:67], v[160:163], v[24:27]
	v_mfma_f32_16x16x32_bf16 v[56:59], v[68:71], v[160:163], v[56:59]
	v_mfma_f32_16x16x32_bf16 v[240:243], v[72:75], v[160:163], v[240:243]
	v_mfma_f32_16x16x32_bf16 v[120:123], v[76:79], v[160:163], v[120:123]
	ds_read_b128 v[160:163], v213 offset:57344
	s_waitcnt lgkmcnt(5)
	v_mfma_f32_16x16x32_bf16 v[28:31], v[64:67], v[176:179], v[28:31]
	v_mfma_f32_16x16x32_bf16 v[60:63], v[68:71], v[176:179], v[60:63]
	v_mfma_f32_16x16x32_bf16 v[248:251], v[72:75], v[176:179], v[248:251]
	v_mfma_f32_16x16x32_bf16 v[124:127], v[76:79], v[176:179], v[124:127]
	s_waitcnt vmcnt(16)
	s_barrier
	s_waitcnt vmcnt(8)
	ds_read_b128 v[176:179], v213 offset:59392
	global_load_dwordx4 v[64:67], v142, s[84:85] offset:1024
	s_waitcnt lgkmcnt(5)
	v_mfma_f32_16x16x32_bf16 v[0:3], v[80:83], v[180:183], v[0:3]
	v_mfma_f32_16x16x32_bf16 v[32:35], v[84:87], v[180:183], v[32:35]
	v_mfma_f32_16x16x32_bf16 v[144:147], v[88:91], v[180:183], v[144:147]
	v_mfma_f32_16x16x32_bf16 v[252:255], v[92:95], v[180:183], v[252:255]
	ds_read_b128 v[180:183], v213 offset:61440
	global_load_dwordx4 v[68:71], v150, s[84:85] offset:1024
	s_waitcnt lgkmcnt(5)
	v_mfma_f32_16x16x32_bf16 v[4:7], v[80:83], v[188:191], v[4:7]
	v_mfma_f32_16x16x32_bf16 v[36:39], v[84:87], v[188:191], v[36:39]
	v_mfma_f32_16x16x32_bf16 v[184:187], v[88:91], v[188:191], v[184:187]
	v_mfma_f32_16x16x32_bf16 v[100:103], v[92:95], v[188:191], v[100:103]
	ds_read_b128 v[188:191], v213 offset:63488
	global_load_dwordx4 v[72:75], v142, s[92:93] offset:1024
	s_waitcnt lgkmcnt(5)
	v_mfma_f32_16x16x32_bf16 v[8:11], v[80:83], v[192:195], v[8:11]
	v_mfma_f32_16x16x32_bf16 v[40:43], v[84:87], v[192:195], v[40:43]
	v_mfma_f32_16x16x32_bf16 v[204:207], v[88:91], v[192:195], v[204:207]
	v_mfma_f32_16x16x32_bf16 v[104:107], v[92:95], v[192:195], v[104:107]
	ds_read_b128 v[192:195], v212 offset:0
	global_load_dwordx4 v[76:79], v150, s[92:93] offset:1024
	s_add_u32 s84, s84, 0x800
	s_addc_u32 s85, s85, 0
	s_add_u32 s92, s92, 0x800
	s_addc_u32 s93, s93, 0
	s_waitcnt lgkmcnt(5)
	v_mfma_f32_16x16x32_bf16 v[12:15], v[80:83], v[196:199], v[12:15]
	v_mfma_f32_16x16x32_bf16 v[44:47], v[84:87], v[196:199], v[44:47]
	v_mfma_f32_16x16x32_bf16 v[208:211], v[88:91], v[196:199], v[208:211]
	v_mfma_f32_16x16x32_bf16 v[108:111], v[92:95], v[196:199], v[108:111]
	ds_read_b128 v[196:199], v212 offset:2048
	s_add_u32 m0, s1, 32768
	s_nop 0
	global_load_lds_dwordx4 v151, s[86:87]
	s_waitcnt lgkmcnt(5)
	v_mfma_f32_16x16x32_bf16 v[16:19], v[80:83], v[160:163], v[16:19]
	v_mfma_f32_16x16x32_bf16 v[48:51], v[84:87], v[160:163], v[48:51]
	v_mfma_f32_16x16x32_bf16 v[232:235], v[88:91], v[160:163], v[232:235]
	v_mfma_f32_16x16x32_bf16 v[112:115], v[92:95], v[160:163], v[112:115]
	ds_read_b128 v[160:163], v212 offset:4096
	s_add_u32 m0, s1, 36864
	s_nop 0
	global_load_lds_dwordx4 v156, s[86:87]
	s_waitcnt lgkmcnt(5)
	v_mfma_f32_16x16x32_bf16 v[20:23], v[80:83], v[176:179], v[20:23]
	v_mfma_f32_16x16x32_bf16 v[52:55], v[84:87], v[176:179], v[52:55]
	v_mfma_f32_16x16x32_bf16 v[236:239], v[88:91], v[176:179], v[236:239]
	v_mfma_f32_16x16x32_bf16 v[116:119], v[92:95], v[176:179], v[116:119]
	ds_read_b128 v[176:179], v212 offset:6144
	s_add_u32 m0, s1, 40960
	s_nop 0
	global_load_lds_dwordx4 v158, s[86:87]
	s_waitcnt lgkmcnt(5)
	v_mfma_f32_16x16x32_bf16 v[24:27], v[80:83], v[180:183], v[24:27]
	v_mfma_f32_16x16x32_bf16 v[56:59], v[84:87], v[180:183], v[56:59]
	v_mfma_f32_16x16x32_bf16 v[240:243], v[88:91], v[180:183], v[240:243]
	v_mfma_f32_16x16x32_bf16 v[120:123], v[92:95], v[180:183], v[120:123]
	ds_read_b128 v[180:183], v212 offset:8192
	s_add_u32 m0, s1, 45056
	s_nop 0
	global_load_lds_dwordx4 v159, s[86:87]
	s_add_u32 s86, s86, 128
	s_addc_u32 s87, s87, 0
	s_waitcnt lgkmcnt(5)
	v_mfma_f32_16x16x32_bf16 v[28:31], v[80:83], v[188:191], v[28:31]
	v_mfma_f32_16x16x32_bf16 v[60:63], v[84:87], v[188:191], v[60:63]
	v_mfma_f32_16x16x32_bf16 v[248:251], v[88:91], v[188:191], v[248:251]
	v_mfma_f32_16x16x32_bf16 v[124:127], v[92:95], v[188:191], v[124:127]
	s_waitcnt vmcnt(8)
	ds_read_b128 v[188:191], v212 offset:10240
	global_load_dwordx4 v[80:83], v142, s[84:85] offset:0
	s_waitcnt lgkmcnt(5)
	v_mfma_f32_16x16x32_bf16 v[0:3], v[96:99], v[192:195], v[0:3]
	v_mfma_f32_16x16x32_bf16 v[32:35], v[164:167], v[192:195], v[32:35]
	v_mfma_f32_16x16x32_bf16 v[144:147], v[168:171], v[192:195], v[144:147]
	v_mfma_f32_16x16x32_bf16 v[252:255], v[172:175], v[192:195], v[252:255]
	ds_read_b128 v[192:195], v212 offset:12288
	global_load_dwordx4 v[84:87], v150, s[84:85] offset:0
	s_waitcnt lgkmcnt(5)
	v_mfma_f32_16x16x32_bf16 v[4:7], v[96:99], v[196:199], v[4:7]
	v_mfma_f32_16x16x32_bf16 v[36:39], v[164:167], v[196:199], v[36:39]
	v_mfma_f32_16x16x32_bf16 v[184:187], v[168:171], v[196:199], v[184:187]
	v_mfma_f32_16x16x32_bf16 v[100:103], v[172:175], v[196:199], v[100:103]
	ds_read_b128 v[196:199], v212 offset:14336
	global_load_dwordx4 v[88:91], v142, s[92:93] offset:0
	s_waitcnt lgkmcnt(5)
	v_mfma_f32_16x16x32_bf16 v[8:11], v[96:99], v[160:163], v[8:11]
	v_mfma_f32_16x16x32_bf16 v[40:43], v[164:167], v[160:163], v[40:43]
	v_mfma_f32_16x16x32_bf16 v[204:207], v[168:171], v[160:163], v[204:207]
	v_mfma_f32_16x16x32_bf16 v[104:107], v[172:175], v[160:163], v[104:107]
	ds_read_b128 v[160:163], v213 offset:0
	global_load_dwordx4 v[92:95], v150, s[92:93] offset:0
	s_waitcnt lgkmcnt(5)
	v_mfma_f32_16x16x32_bf16 v[12:15], v[96:99], v[176:179], v[12:15]
	v_mfma_f32_16x16x32_bf16 v[44:47], v[164:167], v[176:179], v[44:47]
	v_mfma_f32_16x16x32_bf16 v[208:211], v[168:171], v[176:179], v[208:211]
	v_mfma_f32_16x16x32_bf16 v[108:111], v[172:175], v[176:179], v[108:111]
	ds_read_b128 v[176:179], v213 offset:2048
	s_waitcnt lgkmcnt(5)
	v_mfma_f32_16x16x32_bf16 v[16:19], v[96:99], v[180:183], v[16:19]
	v_mfma_f32_16x16x32_bf16 v[48:51], v[164:167], v[180:183], v[48:51]
	v_mfma_f32_16x16x32_bf16 v[232:235], v[168:171], v[180:183], v[232:235]
	v_mfma_f32_16x16x32_bf16 v[112:115], v[172:175], v[180:183], v[112:115]
	ds_read_b128 v[180:183], v213 offset:4096
	s_waitcnt lgkmcnt(5)
	v_mfma_f32_16x16x32_bf16 v[20:23], v[96:99], v[188:191], v[20:23]
	v_mfma_f32_16x16x32_bf16 v[52:55], v[164:167], v[188:191], v[52:55]
	v_mfma_f32_16x16x32_bf16 v[236:239], v[168:171], v[188:191], v[236:239]
	v_mfma_f32_16x16x32_bf16 v[116:119], v[172:175], v[188:191], v[116:119]
	ds_read_b128 v[188:191], v213 offset:6144
	s_waitcnt lgkmcnt(5)
	v_mfma_f32_16x16x32_bf16 v[24:27], v[96:99], v[192:195], v[24:27]
	v_mfma_f32_16x16x32_bf16 v[56:59], v[164:167], v[192:195], v[56:59]
	v_mfma_f32_16x16x32_bf16 v[240:243], v[168:171], v[192:195], v[240:243]
	v_mfma_f32_16x16x32_bf16 v[120:123], v[172:175], v[192:195], v[120:123]
	ds_read_b128 v[192:195], v213 offset:8192
	s_waitcnt lgkmcnt(5)
	v_mfma_f32_16x16x32_bf16 v[28:31], v[96:99], v[196:199], v[28:31]
	v_mfma_f32_16x16x32_bf16 v[60:63], v[164:167], v[196:199], v[60:63]
	v_mfma_f32_16x16x32_bf16 v[248:251], v[168:171], v[196:199], v[248:251]
	v_mfma_f32_16x16x32_bf16 v[124:127], v[172:175], v[196:199], v[124:127]
	s_waitcnt vmcnt(16)
	s_barrier
	s_waitcnt vmcnt(8)
	ds_read_b128 v[196:199], v213 offset:10240
	global_load_dwordx4 v[96:99], v142, s[84:85] offset:1024
	s_waitcnt lgkmcnt(5)
	v_mfma_f32_16x16x32_bf16 v[0:3], v[64:67], v[160:163], v[0:3]
	v_mfma_f32_16x16x32_bf16 v[32:35], v[68:71], v[160:163], v[32:35]
	v_mfma_f32_16x16x32_bf16 v[144:147], v[72:75], v[160:163], v[144:147]
	v_mfma_f32_16x16x32_bf16 v[252:255], v[76:79], v[160:163], v[252:255]
	ds_read_b128 v[160:163], v213 offset:12288
	global_load_dwordx4 v[164:167], v150, s[84:85] offset:1024
	s_waitcnt lgkmcnt(5)
	v_mfma_f32_16x16x32_bf16 v[4:7], v[64:67], v[176:179], v[4:7]
	v_mfma_f32_16x16x32_bf16 v[36:39], v[68:71], v[176:179], v[36:39]
	v_mfma_f32_16x16x32_bf16 v[184:187], v[72:75], v[176:179], v[184:187]
	v_mfma_f32_16x16x32_bf16 v[100:103], v[76:79], v[176:179], v[100:103]
	ds_read_b128 v[176:179], v213 offset:14336
	global_load_dwordx4 v[168:171], v142, s[92:93] offset:1024
	s_waitcnt lgkmcnt(5)
	v_mfma_f32_16x16x32_bf16 v[8:11], v[64:67], v[180:183], v[8:11]
	v_mfma_f32_16x16x32_bf16 v[40:43], v[68:71], v[180:183], v[40:43]
	v_mfma_f32_16x16x32_bf16 v[204:207], v[72:75], v[180:183], v[204:207]
	v_mfma_f32_16x16x32_bf16 v[104:107], v[76:79], v[180:183], v[104:107]
	ds_read_b128 v[180:183], v212 offset:16384
	global_load_dwordx4 v[172:175], v150, s[92:93] offset:1024
	s_add_u32 s84, s84, 0x800
	s_addc_u32 s85, s85, 0
	s_add_u32 s92, s92, 0x800
	s_addc_u32 s93, s93, 0
	s_waitcnt lgkmcnt(5)
	v_mfma_f32_16x16x32_bf16 v[12:15], v[64:67], v[188:191], v[12:15]
	v_mfma_f32_16x16x32_bf16 v[44:47], v[68:71], v[188:191], v[44:47]
	v_mfma_f32_16x16x32_bf16 v[208:211], v[72:75], v[188:191], v[208:211]
	v_mfma_f32_16x16x32_bf16 v[108:111], v[76:79], v[188:191], v[108:111]
	ds_read_b128 v[188:191], v212 offset:18432
	s_add_u32 m0, s1, 49152
	s_nop 0
	global_load_lds_dwordx4 v151, s[86:87]
	s_waitcnt lgkmcnt(5)
	v_mfma_f32_16x16x32_bf16 v[16:19], v[64:67], v[192:195], v[16:19]
	v_mfma_f32_16x16x32_bf16 v[48:51], v[68:71], v[192:195], v[48:51]
	v_mfma_f32_16x16x32_bf16 v[232:235], v[72:75], v[192:195], v[232:235]
	v_mfma_f32_16x16x32_bf16 v[112:115], v[76:79], v[192:195], v[112:115]
	ds_read_b128 v[192:195], v212 offset:20480
	s_add_u32 m0, s1, 53248
	s_nop 0
	global_load_lds_dwordx4 v156, s[86:87]
	s_waitcnt lgkmcnt(5)
	v_mfma_f32_16x16x32_bf16 v[20:23], v[64:67], v[196:199], v[20:23]
	v_mfma_f32_16x16x32_bf16 v[52:55], v[68:71], v[196:199], v[52:55]
	v_mfma_f32_16x16x32_bf16 v[236:239], v[72:75], v[196:199], v[236:239]
	v_mfma_f32_16x16x32_bf16 v[116:119], v[76:79], v[196:199], v[116:119]
	ds_read_b128 v[196:199], v212 offset:22528
	s_add_u32 m0, s1, 57344
	s_nop 0
	global_load_lds_dwordx4 v158, s[86:87]
	s_waitcnt lgkmcnt(5)
	v_mfma_f32_16x16x32_bf16 v[24:27], v[64:67], v[160:163], v[24:27]
	v_mfma_f32_16x16x32_bf16 v[56:59], v[68:71], v[160:163], v[56:59]
	v_mfma_f32_16x16x32_bf16 v[240:243], v[72:75], v[160:163], v[240:243]
	v_mfma_f32_16x16x32_bf16 v[120:123], v[76:79], v[160:163], v[120:123]
	ds_read_b128 v[160:163], v212 offset:24576
	s_add_u32 m0, s1, 61440
	s_nop 0
	global_load_lds_dwordx4 v159, s[86:87]
	s_add_u32 s86, s86, 128
	s_addc_u32 s87, s87, 0
	s_waitcnt lgkmcnt(5)
	v_mfma_f32_16x16x32_bf16 v[28:31], v[64:67], v[176:179], v[28:31]
	v_mfma_f32_16x16x32_bf16 v[60:63], v[68:71], v[176:179], v[60:63]
	v_mfma_f32_16x16x32_bf16 v[248:251], v[72:75], v[176:179], v[248:251]
	v_mfma_f32_16x16x32_bf16 v[124:127], v[76:79], v[176:179], v[124:127]
	s_waitcnt vmcnt(8)
	ds_read_b128 v[176:179], v212 offset:26624
	global_load_dwordx4 v[64:67], v142, s[84:85] offset:0
	s_waitcnt lgkmcnt(5)
	v_mfma_f32_16x16x32_bf16 v[0:3], v[80:83], v[180:183], v[0:3]
	v_mfma_f32_16x16x32_bf16 v[32:35], v[84:87], v[180:183], v[32:35]
	v_mfma_f32_16x16x32_bf16 v[144:147], v[88:91], v[180:183], v[144:147]
	v_mfma_f32_16x16x32_bf16 v[252:255], v[92:95], v[180:183], v[252:255]
	ds_read_b128 v[180:183], v212 offset:28672
	global_load_dwordx4 v[68:71], v150, s[84:85] offset:0
	s_waitcnt lgkmcnt(5)
	v_mfma_f32_16x16x32_bf16 v[4:7], v[80:83], v[188:191], v[4:7]
	v_mfma_f32_16x16x32_bf16 v[36:39], v[84:87], v[188:191], v[36:39]
	v_mfma_f32_16x16x32_bf16 v[184:187], v[88:91], v[188:191], v[184:187]
	v_mfma_f32_16x16x32_bf16 v[100:103], v[92:95], v[188:191], v[100:103]
	ds_read_b128 v[188:191], v212 offset:30720
	global_load_dwordx4 v[72:75], v142, s[92:93] offset:0
	s_waitcnt lgkmcnt(5)
	v_mfma_f32_16x16x32_bf16 v[8:11], v[80:83], v[192:195], v[8:11]
	v_mfma_f32_16x16x32_bf16 v[40:43], v[84:87], v[192:195], v[40:43]
	v_mfma_f32_16x16x32_bf16 v[204:207], v[88:91], v[192:195], v[204:207]
	v_mfma_f32_16x16x32_bf16 v[104:107], v[92:95], v[192:195], v[104:107]
	ds_read_b128 v[192:195], v213 offset:16384
	global_load_dwordx4 v[76:79], v150, s[92:93] offset:0
	s_waitcnt lgkmcnt(5)
	v_mfma_f32_16x16x32_bf16 v[12:15], v[80:83], v[196:199], v[12:15]
	v_mfma_f32_16x16x32_bf16 v[44:47], v[84:87], v[196:199], v[44:47]
	v_mfma_f32_16x16x32_bf16 v[208:211], v[88:91], v[196:199], v[208:211]
	v_mfma_f32_16x16x32_bf16 v[108:111], v[92:95], v[196:199], v[108:111]
	ds_read_b128 v[196:199], v213 offset:18432
	s_waitcnt lgkmcnt(5)
	v_mfma_f32_16x16x32_bf16 v[16:19], v[80:83], v[160:163], v[16:19]
	v_mfma_f32_16x16x32_bf16 v[48:51], v[84:87], v[160:163], v[48:51]
	v_mfma_f32_16x16x32_bf16 v[232:235], v[88:91], v[160:163], v[232:235]
	v_mfma_f32_16x16x32_bf16 v[112:115], v[92:95], v[160:163], v[112:115]
	ds_read_b128 v[160:163], v213 offset:20480
	s_waitcnt lgkmcnt(5)
	v_mfma_f32_16x16x32_bf16 v[20:23], v[80:83], v[176:179], v[20:23]
	v_mfma_f32_16x16x32_bf16 v[52:55], v[84:87], v[176:179], v[52:55]
	v_mfma_f32_16x16x32_bf16 v[236:239], v[88:91], v[176:179], v[236:239]
	v_mfma_f32_16x16x32_bf16 v[116:119], v[92:95], v[176:179], v[116:119]
	ds_read_b128 v[176:179], v213 offset:22528
	s_waitcnt lgkmcnt(5)
	v_mfma_f32_16x16x32_bf16 v[24:27], v[80:83], v[180:183], v[24:27]
	v_mfma_f32_16x16x32_bf16 v[56:59], v[84:87], v[180:183], v[56:59]
	v_mfma_f32_16x16x32_bf16 v[240:243], v[88:91], v[180:183], v[240:243]
	v_mfma_f32_16x16x32_bf16 v[120:123], v[92:95], v[180:183], v[120:123]
	ds_read_b128 v[180:183], v213 offset:24576
	s_waitcnt lgkmcnt(5)
	v_mfma_f32_16x16x32_bf16 v[28:31], v[80:83], v[188:191], v[28:31]
	v_mfma_f32_16x16x32_bf16 v[60:63], v[84:87], v[188:191], v[60:63]
	v_mfma_f32_16x16x32_bf16 v[248:251], v[88:91], v[188:191], v[248:251]
	v_mfma_f32_16x16x32_bf16 v[124:127], v[92:95], v[188:191], v[124:127]
	s_waitcnt vmcnt(16)
	s_barrier
	s_waitcnt vmcnt(8)
	ds_read_b128 v[188:191], v213 offset:26624
	global_load_dwordx4 v[80:83], v142, s[84:85] offset:1024
	s_waitcnt lgkmcnt(5)
	v_mfma_f32_16x16x32_bf16 v[0:3], v[96:99], v[192:195], v[0:3]
	v_mfma_f32_16x16x32_bf16 v[32:35], v[164:167], v[192:195], v[32:35]
	v_mfma_f32_16x16x32_bf16 v[144:147], v[168:171], v[192:195], v[144:147]
	v_mfma_f32_16x16x32_bf16 v[252:255], v[172:175], v[192:195], v[252:255]
	ds_read_b128 v[192:195], v213 offset:28672
	global_load_dwordx4 v[84:87], v150, s[84:85] offset:1024
	s_waitcnt lgkmcnt(5)
	v_mfma_f32_16x16x32_bf16 v[4:7], v[96:99], v[196:199], v[4:7]
	v_mfma_f32_16x16x32_bf16 v[36:39], v[164:167], v[196:199], v[36:39]
	v_mfma_f32_16x16x32_bf16 v[184:187], v[168:171], v[196:199], v[184:187]
	v_mfma_f32_16x16x32_bf16 v[100:103], v[172:175], v[196:199], v[100:103]
	ds_read_b128 v[196:199], v213 offset:30720
	global_load_dwordx4 v[88:91], v142, s[92:93] offset:1024
	s_waitcnt lgkmcnt(5)
	v_mfma_f32_16x16x32_bf16 v[8:11], v[96:99], v[160:163], v[8:11]
	v_mfma_f32_16x16x32_bf16 v[40:43], v[164:167], v[160:163], v[40:43]
	v_mfma_f32_16x16x32_bf16 v[204:207], v[168:171], v[160:163], v[204:207]
	v_mfma_f32_16x16x32_bf16 v[104:107], v[172:175], v[160:163], v[104:107]
	ds_read_b128 v[160:163], v212 offset:32768
	global_load_dwordx4 v[92:95], v150, s[92:93] offset:1024
	s_add_u32 s84, s84, 0x800
	s_addc_u32 s85, s85, 0
	s_add_u32 s92, s92, 0x800
	s_addc_u32 s93, s93, 0
	s_waitcnt lgkmcnt(5)
	v_mfma_f32_16x16x32_bf16 v[12:15], v[96:99], v[176:179], v[12:15]
	v_mfma_f32_16x16x32_bf16 v[44:47], v[164:167], v[176:179], v[44:47]
	v_mfma_f32_16x16x32_bf16 v[208:211], v[168:171], v[176:179], v[208:211]
	v_mfma_f32_16x16x32_bf16 v[108:111], v[172:175], v[176:179], v[108:111]
	ds_read_b128 v[176:179], v212 offset:34816
	s_add_u32 m0, s1, 0
	s_nop 0
	global_load_lds_dwordx4 v151, s[86:87]
	s_waitcnt lgkmcnt(5)
	v_mfma_f32_16x16x32_bf16 v[16:19], v[96:99], v[180:183], v[16:19]
	v_mfma_f32_16x16x32_bf16 v[48:51], v[164:167], v[180:183], v[48:51]
	v_mfma_f32_16x16x32_bf16 v[232:235], v[168:171], v[180:183], v[232:235]
	v_mfma_f32_16x16x32_bf16 v[112:115], v[172:175], v[180:183], v[112:115]
	ds_read_b128 v[180:183], v212 offset:36864
	s_add_u32 m0, s1, 4096
	s_nop 0
	global_load_lds_dwordx4 v156, s[86:87]
	s_waitcnt lgkmcnt(5)
	v_mfma_f32_16x16x32_bf16 v[20:23], v[96:99], v[188:191], v[20:23]
	v_mfma_f32_16x16x32_bf16 v[52:55], v[164:167], v[188:191], v[52:55]
	v_mfma_f32_16x16x32_bf16 v[236:239], v[168:171], v[188:191], v[236:239]
	v_mfma_f32_16x16x32_bf16 v[116:119], v[172:175], v[188:191], v[116:119]
	ds_read_b128 v[188:191], v212 offset:38912
	s_add_u32 m0, s1, 8192
	s_nop 0
	global_load_lds_dwordx4 v158, s[86:87]
	s_waitcnt lgkmcnt(5)
	v_mfma_f32_16x16x32_bf16 v[24:27], v[96:99], v[192:195], v[24:27]
	v_mfma_f32_16x16x32_bf16 v[56:59], v[164:167], v[192:195], v[56:59]
	v_mfma_f32_16x16x32_bf16 v[240:243], v[168:171], v[192:195], v[240:243]
	v_mfma_f32_16x16x32_bf16 v[120:123], v[172:175], v[192:195], v[120:123]
	ds_read_b128 v[192:195], v212 offset:40960
	s_add_u32 m0, s1, 12288
	s_nop 0
	global_load_lds_dwordx4 v159, s[86:87]
	s_add_u32 s86, s86, 128
	s_addc_u32 s87, s87, 0
	s_waitcnt lgkmcnt(5)
	v_mfma_f32_16x16x32_bf16 v[28:31], v[96:99], v[196:199], v[28:31]
	v_mfma_f32_16x16x32_bf16 v[60:63], v[164:167], v[196:199], v[60:63]
	v_mfma_f32_16x16x32_bf16 v[248:251], v[168:171], v[196:199], v[248:251]
	v_mfma_f32_16x16x32_bf16 v[124:127], v[172:175], v[196:199], v[124:127]
	s_waitcnt vmcnt(8)
	ds_read_b128 v[196:199], v212 offset:43008
	global_load_dwordx4 v[96:99], v142, s[84:85] offset:0
	s_waitcnt lgkmcnt(5)
	v_mfma_f32_16x16x32_bf16 v[0:3], v[64:67], v[160:163], v[0:3]
	v_mfma_f32_16x16x32_bf16 v[32:35], v[68:71], v[160:163], v[32:35]
	v_mfma_f32_16x16x32_bf16 v[144:147], v[72:75], v[160:163], v[144:147]
	v_mfma_f32_16x16x32_bf16 v[252:255], v[76:79], v[160:163], v[252:255]
	ds_read_b128 v[160:163], v212 offset:45056
	global_load_dwordx4 v[164:167], v150, s[84:85] offset:0
	s_waitcnt lgkmcnt(5)
	v_mfma_f32_16x16x32_bf16 v[4:7], v[64:67], v[176:179], v[4:7]
	v_mfma_f32_16x16x32_bf16 v[36:39], v[68:71], v[176:179], v[36:39]
	v_mfma_f32_16x16x32_bf16 v[184:187], v[72:75], v[176:179], v[184:187]
	v_mfma_f32_16x16x32_bf16 v[100:103], v[76:79], v[176:179], v[100:103]
	ds_read_b128 v[176:179], v212 offset:47104
	global_load_dwordx4 v[168:171], v142, s[92:93] offset:0
	s_waitcnt lgkmcnt(5)
	v_mfma_f32_16x16x32_bf16 v[8:11], v[64:67], v[180:183], v[8:11]
	v_mfma_f32_16x16x32_bf16 v[40:43], v[68:71], v[180:183], v[40:43]
	v_mfma_f32_16x16x32_bf16 v[204:207], v[72:75], v[180:183], v[204:207]
	v_mfma_f32_16x16x32_bf16 v[104:107], v[76:79], v[180:183], v[104:107]
	ds_read_b128 v[180:183], v213 offset:32768
	global_load_dwordx4 v[172:175], v150, s[92:93] offset:0
	s_waitcnt lgkmcnt(5)
	v_mfma_f32_16x16x32_bf16 v[12:15], v[64:67], v[188:191], v[12:15]
	v_mfma_f32_16x16x32_bf16 v[44:47], v[68:71], v[188:191], v[44:47]
	v_mfma_f32_16x16x32_bf16 v[208:211], v[72:75], v[188:191], v[208:211]
	v_mfma_f32_16x16x32_bf16 v[108:111], v[76:79], v[188:191], v[108:111]
	ds_read_b128 v[188:191], v213 offset:34816
	s_waitcnt lgkmcnt(5)
	v_mfma_f32_16x16x32_bf16 v[16:19], v[64:67], v[192:195], v[16:19]
	v_mfma_f32_16x16x32_bf16 v[48:51], v[68:71], v[192:195], v[48:51]
	v_mfma_f32_16x16x32_bf16 v[232:235], v[72:75], v[192:195], v[232:235]
	v_mfma_f32_16x16x32_bf16 v[112:115], v[76:79], v[192:195], v[112:115]
	ds_read_b128 v[192:195], v213 offset:36864
	s_waitcnt lgkmcnt(5)
	v_mfma_f32_16x16x32_bf16 v[20:23], v[64:67], v[196:199], v[20:23]
	v_mfma_f32_16x16x32_bf16 v[52:55], v[68:71], v[196:199], v[52:55]
	v_mfma_f32_16x16x32_bf16 v[236:239], v[72:75], v[196:199], v[236:239]
	v_mfma_f32_16x16x32_bf16 v[116:119], v[76:79], v[196:199], v[116:119]
	ds_read_b128 v[196:199], v213 offset:38912
	s_waitcnt lgkmcnt(5)
	v_mfma_f32_16x16x32_bf16 v[24:27], v[64:67], v[160:163], v[24:27]
	v_mfma_f32_16x16x32_bf16 v[56:59], v[68:71], v[160:163], v[56:59]
	v_mfma_f32_16x16x32_bf16 v[240:243], v[72:75], v[160:163], v[240:243]
	v_mfma_f32_16x16x32_bf16 v[120:123], v[76:79], v[160:163], v[120:123]
	ds_read_b128 v[160:163], v213 offset:40960
	s_waitcnt lgkmcnt(5)
	v_mfma_f32_16x16x32_bf16 v[28:31], v[64:67], v[176:179], v[28:31]
	v_mfma_f32_16x16x32_bf16 v[60:63], v[68:71], v[176:179], v[60:63]
	v_mfma_f32_16x16x32_bf16 v[248:251], v[72:75], v[176:179], v[248:251]
	v_mfma_f32_16x16x32_bf16 v[124:127], v[76:79], v[176:179], v[124:127]
	s_waitcnt vmcnt(16)
	s_barrier
	s_waitcnt vmcnt(8)
	ds_read_b128 v[176:179], v213 offset:43008
	global_load_dwordx4 v[64:67], v142, s[84:85] offset:1024
	s_waitcnt lgkmcnt(5)
	v_mfma_f32_16x16x32_bf16 v[0:3], v[80:83], v[180:183], v[0:3]
	v_mfma_f32_16x16x32_bf16 v[32:35], v[84:87], v[180:183], v[32:35]
	v_mfma_f32_16x16x32_bf16 v[144:147], v[88:91], v[180:183], v[144:147]
	v_mfma_f32_16x16x32_bf16 v[252:255], v[92:95], v[180:183], v[252:255]
	ds_read_b128 v[180:183], v213 offset:45056
	global_load_dwordx4 v[68:71], v150, s[84:85] offset:1024
	s_waitcnt lgkmcnt(5)
	v_mfma_f32_16x16x32_bf16 v[4:7], v[80:83], v[188:191], v[4:7]
	v_mfma_f32_16x16x32_bf16 v[36:39], v[84:87], v[188:191], v[36:39]
	v_mfma_f32_16x16x32_bf16 v[184:187], v[88:91], v[188:191], v[184:187]
	v_mfma_f32_16x16x32_bf16 v[100:103], v[92:95], v[188:191], v[100:103]
	ds_read_b128 v[188:191], v213 offset:47104
	global_load_dwordx4 v[72:75], v142, s[92:93] offset:1024
	s_waitcnt lgkmcnt(5)
	v_mfma_f32_16x16x32_bf16 v[8:11], v[80:83], v[192:195], v[8:11]
	v_mfma_f32_16x16x32_bf16 v[40:43], v[84:87], v[192:195], v[40:43]
	v_mfma_f32_16x16x32_bf16 v[204:207], v[88:91], v[192:195], v[204:207]
	v_mfma_f32_16x16x32_bf16 v[104:107], v[92:95], v[192:195], v[104:107]
	ds_read_b128 v[192:195], v212 offset:49152
	global_load_dwordx4 v[76:79], v150, s[92:93] offset:1024
	s_add_u32 s84, s84, 0x800
	s_addc_u32 s85, s85, 0
	s_add_u32 s92, s92, 0x800
	s_addc_u32 s93, s93, 0
	s_waitcnt lgkmcnt(5)
	v_mfma_f32_16x16x32_bf16 v[12:15], v[80:83], v[196:199], v[12:15]
	v_mfma_f32_16x16x32_bf16 v[44:47], v[84:87], v[196:199], v[44:47]
	v_mfma_f32_16x16x32_bf16 v[208:211], v[88:91], v[196:199], v[208:211]
	v_mfma_f32_16x16x32_bf16 v[108:111], v[92:95], v[196:199], v[108:111]
	ds_read_b128 v[196:199], v212 offset:51200
	s_add_u32 m0, s1, 16384
	s_nop 0
	global_load_lds_dwordx4 v151, s[86:87]
	s_waitcnt lgkmcnt(5)
	v_mfma_f32_16x16x32_bf16 v[16:19], v[80:83], v[160:163], v[16:19]
	v_mfma_f32_16x16x32_bf16 v[48:51], v[84:87], v[160:163], v[48:51]
	v_mfma_f32_16x16x32_bf16 v[232:235], v[88:91], v[160:163], v[232:235]
	v_mfma_f32_16x16x32_bf16 v[112:115], v[92:95], v[160:163], v[112:115]
	ds_read_b128 v[160:163], v212 offset:53248
	s_add_u32 m0, s1, 20480
	s_nop 0
	global_load_lds_dwordx4 v156, s[86:87]
	s_waitcnt lgkmcnt(5)
	v_mfma_f32_16x16x32_bf16 v[20:23], v[80:83], v[176:179], v[20:23]
	v_mfma_f32_16x16x32_bf16 v[52:55], v[84:87], v[176:179], v[52:55]
	v_mfma_f32_16x16x32_bf16 v[236:239], v[88:91], v[176:179], v[236:239]
	v_mfma_f32_16x16x32_bf16 v[116:119], v[92:95], v[176:179], v[116:119]
	ds_read_b128 v[176:179], v212 offset:55296
	s_add_u32 m0, s1, 24576
	s_nop 0
	global_load_lds_dwordx4 v158, s[86:87]
	s_waitcnt lgkmcnt(5)
	v_mfma_f32_16x16x32_bf16 v[24:27], v[80:83], v[180:183], v[24:27]
	v_mfma_f32_16x16x32_bf16 v[56:59], v[84:87], v[180:183], v[56:59]
	v_mfma_f32_16x16x32_bf16 v[240:243], v[88:91], v[180:183], v[240:243]
	v_mfma_f32_16x16x32_bf16 v[120:123], v[92:95], v[180:183], v[120:123]
	ds_read_b128 v[180:183], v212 offset:57344
	s_add_u32 m0, s1, 28672
	s_nop 0
	global_load_lds_dwordx4 v159, s[86:87]
	s_add_u32 s86, s86, 128
	s_addc_u32 s87, s87, 0
	s_waitcnt lgkmcnt(5)
	v_mfma_f32_16x16x32_bf16 v[28:31], v[80:83], v[188:191], v[28:31]
	v_mfma_f32_16x16x32_bf16 v[60:63], v[84:87], v[188:191], v[60:63]
	v_mfma_f32_16x16x32_bf16 v[248:251], v[88:91], v[188:191], v[248:251]
	v_mfma_f32_16x16x32_bf16 v[124:127], v[92:95], v[188:191], v[124:127]
	s_waitcnt vmcnt(8)
	ds_read_b128 v[188:191], v212 offset:59392
	global_load_dwordx4 v[80:83], v142, s[84:85] offset:0
	s_waitcnt lgkmcnt(5)
	v_mfma_f32_16x16x32_bf16 v[0:3], v[96:99], v[192:195], v[0:3]
	v_mfma_f32_16x16x32_bf16 v[32:35], v[164:167], v[192:195], v[32:35]
	v_mfma_f32_16x16x32_bf16 v[144:147], v[168:171], v[192:195], v[144:147]
	v_mfma_f32_16x16x32_bf16 v[252:255], v[172:175], v[192:195], v[252:255]
	ds_read_b128 v[192:195], v212 offset:61440
	global_load_dwordx4 v[84:87], v150, s[84:85] offset:0
	s_waitcnt lgkmcnt(5)
	v_mfma_f32_16x16x32_bf16 v[4:7], v[96:99], v[196:199], v[4:7]
	v_mfma_f32_16x16x32_bf16 v[36:39], v[164:167], v[196:199], v[36:39]
	v_mfma_f32_16x16x32_bf16 v[184:187], v[168:171], v[196:199], v[184:187]
	v_mfma_f32_16x16x32_bf16 v[100:103], v[172:175], v[196:199], v[100:103]
	ds_read_b128 v[196:199], v212 offset:63488
	global_load_dwordx4 v[88:91], v142, s[92:93] offset:0
	s_waitcnt lgkmcnt(5)
	v_mfma_f32_16x16x32_bf16 v[8:11], v[96:99], v[160:163], v[8:11]
	v_mfma_f32_16x16x32_bf16 v[40:43], v[164:167], v[160:163], v[40:43]
	v_mfma_f32_16x16x32_bf16 v[204:207], v[168:171], v[160:163], v[204:207]
	v_mfma_f32_16x16x32_bf16 v[104:107], v[172:175], v[160:163], v[104:107]
	ds_read_b128 v[160:163], v213 offset:49152
	global_load_dwordx4 v[92:95], v150, s[92:93] offset:0
	s_waitcnt lgkmcnt(5)
	v_mfma_f32_16x16x32_bf16 v[12:15], v[96:99], v[176:179], v[12:15]
	v_mfma_f32_16x16x32_bf16 v[44:47], v[164:167], v[176:179], v[44:47]
	v_mfma_f32_16x16x32_bf16 v[208:211], v[168:171], v[176:179], v[208:211]
	v_mfma_f32_16x16x32_bf16 v[108:111], v[172:175], v[176:179], v[108:111]
	ds_read_b128 v[176:179], v213 offset:51200
	s_waitcnt lgkmcnt(5)
	v_mfma_f32_16x16x32_bf16 v[16:19], v[96:99], v[180:183], v[16:19]
	v_mfma_f32_16x16x32_bf16 v[48:51], v[164:167], v[180:183], v[48:51]
	v_mfma_f32_16x16x32_bf16 v[232:235], v[168:171], v[180:183], v[232:235]
	v_mfma_f32_16x16x32_bf16 v[112:115], v[172:175], v[180:183], v[112:115]
	ds_read_b128 v[180:183], v213 offset:53248
	s_waitcnt lgkmcnt(5)
	v_mfma_f32_16x16x32_bf16 v[20:23], v[96:99], v[188:191], v[20:23]
	v_mfma_f32_16x16x32_bf16 v[52:55], v[164:167], v[188:191], v[52:55]
	v_mfma_f32_16x16x32_bf16 v[236:239], v[168:171], v[188:191], v[236:239]
	v_mfma_f32_16x16x32_bf16 v[116:119], v[172:175], v[188:191], v[116:119]
	ds_read_b128 v[188:191], v213 offset:55296
	s_waitcnt lgkmcnt(5)
	v_mfma_f32_16x16x32_bf16 v[24:27], v[96:99], v[192:195], v[24:27]
	v_mfma_f32_16x16x32_bf16 v[56:59], v[164:167], v[192:195], v[56:59]
	v_mfma_f32_16x16x32_bf16 v[240:243], v[168:171], v[192:195], v[240:243]
	v_mfma_f32_16x16x32_bf16 v[120:123], v[172:175], v[192:195], v[120:123]
	ds_read_b128 v[192:195], v213 offset:57344
	s_waitcnt lgkmcnt(5)
	v_mfma_f32_16x16x32_bf16 v[28:31], v[96:99], v[196:199], v[28:31]
	v_mfma_f32_16x16x32_bf16 v[60:63], v[164:167], v[196:199], v[60:63]
	v_mfma_f32_16x16x32_bf16 v[248:251], v[168:171], v[196:199], v[248:251]
	v_mfma_f32_16x16x32_bf16 v[124:127], v[172:175], v[196:199], v[124:127]
	s_waitcnt vmcnt(16)
	s_barrier
	s_waitcnt vmcnt(8)
	ds_read_b128 v[196:199], v213 offset:59392
	global_load_dwordx4 v[96:99], v142, s[84:85] offset:1024
	s_waitcnt lgkmcnt(5)
	v_mfma_f32_16x16x32_bf16 v[0:3], v[64:67], v[160:163], v[0:3]
	v_mfma_f32_16x16x32_bf16 v[32:35], v[68:71], v[160:163], v[32:35]
	v_mfma_f32_16x16x32_bf16 v[144:147], v[72:75], v[160:163], v[144:147]
	v_mfma_f32_16x16x32_bf16 v[252:255], v[76:79], v[160:163], v[252:255]
	ds_read_b128 v[160:163], v213 offset:61440
	global_load_dwordx4 v[164:167], v150, s[84:85] offset:1024
	s_waitcnt lgkmcnt(5)
	v_mfma_f32_16x16x32_bf16 v[4:7], v[64:67], v[176:179], v[4:7]
	v_mfma_f32_16x16x32_bf16 v[36:39], v[68:71], v[176:179], v[36:39]
	v_mfma_f32_16x16x32_bf16 v[184:187], v[72:75], v[176:179], v[184:187]
	v_mfma_f32_16x16x32_bf16 v[100:103], v[76:79], v[176:179], v[100:103]
	ds_read_b128 v[176:179], v213 offset:63488
	global_load_dwordx4 v[168:171], v142, s[92:93] offset:1024
	s_waitcnt lgkmcnt(5)
	v_mfma_f32_16x16x32_bf16 v[8:11], v[64:67], v[180:183], v[8:11]
	v_mfma_f32_16x16x32_bf16 v[40:43], v[68:71], v[180:183], v[40:43]
	v_mfma_f32_16x16x32_bf16 v[204:207], v[72:75], v[180:183], v[204:207]
	v_mfma_f32_16x16x32_bf16 v[104:107], v[76:79], v[180:183], v[104:107]
	ds_read_b128 v[180:183], v212 offset:0
	global_load_dwordx4 v[172:175], v150, s[92:93] offset:1024
	s_add_u32 s84, s84, 0x800
	s_addc_u32 s85, s85, 0
	s_add_u32 s92, s92, 0x800
	s_addc_u32 s93, s93, 0
	s_waitcnt lgkmcnt(5)
	v_mfma_f32_16x16x32_bf16 v[12:15], v[64:67], v[188:191], v[12:15]
	v_mfma_f32_16x16x32_bf16 v[44:47], v[68:71], v[188:191], v[44:47]
	v_mfma_f32_16x16x32_bf16 v[208:211], v[72:75], v[188:191], v[208:211]
	v_mfma_f32_16x16x32_bf16 v[108:111], v[76:79], v[188:191], v[108:111]
	ds_read_b128 v[188:191], v212 offset:2048
	s_add_u32 m0, s1, 32768
	s_nop 0
	global_load_lds_dwordx4 v151, s[86:87]
	s_waitcnt lgkmcnt(5)
	v_mfma_f32_16x16x32_bf16 v[16:19], v[64:67], v[192:195], v[16:19]
	v_mfma_f32_16x16x32_bf16 v[48:51], v[68:71], v[192:195], v[48:51]
	v_mfma_f32_16x16x32_bf16 v[232:235], v[72:75], v[192:195], v[232:235]
	v_mfma_f32_16x16x32_bf16 v[112:115], v[76:79], v[192:195], v[112:115]
	ds_read_b128 v[192:195], v212 offset:4096
	s_add_u32 m0, s1, 36864
	s_nop 0
	global_load_lds_dwordx4 v156, s[86:87]
	s_waitcnt lgkmcnt(5)
	v_mfma_f32_16x16x32_bf16 v[20:23], v[64:67], v[196:199], v[20:23]
	v_mfma_f32_16x16x32_bf16 v[52:55], v[68:71], v[196:199], v[52:55]
	v_mfma_f32_16x16x32_bf16 v[236:239], v[72:75], v[196:199], v[236:239]
	v_mfma_f32_16x16x32_bf16 v[116:119], v[76:79], v[196:199], v[116:119]
	ds_read_b128 v[196:199], v212 offset:6144
	s_add_u32 m0, s1, 40960
	s_nop 0
	global_load_lds_dwordx4 v158, s[86:87]
	s_waitcnt lgkmcnt(5)
	v_mfma_f32_16x16x32_bf16 v[24:27], v[64:67], v[160:163], v[24:27]
	v_mfma_f32_16x16x32_bf16 v[56:59], v[68:71], v[160:163], v[56:59]
	v_mfma_f32_16x16x32_bf16 v[240:243], v[72:75], v[160:163], v[240:243]
	v_mfma_f32_16x16x32_bf16 v[120:123], v[76:79], v[160:163], v[120:123]
	ds_read_b128 v[160:163], v212 offset:8192
	s_add_u32 m0, s1, 45056
	s_nop 0
	global_load_lds_dwordx4 v159, s[86:87]
	s_add_u32 s86, s86, 128
	s_addc_u32 s87, s87, 0
	s_waitcnt lgkmcnt(5)
	v_mfma_f32_16x16x32_bf16 v[28:31], v[64:67], v[176:179], v[28:31]
	v_mfma_f32_16x16x32_bf16 v[60:63], v[68:71], v[176:179], v[60:63]
	v_mfma_f32_16x16x32_bf16 v[248:251], v[72:75], v[176:179], v[248:251]
	v_mfma_f32_16x16x32_bf16 v[124:127], v[76:79], v[176:179], v[124:127]
	s_waitcnt vmcnt(8)
	ds_read_b128 v[176:179], v212 offset:10240
	global_load_dwordx4 v[64:67], v142, s[84:85] offset:0
	s_waitcnt lgkmcnt(5)
	v_mfma_f32_16x16x32_bf16 v[0:3], v[80:83], v[180:183], v[0:3]
	v_mfma_f32_16x16x32_bf16 v[32:35], v[84:87], v[180:183], v[32:35]
	v_mfma_f32_16x16x32_bf16 v[144:147], v[88:91], v[180:183], v[144:147]
	v_mfma_f32_16x16x32_bf16 v[252:255], v[92:95], v[180:183], v[252:255]
	ds_read_b128 v[180:183], v212 offset:12288
	global_load_dwordx4 v[68:71], v150, s[84:85] offset:0
	s_waitcnt lgkmcnt(5)
	v_mfma_f32_16x16x32_bf16 v[4:7], v[80:83], v[188:191], v[4:7]
	v_mfma_f32_16x16x32_bf16 v[36:39], v[84:87], v[188:191], v[36:39]
	v_mfma_f32_16x16x32_bf16 v[184:187], v[88:91], v[188:191], v[184:187]
	v_mfma_f32_16x16x32_bf16 v[100:103], v[92:95], v[188:191], v[100:103]
	ds_read_b128 v[188:191], v212 offset:14336
	global_load_dwordx4 v[72:75], v142, s[92:93] offset:0
	s_waitcnt lgkmcnt(5)
	v_mfma_f32_16x16x32_bf16 v[8:11], v[80:83], v[192:195], v[8:11]
	v_mfma_f32_16x16x32_bf16 v[40:43], v[84:87], v[192:195], v[40:43]
	v_mfma_f32_16x16x32_bf16 v[204:207], v[88:91], v[192:195], v[204:207]
	v_mfma_f32_16x16x32_bf16 v[104:107], v[92:95], v[192:195], v[104:107]
	ds_read_b128 v[192:195], v213 offset:0
	global_load_dwordx4 v[76:79], v150, s[92:93] offset:0
	s_waitcnt lgkmcnt(5)
	v_mfma_f32_16x16x32_bf16 v[12:15], v[80:83], v[196:199], v[12:15]
	v_mfma_f32_16x16x32_bf16 v[44:47], v[84:87], v[196:199], v[44:47]
	v_mfma_f32_16x16x32_bf16 v[208:211], v[88:91], v[196:199], v[208:211]
	v_mfma_f32_16x16x32_bf16 v[108:111], v[92:95], v[196:199], v[108:111]
	ds_read_b128 v[196:199], v213 offset:2048
	s_waitcnt lgkmcnt(5)
	v_mfma_f32_16x16x32_bf16 v[16:19], v[80:83], v[160:163], v[16:19]
	v_mfma_f32_16x16x32_bf16 v[48:51], v[84:87], v[160:163], v[48:51]
	v_mfma_f32_16x16x32_bf16 v[232:235], v[88:91], v[160:163], v[232:235]
	v_mfma_f32_16x16x32_bf16 v[112:115], v[92:95], v[160:163], v[112:115]
	ds_read_b128 v[160:163], v213 offset:4096
	s_waitcnt lgkmcnt(5)
	v_mfma_f32_16x16x32_bf16 v[20:23], v[80:83], v[176:179], v[20:23]
	v_mfma_f32_16x16x32_bf16 v[52:55], v[84:87], v[176:179], v[52:55]
	v_mfma_f32_16x16x32_bf16 v[236:239], v[88:91], v[176:179], v[236:239]
	v_mfma_f32_16x16x32_bf16 v[116:119], v[92:95], v[176:179], v[116:119]
	ds_read_b128 v[176:179], v213 offset:6144
	s_waitcnt lgkmcnt(5)
	v_mfma_f32_16x16x32_bf16 v[24:27], v[80:83], v[180:183], v[24:27]
	v_mfma_f32_16x16x32_bf16 v[56:59], v[84:87], v[180:183], v[56:59]
	v_mfma_f32_16x16x32_bf16 v[240:243], v[88:91], v[180:183], v[240:243]
	v_mfma_f32_16x16x32_bf16 v[120:123], v[92:95], v[180:183], v[120:123]
	ds_read_b128 v[180:183], v213 offset:8192
	s_waitcnt lgkmcnt(5)
	v_mfma_f32_16x16x32_bf16 v[28:31], v[80:83], v[188:191], v[28:31]
	v_mfma_f32_16x16x32_bf16 v[60:63], v[84:87], v[188:191], v[60:63]
	v_mfma_f32_16x16x32_bf16 v[248:251], v[88:91], v[188:191], v[248:251]
	v_mfma_f32_16x16x32_bf16 v[124:127], v[92:95], v[188:191], v[124:127]
	s_waitcnt vmcnt(16)
	s_barrier
	s_waitcnt vmcnt(8)
	ds_read_b128 v[188:191], v213 offset:10240
	global_load_dwordx4 v[80:83], v142, s[84:85] offset:1024
	s_waitcnt lgkmcnt(5)
	v_mfma_f32_16x16x32_bf16 v[0:3], v[96:99], v[192:195], v[0:3]
	v_mfma_f32_16x16x32_bf16 v[32:35], v[164:167], v[192:195], v[32:35]
	v_mfma_f32_16x16x32_bf16 v[144:147], v[168:171], v[192:195], v[144:147]
	v_mfma_f32_16x16x32_bf16 v[252:255], v[172:175], v[192:195], v[252:255]
	ds_read_b128 v[192:195], v213 offset:12288
	global_load_dwordx4 v[84:87], v150, s[84:85] offset:1024
	s_waitcnt lgkmcnt(5)
	v_mfma_f32_16x16x32_bf16 v[4:7], v[96:99], v[196:199], v[4:7]
	v_mfma_f32_16x16x32_bf16 v[36:39], v[164:167], v[196:199], v[36:39]
	v_mfma_f32_16x16x32_bf16 v[184:187], v[168:171], v[196:199], v[184:187]
	v_mfma_f32_16x16x32_bf16 v[100:103], v[172:175], v[196:199], v[100:103]
	ds_read_b128 v[196:199], v213 offset:14336
	global_load_dwordx4 v[88:91], v142, s[92:93] offset:1024
	s_waitcnt lgkmcnt(5)
	v_mfma_f32_16x16x32_bf16 v[8:11], v[96:99], v[160:163], v[8:11]
	v_mfma_f32_16x16x32_bf16 v[40:43], v[164:167], v[160:163], v[40:43]
	v_mfma_f32_16x16x32_bf16 v[204:207], v[168:171], v[160:163], v[204:207]
	v_mfma_f32_16x16x32_bf16 v[104:107], v[172:175], v[160:163], v[104:107]
	ds_read_b128 v[160:163], v212 offset:16384
	global_load_dwordx4 v[92:95], v150, s[92:93] offset:1024
	s_add_u32 s84, s84, 0x800
	s_addc_u32 s85, s85, 0
	s_add_u32 s92, s92, 0x800
	s_addc_u32 s93, s93, 0
	s_waitcnt lgkmcnt(5)
	v_mfma_f32_16x16x32_bf16 v[12:15], v[96:99], v[176:179], v[12:15]
	v_mfma_f32_16x16x32_bf16 v[44:47], v[164:167], v[176:179], v[44:47]
	v_mfma_f32_16x16x32_bf16 v[208:211], v[168:171], v[176:179], v[208:211]
	v_mfma_f32_16x16x32_bf16 v[108:111], v[172:175], v[176:179], v[108:111]
	ds_read_b128 v[176:179], v212 offset:18432
	s_add_u32 m0, s1, 49152
	s_nop 0
	global_load_lds_dwordx4 v151, s[86:87]
	s_waitcnt lgkmcnt(5)
	v_mfma_f32_16x16x32_bf16 v[16:19], v[96:99], v[180:183], v[16:19]
	v_mfma_f32_16x16x32_bf16 v[48:51], v[164:167], v[180:183], v[48:51]
	v_mfma_f32_16x16x32_bf16 v[232:235], v[168:171], v[180:183], v[232:235]
	v_mfma_f32_16x16x32_bf16 v[112:115], v[172:175], v[180:183], v[112:115]
	ds_read_b128 v[180:183], v212 offset:20480
	s_add_u32 m0, s1, 53248
	s_nop 0
	global_load_lds_dwordx4 v156, s[86:87]
	s_waitcnt lgkmcnt(5)
	v_mfma_f32_16x16x32_bf16 v[20:23], v[96:99], v[188:191], v[20:23]
	v_mfma_f32_16x16x32_bf16 v[52:55], v[164:167], v[188:191], v[52:55]
	v_mfma_f32_16x16x32_bf16 v[236:239], v[168:171], v[188:191], v[236:239]
	v_mfma_f32_16x16x32_bf16 v[116:119], v[172:175], v[188:191], v[116:119]
	ds_read_b128 v[188:191], v212 offset:22528
	s_add_u32 m0, s1, 57344
	s_nop 0
	global_load_lds_dwordx4 v158, s[86:87]
	s_waitcnt lgkmcnt(5)
	v_mfma_f32_16x16x32_bf16 v[24:27], v[96:99], v[192:195], v[24:27]
	v_mfma_f32_16x16x32_bf16 v[56:59], v[164:167], v[192:195], v[56:59]
	v_mfma_f32_16x16x32_bf16 v[240:243], v[168:171], v[192:195], v[240:243]
	v_mfma_f32_16x16x32_bf16 v[120:123], v[172:175], v[192:195], v[120:123]
	ds_read_b128 v[192:195], v212 offset:24576
	s_add_u32 m0, s1, 61440
	s_nop 0
	global_load_lds_dwordx4 v159, s[86:87]
	s_add_u32 s86, s86, 128
	s_addc_u32 s87, s87, 0
	s_waitcnt lgkmcnt(5)
	v_mfma_f32_16x16x32_bf16 v[28:31], v[96:99], v[196:199], v[28:31]
	v_mfma_f32_16x16x32_bf16 v[60:63], v[164:167], v[196:199], v[60:63]
	v_mfma_f32_16x16x32_bf16 v[248:251], v[168:171], v[196:199], v[248:251]
	v_mfma_f32_16x16x32_bf16 v[124:127], v[172:175], v[196:199], v[124:127]
	s_waitcnt vmcnt(8)
	ds_read_b128 v[196:199], v212 offset:26624
	global_load_dwordx4 v[96:99], v142, s[84:85] offset:0
	s_waitcnt lgkmcnt(5)
	v_mfma_f32_16x16x32_bf16 v[0:3], v[64:67], v[160:163], v[0:3]
	v_mfma_f32_16x16x32_bf16 v[32:35], v[68:71], v[160:163], v[32:35]
	v_mfma_f32_16x16x32_bf16 v[144:147], v[72:75], v[160:163], v[144:147]
	v_mfma_f32_16x16x32_bf16 v[252:255], v[76:79], v[160:163], v[252:255]
	ds_read_b128 v[160:163], v212 offset:28672
	global_load_dwordx4 v[164:167], v150, s[84:85] offset:0
	s_waitcnt lgkmcnt(5)
	v_mfma_f32_16x16x32_bf16 v[4:7], v[64:67], v[176:179], v[4:7]
	v_mfma_f32_16x16x32_bf16 v[36:39], v[68:71], v[176:179], v[36:39]
	v_mfma_f32_16x16x32_bf16 v[184:187], v[72:75], v[176:179], v[184:187]
	v_mfma_f32_16x16x32_bf16 v[100:103], v[76:79], v[176:179], v[100:103]
	ds_read_b128 v[176:179], v212 offset:30720
	global_load_dwordx4 v[168:171], v142, s[92:93] offset:0
	s_waitcnt lgkmcnt(5)
	v_mfma_f32_16x16x32_bf16 v[8:11], v[64:67], v[180:183], v[8:11]
	v_mfma_f32_16x16x32_bf16 v[40:43], v[68:71], v[180:183], v[40:43]
	v_mfma_f32_16x16x32_bf16 v[204:207], v[72:75], v[180:183], v[204:207]
	v_mfma_f32_16x16x32_bf16 v[104:107], v[76:79], v[180:183], v[104:107]
	ds_read_b128 v[180:183], v213 offset:16384
	global_load_dwordx4 v[172:175], v150, s[92:93] offset:0
	s_waitcnt lgkmcnt(5)
	v_mfma_f32_16x16x32_bf16 v[12:15], v[64:67], v[188:191], v[12:15]
	v_mfma_f32_16x16x32_bf16 v[44:47], v[68:71], v[188:191], v[44:47]
	v_mfma_f32_16x16x32_bf16 v[208:211], v[72:75], v[188:191], v[208:211]
	v_mfma_f32_16x16x32_bf16 v[108:111], v[76:79], v[188:191], v[108:111]
	ds_read_b128 v[188:191], v213 offset:18432
	s_waitcnt lgkmcnt(5)
	v_mfma_f32_16x16x32_bf16 v[16:19], v[64:67], v[192:195], v[16:19]
	v_mfma_f32_16x16x32_bf16 v[48:51], v[68:71], v[192:195], v[48:51]
	v_mfma_f32_16x16x32_bf16 v[232:235], v[72:75], v[192:195], v[232:235]
	v_mfma_f32_16x16x32_bf16 v[112:115], v[76:79], v[192:195], v[112:115]
	ds_read_b128 v[192:195], v213 offset:20480
	s_waitcnt lgkmcnt(5)
	v_mfma_f32_16x16x32_bf16 v[20:23], v[64:67], v[196:199], v[20:23]
	v_mfma_f32_16x16x32_bf16 v[52:55], v[68:71], v[196:199], v[52:55]
	v_mfma_f32_16x16x32_bf16 v[236:239], v[72:75], v[196:199], v[236:239]
	v_mfma_f32_16x16x32_bf16 v[116:119], v[76:79], v[196:199], v[116:119]
	ds_read_b128 v[196:199], v213 offset:22528
	s_waitcnt lgkmcnt(5)
	v_mfma_f32_16x16x32_bf16 v[24:27], v[64:67], v[160:163], v[24:27]
	v_mfma_f32_16x16x32_bf16 v[56:59], v[68:71], v[160:163], v[56:59]
	v_mfma_f32_16x16x32_bf16 v[240:243], v[72:75], v[160:163], v[240:243]
	v_mfma_f32_16x16x32_bf16 v[120:123], v[76:79], v[160:163], v[120:123]
	ds_read_b128 v[160:163], v213 offset:24576
	s_waitcnt lgkmcnt(5)
	v_mfma_f32_16x16x32_bf16 v[28:31], v[64:67], v[176:179], v[28:31]
	v_mfma_f32_16x16x32_bf16 v[60:63], v[68:71], v[176:179], v[60:63]
	v_mfma_f32_16x16x32_bf16 v[248:251], v[72:75], v[176:179], v[248:251]
	v_mfma_f32_16x16x32_bf16 v[124:127], v[76:79], v[176:179], v[124:127]
	s_waitcnt vmcnt(16)
	s_barrier
	s_waitcnt vmcnt(8)
	ds_read_b128 v[176:179], v213 offset:26624
	global_load_dwordx4 v[64:67], v142, s[84:85] offset:1024
	s_waitcnt lgkmcnt(5)
	v_mfma_f32_16x16x32_bf16 v[0:3], v[80:83], v[180:183], v[0:3]
	v_mfma_f32_16x16x32_bf16 v[32:35], v[84:87], v[180:183], v[32:35]
	v_mfma_f32_16x16x32_bf16 v[144:147], v[88:91], v[180:183], v[144:147]
	v_mfma_f32_16x16x32_bf16 v[252:255], v[92:95], v[180:183], v[252:255]
	ds_read_b128 v[180:183], v213 offset:28672
	global_load_dwordx4 v[68:71], v150, s[84:85] offset:1024
	s_waitcnt lgkmcnt(5)
	v_mfma_f32_16x16x32_bf16 v[4:7], v[80:83], v[188:191], v[4:7]
	v_mfma_f32_16x16x32_bf16 v[36:39], v[84:87], v[188:191], v[36:39]
	v_mfma_f32_16x16x32_bf16 v[184:187], v[88:91], v[188:191], v[184:187]
	v_mfma_f32_16x16x32_bf16 v[100:103], v[92:95], v[188:191], v[100:103]
	ds_read_b128 v[188:191], v213 offset:30720
	global_load_dwordx4 v[72:75], v142, s[92:93] offset:1024
	s_waitcnt lgkmcnt(5)
	v_mfma_f32_16x16x32_bf16 v[8:11], v[80:83], v[192:195], v[8:11]
	v_mfma_f32_16x16x32_bf16 v[40:43], v[84:87], v[192:195], v[40:43]
	v_mfma_f32_16x16x32_bf16 v[204:207], v[88:91], v[192:195], v[204:207]
	v_mfma_f32_16x16x32_bf16 v[104:107], v[92:95], v[192:195], v[104:107]
	ds_read_b128 v[192:195], v212 offset:32768
	global_load_dwordx4 v[76:79], v150, s[92:93] offset:1024
	s_add_u32 s84, s84, 0x800
	s_addc_u32 s85, s85, 0
	s_add_u32 s92, s92, 0x800
	s_addc_u32 s93, s93, 0
	s_waitcnt lgkmcnt(5)
	v_mfma_f32_16x16x32_bf16 v[12:15], v[80:83], v[196:199], v[12:15]
	v_mfma_f32_16x16x32_bf16 v[44:47], v[84:87], v[196:199], v[44:47]
	v_mfma_f32_16x16x32_bf16 v[208:211], v[88:91], v[196:199], v[208:211]
	v_mfma_f32_16x16x32_bf16 v[108:111], v[92:95], v[196:199], v[108:111]
	ds_read_b128 v[196:199], v212 offset:34816
	s_add_u32 m0, s1, 0
	s_nop 0
	global_load_lds_dwordx4 v151, s[86:87]
	s_waitcnt lgkmcnt(5)
	v_mfma_f32_16x16x32_bf16 v[16:19], v[80:83], v[160:163], v[16:19]
	v_mfma_f32_16x16x32_bf16 v[48:51], v[84:87], v[160:163], v[48:51]
	v_mfma_f32_16x16x32_bf16 v[232:235], v[88:91], v[160:163], v[232:235]
	v_mfma_f32_16x16x32_bf16 v[112:115], v[92:95], v[160:163], v[112:115]
	ds_read_b128 v[160:163], v212 offset:36864
	s_add_u32 m0, s1, 4096
	s_nop 0
	global_load_lds_dwordx4 v156, s[86:87]
	s_waitcnt lgkmcnt(5)
	v_mfma_f32_16x16x32_bf16 v[20:23], v[80:83], v[176:179], v[20:23]
	v_mfma_f32_16x16x32_bf16 v[52:55], v[84:87], v[176:179], v[52:55]
	v_mfma_f32_16x16x32_bf16 v[236:239], v[88:91], v[176:179], v[236:239]
	v_mfma_f32_16x16x32_bf16 v[116:119], v[92:95], v[176:179], v[116:119]
	ds_read_b128 v[176:179], v212 offset:38912
	s_add_u32 m0, s1, 8192
	s_nop 0
	global_load_lds_dwordx4 v158, s[86:87]
	s_waitcnt lgkmcnt(5)
	v_mfma_f32_16x16x32_bf16 v[24:27], v[80:83], v[180:183], v[24:27]
	v_mfma_f32_16x16x32_bf16 v[56:59], v[84:87], v[180:183], v[56:59]
	v_mfma_f32_16x16x32_bf16 v[240:243], v[88:91], v[180:183], v[240:243]
	v_mfma_f32_16x16x32_bf16 v[120:123], v[92:95], v[180:183], v[120:123]
	ds_read_b128 v[180:183], v212 offset:40960
	s_add_u32 m0, s1, 12288
	s_nop 0
	global_load_lds_dwordx4 v159, s[86:87]
	s_add_u32 s86, s86, 128
	s_addc_u32 s87, s87, 0
	s_waitcnt lgkmcnt(5)
	v_mfma_f32_16x16x32_bf16 v[28:31], v[80:83], v[188:191], v[28:31]
	v_mfma_f32_16x16x32_bf16 v[60:63], v[84:87], v[188:191], v[60:63]
	v_mfma_f32_16x16x32_bf16 v[248:251], v[88:91], v[188:191], v[248:251]
	v_mfma_f32_16x16x32_bf16 v[124:127], v[92:95], v[188:191], v[124:127]
	s_waitcnt vmcnt(8)
	ds_read_b128 v[188:191], v212 offset:43008
	global_load_dwordx4 v[80:83], v142, s[84:85] offset:0
	s_waitcnt lgkmcnt(5)
	v_mfma_f32_16x16x32_bf16 v[0:3], v[96:99], v[192:195], v[0:3]
	v_mfma_f32_16x16x32_bf16 v[32:35], v[164:167], v[192:195], v[32:35]
	v_mfma_f32_16x16x32_bf16 v[144:147], v[168:171], v[192:195], v[144:147]
	v_mfma_f32_16x16x32_bf16 v[252:255], v[172:175], v[192:195], v[252:255]
	ds_read_b128 v[192:195], v212 offset:45056
	global_load_dwordx4 v[84:87], v150, s[84:85] offset:0
	s_waitcnt lgkmcnt(5)
	v_mfma_f32_16x16x32_bf16 v[4:7], v[96:99], v[196:199], v[4:7]
	v_mfma_f32_16x16x32_bf16 v[36:39], v[164:167], v[196:199], v[36:39]
	v_mfma_f32_16x16x32_bf16 v[184:187], v[168:171], v[196:199], v[184:187]
	v_mfma_f32_16x16x32_bf16 v[100:103], v[172:175], v[196:199], v[100:103]
	ds_read_b128 v[196:199], v212 offset:47104
	global_load_dwordx4 v[88:91], v142, s[92:93] offset:0
	s_waitcnt lgkmcnt(5)
	v_mfma_f32_16x16x32_bf16 v[8:11], v[96:99], v[160:163], v[8:11]
	v_mfma_f32_16x16x32_bf16 v[40:43], v[164:167], v[160:163], v[40:43]
	v_mfma_f32_16x16x32_bf16 v[204:207], v[168:171], v[160:163], v[204:207]
	v_mfma_f32_16x16x32_bf16 v[104:107], v[172:175], v[160:163], v[104:107]
	ds_read_b128 v[160:163], v213 offset:32768
	global_load_dwordx4 v[92:95], v150, s[92:93] offset:0
	s_waitcnt lgkmcnt(5)
	v_mfma_f32_16x16x32_bf16 v[12:15], v[96:99], v[176:179], v[12:15]
	v_mfma_f32_16x16x32_bf16 v[44:47], v[164:167], v[176:179], v[44:47]
	v_mfma_f32_16x16x32_bf16 v[208:211], v[168:171], v[176:179], v[208:211]
	v_mfma_f32_16x16x32_bf16 v[108:111], v[172:175], v[176:179], v[108:111]
	ds_read_b128 v[176:179], v213 offset:34816
	s_waitcnt lgkmcnt(5)
	v_mfma_f32_16x16x32_bf16 v[16:19], v[96:99], v[180:183], v[16:19]
	v_mfma_f32_16x16x32_bf16 v[48:51], v[164:167], v[180:183], v[48:51]
	v_mfma_f32_16x16x32_bf16 v[232:235], v[168:171], v[180:183], v[232:235]
	v_mfma_f32_16x16x32_bf16 v[112:115], v[172:175], v[180:183], v[112:115]
	ds_read_b128 v[180:183], v213 offset:36864
	s_waitcnt lgkmcnt(5)
	v_mfma_f32_16x16x32_bf16 v[20:23], v[96:99], v[188:191], v[20:23]
	v_mfma_f32_16x16x32_bf16 v[52:55], v[164:167], v[188:191], v[52:55]
	v_mfma_f32_16x16x32_bf16 v[236:239], v[168:171], v[188:191], v[236:239]
	v_mfma_f32_16x16x32_bf16 v[116:119], v[172:175], v[188:191], v[116:119]
	ds_read_b128 v[188:191], v213 offset:38912
	s_waitcnt lgkmcnt(5)
	v_mfma_f32_16x16x32_bf16 v[24:27], v[96:99], v[192:195], v[24:27]
	v_mfma_f32_16x16x32_bf16 v[56:59], v[164:167], v[192:195], v[56:59]
	v_mfma_f32_16x16x32_bf16 v[240:243], v[168:171], v[192:195], v[240:243]
	v_mfma_f32_16x16x32_bf16 v[120:123], v[172:175], v[192:195], v[120:123]
	ds_read_b128 v[192:195], v213 offset:40960
	s_waitcnt lgkmcnt(5)
	v_mfma_f32_16x16x32_bf16 v[28:31], v[96:99], v[196:199], v[28:31]
	v_mfma_f32_16x16x32_bf16 v[60:63], v[164:167], v[196:199], v[60:63]
	v_mfma_f32_16x16x32_bf16 v[248:251], v[168:171], v[196:199], v[248:251]
	v_mfma_f32_16x16x32_bf16 v[124:127], v[172:175], v[196:199], v[124:127]
	s_waitcnt vmcnt(16)
	s_barrier
	s_waitcnt vmcnt(8)
	ds_read_b128 v[196:199], v213 offset:43008
	global_load_dwordx4 v[96:99], v142, s[84:85] offset:1024
	s_waitcnt lgkmcnt(5)
	v_mfma_f32_16x16x32_bf16 v[0:3], v[64:67], v[160:163], v[0:3]
	v_mfma_f32_16x16x32_bf16 v[32:35], v[68:71], v[160:163], v[32:35]
	v_mfma_f32_16x16x32_bf16 v[144:147], v[72:75], v[160:163], v[144:147]
	v_mfma_f32_16x16x32_bf16 v[252:255], v[76:79], v[160:163], v[252:255]
	ds_read_b128 v[160:163], v213 offset:45056
	global_load_dwordx4 v[164:167], v150, s[84:85] offset:1024
	s_waitcnt lgkmcnt(5)
	v_mfma_f32_16x16x32_bf16 v[4:7], v[64:67], v[176:179], v[4:7]
	v_mfma_f32_16x16x32_bf16 v[36:39], v[68:71], v[176:179], v[36:39]
	v_mfma_f32_16x16x32_bf16 v[184:187], v[72:75], v[176:179], v[184:187]
	v_mfma_f32_16x16x32_bf16 v[100:103], v[76:79], v[176:179], v[100:103]
	ds_read_b128 v[176:179], v213 offset:47104
	global_load_dwordx4 v[168:171], v142, s[92:93] offset:1024
	s_waitcnt lgkmcnt(5)
	v_mfma_f32_16x16x32_bf16 v[8:11], v[64:67], v[180:183], v[8:11]
	v_mfma_f32_16x16x32_bf16 v[40:43], v[68:71], v[180:183], v[40:43]
	v_mfma_f32_16x16x32_bf16 v[204:207], v[72:75], v[180:183], v[204:207]
	v_mfma_f32_16x16x32_bf16 v[104:107], v[76:79], v[180:183], v[104:107]
	ds_read_b128 v[180:183], v212 offset:49152
	global_load_dwordx4 v[172:175], v150, s[92:93] offset:1024
	s_add_u32 s84, s84, 0x800
	s_addc_u32 s85, s85, 0
	s_add_u32 s92, s92, 0x800
	s_addc_u32 s93, s93, 0
	s_waitcnt lgkmcnt(5)
	v_mfma_f32_16x16x32_bf16 v[12:15], v[64:67], v[188:191], v[12:15]
	v_mfma_f32_16x16x32_bf16 v[44:47], v[68:71], v[188:191], v[44:47]
	v_mfma_f32_16x16x32_bf16 v[208:211], v[72:75], v[188:191], v[208:211]
	v_mfma_f32_16x16x32_bf16 v[108:111], v[76:79], v[188:191], v[108:111]
	ds_read_b128 v[188:191], v212 offset:51200
	s_add_u32 m0, s1, 16384
	s_nop 0
	global_load_lds_dwordx4 v151, s[86:87]
	s_waitcnt lgkmcnt(5)
	v_mfma_f32_16x16x32_bf16 v[16:19], v[64:67], v[192:195], v[16:19]
	v_mfma_f32_16x16x32_bf16 v[48:51], v[68:71], v[192:195], v[48:51]
	v_mfma_f32_16x16x32_bf16 v[232:235], v[72:75], v[192:195], v[232:235]
	v_mfma_f32_16x16x32_bf16 v[112:115], v[76:79], v[192:195], v[112:115]
	ds_read_b128 v[192:195], v212 offset:53248
	s_add_u32 m0, s1, 20480
	s_nop 0
	global_load_lds_dwordx4 v156, s[86:87]
	s_waitcnt lgkmcnt(5)
	v_mfma_f32_16x16x32_bf16 v[20:23], v[64:67], v[196:199], v[20:23]
	v_mfma_f32_16x16x32_bf16 v[52:55], v[68:71], v[196:199], v[52:55]
	v_mfma_f32_16x16x32_bf16 v[236:239], v[72:75], v[196:199], v[236:239]
	v_mfma_f32_16x16x32_bf16 v[116:119], v[76:79], v[196:199], v[116:119]
	ds_read_b128 v[196:199], v212 offset:55296
	s_add_u32 m0, s1, 24576
	s_nop 0
	global_load_lds_dwordx4 v158, s[86:87]
	s_waitcnt lgkmcnt(5)
	v_mfma_f32_16x16x32_bf16 v[24:27], v[64:67], v[160:163], v[24:27]
	v_mfma_f32_16x16x32_bf16 v[56:59], v[68:71], v[160:163], v[56:59]
	v_mfma_f32_16x16x32_bf16 v[240:243], v[72:75], v[160:163], v[240:243]
	v_mfma_f32_16x16x32_bf16 v[120:123], v[76:79], v[160:163], v[120:123]
	ds_read_b128 v[160:163], v212 offset:57344
	s_add_u32 m0, s1, 28672
	s_nop 0
	global_load_lds_dwordx4 v159, s[86:87]
	s_add_u32 s86, s86, 128
	s_addc_u32 s87, s87, 0
	s_waitcnt lgkmcnt(5)
	v_mfma_f32_16x16x32_bf16 v[28:31], v[64:67], v[176:179], v[28:31]
	v_mfma_f32_16x16x32_bf16 v[60:63], v[68:71], v[176:179], v[60:63]
	v_mfma_f32_16x16x32_bf16 v[248:251], v[72:75], v[176:179], v[248:251]
	v_mfma_f32_16x16x32_bf16 v[124:127], v[76:79], v[176:179], v[124:127]
	s_waitcnt vmcnt(8)
	ds_read_b128 v[176:179], v212 offset:59392
	global_load_dwordx4 v[64:67], v142, s[84:85] offset:0
	s_waitcnt lgkmcnt(5)
	v_mfma_f32_16x16x32_bf16 v[0:3], v[80:83], v[180:183], v[0:3]
	v_mfma_f32_16x16x32_bf16 v[32:35], v[84:87], v[180:183], v[32:35]
	v_mfma_f32_16x16x32_bf16 v[144:147], v[88:91], v[180:183], v[144:147]
	v_mfma_f32_16x16x32_bf16 v[252:255], v[92:95], v[180:183], v[252:255]
	ds_read_b128 v[180:183], v212 offset:61440
	global_load_dwordx4 v[68:71], v150, s[84:85] offset:0
	s_waitcnt lgkmcnt(5)
	v_mfma_f32_16x16x32_bf16 v[4:7], v[80:83], v[188:191], v[4:7]
	v_mfma_f32_16x16x32_bf16 v[36:39], v[84:87], v[188:191], v[36:39]
	v_mfma_f32_16x16x32_bf16 v[184:187], v[88:91], v[188:191], v[184:187]
	v_mfma_f32_16x16x32_bf16 v[100:103], v[92:95], v[188:191], v[100:103]
	ds_read_b128 v[188:191], v212 offset:63488
	global_load_dwordx4 v[72:75], v142, s[92:93] offset:0
	s_waitcnt lgkmcnt(5)
	v_mfma_f32_16x16x32_bf16 v[8:11], v[80:83], v[192:195], v[8:11]
	v_mfma_f32_16x16x32_bf16 v[40:43], v[84:87], v[192:195], v[40:43]
	v_mfma_f32_16x16x32_bf16 v[204:207], v[88:91], v[192:195], v[204:207]
	v_mfma_f32_16x16x32_bf16 v[104:107], v[92:95], v[192:195], v[104:107]
	ds_read_b128 v[192:195], v213 offset:49152
	global_load_dwordx4 v[76:79], v150, s[92:93] offset:0
	s_waitcnt lgkmcnt(5)
	v_mfma_f32_16x16x32_bf16 v[12:15], v[80:83], v[196:199], v[12:15]
	v_mfma_f32_16x16x32_bf16 v[44:47], v[84:87], v[196:199], v[44:47]
	v_mfma_f32_16x16x32_bf16 v[208:211], v[88:91], v[196:199], v[208:211]
	v_mfma_f32_16x16x32_bf16 v[108:111], v[92:95], v[196:199], v[108:111]
	ds_read_b128 v[196:199], v213 offset:51200
	s_waitcnt lgkmcnt(5)
	v_mfma_f32_16x16x32_bf16 v[16:19], v[80:83], v[160:163], v[16:19]
	v_mfma_f32_16x16x32_bf16 v[48:51], v[84:87], v[160:163], v[48:51]
	v_mfma_f32_16x16x32_bf16 v[232:235], v[88:91], v[160:163], v[232:235]
	v_mfma_f32_16x16x32_bf16 v[112:115], v[92:95], v[160:163], v[112:115]
	ds_read_b128 v[160:163], v213 offset:53248
	s_waitcnt lgkmcnt(5)
	v_mfma_f32_16x16x32_bf16 v[20:23], v[80:83], v[176:179], v[20:23]
	v_mfma_f32_16x16x32_bf16 v[52:55], v[84:87], v[176:179], v[52:55]
	v_mfma_f32_16x16x32_bf16 v[236:239], v[88:91], v[176:179], v[236:239]
	v_mfma_f32_16x16x32_bf16 v[116:119], v[92:95], v[176:179], v[116:119]
	ds_read_b128 v[176:179], v213 offset:55296
	s_waitcnt lgkmcnt(5)
	v_mfma_f32_16x16x32_bf16 v[24:27], v[80:83], v[180:183], v[24:27]
	v_mfma_f32_16x16x32_bf16 v[56:59], v[84:87], v[180:183], v[56:59]
	v_mfma_f32_16x16x32_bf16 v[240:243], v[88:91], v[180:183], v[240:243]
	v_mfma_f32_16x16x32_bf16 v[120:123], v[92:95], v[180:183], v[120:123]
	ds_read_b128 v[180:183], v213 offset:57344
	s_waitcnt lgkmcnt(5)
	v_mfma_f32_16x16x32_bf16 v[28:31], v[80:83], v[188:191], v[28:31]
	v_mfma_f32_16x16x32_bf16 v[60:63], v[84:87], v[188:191], v[60:63]
	v_mfma_f32_16x16x32_bf16 v[248:251], v[88:91], v[188:191], v[248:251]
	v_mfma_f32_16x16x32_bf16 v[124:127], v[92:95], v[188:191], v[124:127]
	s_waitcnt vmcnt(16)
	s_barrier
	s_waitcnt vmcnt(8)
	ds_read_b128 v[188:191], v213 offset:59392
	global_load_dwordx4 v[80:83], v142, s[84:85] offset:1024
	s_waitcnt lgkmcnt(5)
	v_mfma_f32_16x16x32_bf16 v[0:3], v[96:99], v[192:195], v[0:3]
	v_mfma_f32_16x16x32_bf16 v[32:35], v[164:167], v[192:195], v[32:35]
	v_mfma_f32_16x16x32_bf16 v[144:147], v[168:171], v[192:195], v[144:147]
	v_mfma_f32_16x16x32_bf16 v[252:255], v[172:175], v[192:195], v[252:255]
	ds_read_b128 v[192:195], v213 offset:61440
	global_load_dwordx4 v[84:87], v150, s[84:85] offset:1024
	s_waitcnt lgkmcnt(5)
	v_mfma_f32_16x16x32_bf16 v[4:7], v[96:99], v[196:199], v[4:7]
	v_mfma_f32_16x16x32_bf16 v[36:39], v[164:167], v[196:199], v[36:39]
	v_mfma_f32_16x16x32_bf16 v[184:187], v[168:171], v[196:199], v[184:187]
	v_mfma_f32_16x16x32_bf16 v[100:103], v[172:175], v[196:199], v[100:103]
	ds_read_b128 v[196:199], v213 offset:63488
	global_load_dwordx4 v[88:91], v142, s[92:93] offset:1024
	s_waitcnt lgkmcnt(5)
	v_mfma_f32_16x16x32_bf16 v[8:11], v[96:99], v[160:163], v[8:11]
	v_mfma_f32_16x16x32_bf16 v[40:43], v[164:167], v[160:163], v[40:43]
	v_mfma_f32_16x16x32_bf16 v[204:207], v[168:171], v[160:163], v[204:207]
	v_mfma_f32_16x16x32_bf16 v[104:107], v[172:175], v[160:163], v[104:107]
	ds_read_b128 v[160:163], v212 offset:0
	global_load_dwordx4 v[92:95], v150, s[92:93] offset:1024
	s_add_u32 s84, s84, 0x800
	s_addc_u32 s85, s85, 0
	s_add_u32 s92, s92, 0x800
	s_addc_u32 s93, s93, 0
	s_waitcnt lgkmcnt(5)
	v_mfma_f32_16x16x32_bf16 v[12:15], v[96:99], v[176:179], v[12:15]
	v_mfma_f32_16x16x32_bf16 v[44:47], v[164:167], v[176:179], v[44:47]
	v_mfma_f32_16x16x32_bf16 v[208:211], v[168:171], v[176:179], v[208:211]
	v_mfma_f32_16x16x32_bf16 v[108:111], v[172:175], v[176:179], v[108:111]
	ds_read_b128 v[176:179], v212 offset:2048
	s_add_u32 m0, s1, 32768
	s_nop 0
	global_load_lds_dwordx4 v151, s[86:87]
	s_waitcnt lgkmcnt(5)
	v_mfma_f32_16x16x32_bf16 v[16:19], v[96:99], v[180:183], v[16:19]
	v_mfma_f32_16x16x32_bf16 v[48:51], v[164:167], v[180:183], v[48:51]
	v_mfma_f32_16x16x32_bf16 v[232:235], v[168:171], v[180:183], v[232:235]
	v_mfma_f32_16x16x32_bf16 v[112:115], v[172:175], v[180:183], v[112:115]
	ds_read_b128 v[180:183], v212 offset:4096
	s_add_u32 m0, s1, 36864
	s_nop 0
	global_load_lds_dwordx4 v156, s[86:87]
	s_waitcnt lgkmcnt(5)
	v_mfma_f32_16x16x32_bf16 v[20:23], v[96:99], v[188:191], v[20:23]
	v_mfma_f32_16x16x32_bf16 v[52:55], v[164:167], v[188:191], v[52:55]
	v_mfma_f32_16x16x32_bf16 v[236:239], v[168:171], v[188:191], v[236:239]
	v_mfma_f32_16x16x32_bf16 v[116:119], v[172:175], v[188:191], v[116:119]
	ds_read_b128 v[188:191], v212 offset:6144
	s_add_u32 m0, s1, 40960
	s_nop 0
	global_load_lds_dwordx4 v158, s[86:87]
	s_waitcnt lgkmcnt(5)
	v_mfma_f32_16x16x32_bf16 v[24:27], v[96:99], v[192:195], v[24:27]
	v_mfma_f32_16x16x32_bf16 v[56:59], v[164:167], v[192:195], v[56:59]
	v_mfma_f32_16x16x32_bf16 v[240:243], v[168:171], v[192:195], v[240:243]
	v_mfma_f32_16x16x32_bf16 v[120:123], v[172:175], v[192:195], v[120:123]
	ds_read_b128 v[192:195], v212 offset:8192
	s_add_u32 m0, s1, 45056
	s_nop 0
	global_load_lds_dwordx4 v159, s[86:87]
	s_add_u32 s86, s86, 128
	s_addc_u32 s87, s87, 0
	s_waitcnt lgkmcnt(5)
	v_mfma_f32_16x16x32_bf16 v[28:31], v[96:99], v[196:199], v[28:31]
	v_mfma_f32_16x16x32_bf16 v[60:63], v[164:167], v[196:199], v[60:63]
	v_mfma_f32_16x16x32_bf16 v[248:251], v[168:171], v[196:199], v[248:251]
	v_mfma_f32_16x16x32_bf16 v[124:127], v[172:175], v[196:199], v[124:127]
	s_waitcnt vmcnt(8)
	ds_read_b128 v[196:199], v212 offset:10240
	global_load_dwordx4 v[96:99], v142, s[84:85] offset:0
	s_waitcnt lgkmcnt(5)
	v_mfma_f32_16x16x32_bf16 v[0:3], v[64:67], v[160:163], v[0:3]
	v_mfma_f32_16x16x32_bf16 v[32:35], v[68:71], v[160:163], v[32:35]
	v_mfma_f32_16x16x32_bf16 v[144:147], v[72:75], v[160:163], v[144:147]
	v_mfma_f32_16x16x32_bf16 v[252:255], v[76:79], v[160:163], v[252:255]
	ds_read_b128 v[160:163], v212 offset:12288
	global_load_dwordx4 v[164:167], v150, s[84:85] offset:0
	s_waitcnt lgkmcnt(5)
	v_mfma_f32_16x16x32_bf16 v[4:7], v[64:67], v[176:179], v[4:7]
	v_mfma_f32_16x16x32_bf16 v[36:39], v[68:71], v[176:179], v[36:39]
	v_mfma_f32_16x16x32_bf16 v[184:187], v[72:75], v[176:179], v[184:187]
	v_mfma_f32_16x16x32_bf16 v[100:103], v[76:79], v[176:179], v[100:103]
	ds_read_b128 v[176:179], v212 offset:14336
	global_load_dwordx4 v[168:171], v142, s[92:93] offset:0
	s_waitcnt lgkmcnt(5)
	v_mfma_f32_16x16x32_bf16 v[8:11], v[64:67], v[180:183], v[8:11]
	v_mfma_f32_16x16x32_bf16 v[40:43], v[68:71], v[180:183], v[40:43]
	v_mfma_f32_16x16x32_bf16 v[204:207], v[72:75], v[180:183], v[204:207]
	v_mfma_f32_16x16x32_bf16 v[104:107], v[76:79], v[180:183], v[104:107]
	ds_read_b128 v[180:183], v213 offset:0
	global_load_dwordx4 v[172:175], v150, s[92:93] offset:0
	s_waitcnt lgkmcnt(5)
	v_mfma_f32_16x16x32_bf16 v[12:15], v[64:67], v[188:191], v[12:15]
	v_mfma_f32_16x16x32_bf16 v[44:47], v[68:71], v[188:191], v[44:47]
	v_mfma_f32_16x16x32_bf16 v[208:211], v[72:75], v[188:191], v[208:211]
	v_mfma_f32_16x16x32_bf16 v[108:111], v[76:79], v[188:191], v[108:111]
	ds_read_b128 v[188:191], v213 offset:2048
	s_waitcnt lgkmcnt(5)
	v_mfma_f32_16x16x32_bf16 v[16:19], v[64:67], v[192:195], v[16:19]
	v_mfma_f32_16x16x32_bf16 v[48:51], v[68:71], v[192:195], v[48:51]
	v_mfma_f32_16x16x32_bf16 v[232:235], v[72:75], v[192:195], v[232:235]
	v_mfma_f32_16x16x32_bf16 v[112:115], v[76:79], v[192:195], v[112:115]
	ds_read_b128 v[192:195], v213 offset:4096
	s_waitcnt lgkmcnt(5)
	v_mfma_f32_16x16x32_bf16 v[20:23], v[64:67], v[196:199], v[20:23]
	v_mfma_f32_16x16x32_bf16 v[52:55], v[68:71], v[196:199], v[52:55]
	v_mfma_f32_16x16x32_bf16 v[236:239], v[72:75], v[196:199], v[236:239]
	v_mfma_f32_16x16x32_bf16 v[116:119], v[76:79], v[196:199], v[116:119]
	ds_read_b128 v[196:199], v213 offset:6144
	s_waitcnt lgkmcnt(5)
	v_mfma_f32_16x16x32_bf16 v[24:27], v[64:67], v[160:163], v[24:27]
	v_mfma_f32_16x16x32_bf16 v[56:59], v[68:71], v[160:163], v[56:59]
	v_mfma_f32_16x16x32_bf16 v[240:243], v[72:75], v[160:163], v[240:243]
	v_mfma_f32_16x16x32_bf16 v[120:123], v[76:79], v[160:163], v[120:123]
	ds_read_b128 v[160:163], v213 offset:8192
	s_waitcnt lgkmcnt(5)
	v_mfma_f32_16x16x32_bf16 v[28:31], v[64:67], v[176:179], v[28:31]
	v_mfma_f32_16x16x32_bf16 v[60:63], v[68:71], v[176:179], v[60:63]
	v_mfma_f32_16x16x32_bf16 v[248:251], v[72:75], v[176:179], v[248:251]
	v_mfma_f32_16x16x32_bf16 v[124:127], v[76:79], v[176:179], v[124:127]
	s_waitcnt vmcnt(16)
	s_barrier
	s_waitcnt vmcnt(8)
	ds_read_b128 v[176:179], v213 offset:10240
	global_load_dwordx4 v[64:67], v142, s[84:85] offset:1024
	s_waitcnt lgkmcnt(5)
	v_mfma_f32_16x16x32_bf16 v[0:3], v[80:83], v[180:183], v[0:3]
	v_mfma_f32_16x16x32_bf16 v[32:35], v[84:87], v[180:183], v[32:35]
	v_mfma_f32_16x16x32_bf16 v[144:147], v[88:91], v[180:183], v[144:147]
	v_mfma_f32_16x16x32_bf16 v[252:255], v[92:95], v[180:183], v[252:255]
	ds_read_b128 v[180:183], v213 offset:12288
	global_load_dwordx4 v[68:71], v150, s[84:85] offset:1024
	s_waitcnt lgkmcnt(5)
	v_mfma_f32_16x16x32_bf16 v[4:7], v[80:83], v[188:191], v[4:7]
	v_mfma_f32_16x16x32_bf16 v[36:39], v[84:87], v[188:191], v[36:39]
	v_mfma_f32_16x16x32_bf16 v[184:187], v[88:91], v[188:191], v[184:187]
	v_mfma_f32_16x16x32_bf16 v[100:103], v[92:95], v[188:191], v[100:103]
	ds_read_b128 v[188:191], v213 offset:14336
	global_load_dwordx4 v[72:75], v142, s[92:93] offset:1024
	s_waitcnt lgkmcnt(5)
	v_mfma_f32_16x16x32_bf16 v[8:11], v[80:83], v[192:195], v[8:11]
	v_mfma_f32_16x16x32_bf16 v[40:43], v[84:87], v[192:195], v[40:43]
	v_mfma_f32_16x16x32_bf16 v[204:207], v[88:91], v[192:195], v[204:207]
	v_mfma_f32_16x16x32_bf16 v[104:107], v[92:95], v[192:195], v[104:107]
	ds_read_b128 v[192:195], v212 offset:16384
	global_load_dwordx4 v[76:79], v150, s[92:93] offset:1024
	s_add_u32 s84, s84, 0x800
	s_addc_u32 s85, s85, 0
	s_add_u32 s92, s92, 0x800
	s_addc_u32 s93, s93, 0
	s_waitcnt lgkmcnt(5)
	v_mfma_f32_16x16x32_bf16 v[12:15], v[80:83], v[196:199], v[12:15]
	v_mfma_f32_16x16x32_bf16 v[44:47], v[84:87], v[196:199], v[44:47]
	v_mfma_f32_16x16x32_bf16 v[208:211], v[88:91], v[196:199], v[208:211]
	v_mfma_f32_16x16x32_bf16 v[108:111], v[92:95], v[196:199], v[108:111]
	ds_read_b128 v[196:199], v212 offset:18432
	s_add_u32 m0, s1, 49152
	s_nop 0
	global_load_lds_dwordx4 v151, s[86:87]
	s_waitcnt lgkmcnt(5)
	v_mfma_f32_16x16x32_bf16 v[16:19], v[80:83], v[160:163], v[16:19]
	v_mfma_f32_16x16x32_bf16 v[48:51], v[84:87], v[160:163], v[48:51]
	v_mfma_f32_16x16x32_bf16 v[232:235], v[88:91], v[160:163], v[232:235]
	v_mfma_f32_16x16x32_bf16 v[112:115], v[92:95], v[160:163], v[112:115]
	ds_read_b128 v[160:163], v212 offset:20480
	s_add_u32 m0, s1, 53248
	s_nop 0
	global_load_lds_dwordx4 v156, s[86:87]
	s_waitcnt lgkmcnt(5)
	v_mfma_f32_16x16x32_bf16 v[20:23], v[80:83], v[176:179], v[20:23]
	v_mfma_f32_16x16x32_bf16 v[52:55], v[84:87], v[176:179], v[52:55]
	v_mfma_f32_16x16x32_bf16 v[236:239], v[88:91], v[176:179], v[236:239]
	v_mfma_f32_16x16x32_bf16 v[116:119], v[92:95], v[176:179], v[116:119]
	ds_read_b128 v[176:179], v212 offset:22528
	s_add_u32 m0, s1, 57344
	s_nop 0
	global_load_lds_dwordx4 v158, s[86:87]
	s_waitcnt lgkmcnt(5)
	v_mfma_f32_16x16x32_bf16 v[24:27], v[80:83], v[180:183], v[24:27]
	v_mfma_f32_16x16x32_bf16 v[56:59], v[84:87], v[180:183], v[56:59]
	v_mfma_f32_16x16x32_bf16 v[240:243], v[88:91], v[180:183], v[240:243]
	v_mfma_f32_16x16x32_bf16 v[120:123], v[92:95], v[180:183], v[120:123]
	ds_read_b128 v[180:183], v212 offset:24576
	s_add_u32 m0, s1, 61440
	s_nop 0
	global_load_lds_dwordx4 v159, s[86:87]
	s_add_u32 s86, s86, 128
	s_addc_u32 s87, s87, 0
	s_waitcnt lgkmcnt(5)
	v_mfma_f32_16x16x32_bf16 v[28:31], v[80:83], v[188:191], v[28:31]
	v_mfma_f32_16x16x32_bf16 v[60:63], v[84:87], v[188:191], v[60:63]
	v_mfma_f32_16x16x32_bf16 v[248:251], v[88:91], v[188:191], v[248:251]
	v_mfma_f32_16x16x32_bf16 v[124:127], v[92:95], v[188:191], v[124:127]
	s_waitcnt vmcnt(8)
	ds_read_b128 v[188:191], v212 offset:26624
	global_load_dwordx4 v[80:83], v142, s[84:85] offset:0
	s_waitcnt lgkmcnt(5)
	v_mfma_f32_16x16x32_bf16 v[0:3], v[96:99], v[192:195], v[0:3]
	v_mfma_f32_16x16x32_bf16 v[32:35], v[164:167], v[192:195], v[32:35]
	v_mfma_f32_16x16x32_bf16 v[144:147], v[168:171], v[192:195], v[144:147]
	v_mfma_f32_16x16x32_bf16 v[252:255], v[172:175], v[192:195], v[252:255]
	ds_read_b128 v[192:195], v212 offset:28672
	global_load_dwordx4 v[84:87], v150, s[84:85] offset:0
	s_waitcnt lgkmcnt(5)
	v_mfma_f32_16x16x32_bf16 v[4:7], v[96:99], v[196:199], v[4:7]
	v_mfma_f32_16x16x32_bf16 v[36:39], v[164:167], v[196:199], v[36:39]
	v_mfma_f32_16x16x32_bf16 v[184:187], v[168:171], v[196:199], v[184:187]
	v_mfma_f32_16x16x32_bf16 v[100:103], v[172:175], v[196:199], v[100:103]
	ds_read_b128 v[196:199], v212 offset:30720
	global_load_dwordx4 v[88:91], v142, s[92:93] offset:0
	s_waitcnt lgkmcnt(5)
	v_mfma_f32_16x16x32_bf16 v[8:11], v[96:99], v[160:163], v[8:11]
	v_mfma_f32_16x16x32_bf16 v[40:43], v[164:167], v[160:163], v[40:43]
	v_mfma_f32_16x16x32_bf16 v[204:207], v[168:171], v[160:163], v[204:207]
	v_mfma_f32_16x16x32_bf16 v[104:107], v[172:175], v[160:163], v[104:107]
	ds_read_b128 v[160:163], v213 offset:16384
	global_load_dwordx4 v[92:95], v150, s[92:93] offset:0
	s_waitcnt lgkmcnt(5)
	v_mfma_f32_16x16x32_bf16 v[12:15], v[96:99], v[176:179], v[12:15]
	v_mfma_f32_16x16x32_bf16 v[44:47], v[164:167], v[176:179], v[44:47]
	v_mfma_f32_16x16x32_bf16 v[208:211], v[168:171], v[176:179], v[208:211]
	v_mfma_f32_16x16x32_bf16 v[108:111], v[172:175], v[176:179], v[108:111]
	ds_read_b128 v[176:179], v213 offset:18432
	s_waitcnt lgkmcnt(5)
	v_mfma_f32_16x16x32_bf16 v[16:19], v[96:99], v[180:183], v[16:19]
	v_mfma_f32_16x16x32_bf16 v[48:51], v[164:167], v[180:183], v[48:51]
	v_mfma_f32_16x16x32_bf16 v[232:235], v[168:171], v[180:183], v[232:235]
	v_mfma_f32_16x16x32_bf16 v[112:115], v[172:175], v[180:183], v[112:115]
	ds_read_b128 v[180:183], v213 offset:20480
	s_waitcnt lgkmcnt(5)
	v_mfma_f32_16x16x32_bf16 v[20:23], v[96:99], v[188:191], v[20:23]
	v_mfma_f32_16x16x32_bf16 v[52:55], v[164:167], v[188:191], v[52:55]
	v_mfma_f32_16x16x32_bf16 v[236:239], v[168:171], v[188:191], v[236:239]
	v_mfma_f32_16x16x32_bf16 v[116:119], v[172:175], v[188:191], v[116:119]
	ds_read_b128 v[188:191], v213 offset:22528
	s_waitcnt lgkmcnt(5)
	v_mfma_f32_16x16x32_bf16 v[24:27], v[96:99], v[192:195], v[24:27]
	v_mfma_f32_16x16x32_bf16 v[56:59], v[164:167], v[192:195], v[56:59]
	v_mfma_f32_16x16x32_bf16 v[240:243], v[168:171], v[192:195], v[240:243]
	v_mfma_f32_16x16x32_bf16 v[120:123], v[172:175], v[192:195], v[120:123]
	ds_read_b128 v[192:195], v213 offset:24576
	s_waitcnt lgkmcnt(5)
	v_mfma_f32_16x16x32_bf16 v[28:31], v[96:99], v[196:199], v[28:31]
	v_mfma_f32_16x16x32_bf16 v[60:63], v[164:167], v[196:199], v[60:63]
	v_mfma_f32_16x16x32_bf16 v[248:251], v[168:171], v[196:199], v[248:251]
	v_mfma_f32_16x16x32_bf16 v[124:127], v[172:175], v[196:199], v[124:127]
	s_waitcnt vmcnt(16)
	s_barrier
	s_waitcnt vmcnt(8)
	ds_read_b128 v[196:199], v213 offset:26624
	global_load_dwordx4 v[96:99], v142, s[84:85] offset:1024
	s_waitcnt lgkmcnt(5)
	v_mfma_f32_16x16x32_bf16 v[0:3], v[64:67], v[160:163], v[0:3]
	v_mfma_f32_16x16x32_bf16 v[32:35], v[68:71], v[160:163], v[32:35]
	v_mfma_f32_16x16x32_bf16 v[144:147], v[72:75], v[160:163], v[144:147]
	v_mfma_f32_16x16x32_bf16 v[252:255], v[76:79], v[160:163], v[252:255]
	ds_read_b128 v[160:163], v213 offset:28672
	global_load_dwordx4 v[164:167], v150, s[84:85] offset:1024
	s_waitcnt lgkmcnt(5)
	v_mfma_f32_16x16x32_bf16 v[4:7], v[64:67], v[176:179], v[4:7]
	v_mfma_f32_16x16x32_bf16 v[36:39], v[68:71], v[176:179], v[36:39]
	v_mfma_f32_16x16x32_bf16 v[184:187], v[72:75], v[176:179], v[184:187]
	v_mfma_f32_16x16x32_bf16 v[100:103], v[76:79], v[176:179], v[100:103]
	ds_read_b128 v[176:179], v213 offset:30720
	global_load_dwordx4 v[168:171], v142, s[92:93] offset:1024
	s_waitcnt lgkmcnt(5)
	v_mfma_f32_16x16x32_bf16 v[8:11], v[64:67], v[180:183], v[8:11]
	v_mfma_f32_16x16x32_bf16 v[40:43], v[68:71], v[180:183], v[40:43]
	v_mfma_f32_16x16x32_bf16 v[204:207], v[72:75], v[180:183], v[204:207]
	v_mfma_f32_16x16x32_bf16 v[104:107], v[76:79], v[180:183], v[104:107]
	ds_read_b128 v[180:183], v212 offset:32768
	global_load_dwordx4 v[172:175], v150, s[92:93] offset:1024
	s_add_u32 s84, s84, 0x800
	s_addc_u32 s85, s85, 0
	s_add_u32 s92, s92, 0x800
	s_addc_u32 s93, s93, 0
	s_waitcnt lgkmcnt(5)
	v_mfma_f32_16x16x32_bf16 v[12:15], v[64:67], v[188:191], v[12:15]
	v_mfma_f32_16x16x32_bf16 v[44:47], v[68:71], v[188:191], v[44:47]
	v_mfma_f32_16x16x32_bf16 v[208:211], v[72:75], v[188:191], v[208:211]
	v_mfma_f32_16x16x32_bf16 v[108:111], v[76:79], v[188:191], v[108:111]
	ds_read_b128 v[188:191], v212 offset:34816
	s_waitcnt lgkmcnt(5)
	v_mfma_f32_16x16x32_bf16 v[16:19], v[64:67], v[192:195], v[16:19]
	v_mfma_f32_16x16x32_bf16 v[48:51], v[68:71], v[192:195], v[48:51]
	v_mfma_f32_16x16x32_bf16 v[232:235], v[72:75], v[192:195], v[232:235]
	v_mfma_f32_16x16x32_bf16 v[112:115], v[76:79], v[192:195], v[112:115]
	ds_read_b128 v[192:195], v212 offset:36864
	s_waitcnt lgkmcnt(5)
	v_mfma_f32_16x16x32_bf16 v[20:23], v[64:67], v[196:199], v[20:23]
	v_mfma_f32_16x16x32_bf16 v[52:55], v[68:71], v[196:199], v[52:55]
	v_mfma_f32_16x16x32_bf16 v[236:239], v[72:75], v[196:199], v[236:239]
	v_mfma_f32_16x16x32_bf16 v[116:119], v[76:79], v[196:199], v[116:119]
	ds_read_b128 v[196:199], v212 offset:38912
	s_waitcnt lgkmcnt(5)
	v_mfma_f32_16x16x32_bf16 v[24:27], v[64:67], v[160:163], v[24:27]
	v_mfma_f32_16x16x32_bf16 v[56:59], v[68:71], v[160:163], v[56:59]
	v_mfma_f32_16x16x32_bf16 v[240:243], v[72:75], v[160:163], v[240:243]
	v_mfma_f32_16x16x32_bf16 v[120:123], v[76:79], v[160:163], v[120:123]
	ds_read_b128 v[160:163], v212 offset:40960
	s_waitcnt lgkmcnt(5)
	v_mfma_f32_16x16x32_bf16 v[28:31], v[64:67], v[176:179], v[28:31]
	v_mfma_f32_16x16x32_bf16 v[60:63], v[68:71], v[176:179], v[60:63]
	v_mfma_f32_16x16x32_bf16 v[248:251], v[72:75], v[176:179], v[248:251]
	v_mfma_f32_16x16x32_bf16 v[124:127], v[76:79], v[176:179], v[124:127]
	s_waitcnt vmcnt(4)
	ds_read_b128 v[176:179], v212 offset:43008
	global_load_dwordx4 v[64:67], v142, s[84:85] offset:0
	s_waitcnt lgkmcnt(5)
	v_mfma_f32_16x16x32_bf16 v[0:3], v[80:83], v[180:183], v[0:3]
	v_mfma_f32_16x16x32_bf16 v[32:35], v[84:87], v[180:183], v[32:35]
	v_mfma_f32_16x16x32_bf16 v[144:147], v[88:91], v[180:183], v[144:147]
	v_mfma_f32_16x16x32_bf16 v[252:255], v[92:95], v[180:183], v[252:255]
	ds_read_b128 v[180:183], v212 offset:45056
	global_load_dwordx4 v[68:71], v150, s[84:85] offset:0
	s_waitcnt lgkmcnt(5)
	v_mfma_f32_16x16x32_bf16 v[4:7], v[80:83], v[188:191], v[4:7]
	v_mfma_f32_16x16x32_bf16 v[36:39], v[84:87], v[188:191], v[36:39]
	v_mfma_f32_16x16x32_bf16 v[184:187], v[88:91], v[188:191], v[184:187]
	v_mfma_f32_16x16x32_bf16 v[100:103], v[92:95], v[188:191], v[100:103]
	ds_read_b128 v[188:191], v212 offset:47104
	global_load_dwordx4 v[72:75], v142, s[92:93] offset:0
	s_waitcnt lgkmcnt(5)
	v_mfma_f32_16x16x32_bf16 v[8:11], v[80:83], v[192:195], v[8:11]
	v_mfma_f32_16x16x32_bf16 v[40:43], v[84:87], v[192:195], v[40:43]
	v_mfma_f32_16x16x32_bf16 v[204:207], v[88:91], v[192:195], v[204:207]
	v_mfma_f32_16x16x32_bf16 v[104:107], v[92:95], v[192:195], v[104:107]
	ds_read_b128 v[192:195], v213 offset:32768
	global_load_dwordx4 v[76:79], v150, s[92:93] offset:0
	s_waitcnt lgkmcnt(5)
	v_mfma_f32_16x16x32_bf16 v[12:15], v[80:83], v[196:199], v[12:15]
	v_mfma_f32_16x16x32_bf16 v[44:47], v[84:87], v[196:199], v[44:47]
	v_mfma_f32_16x16x32_bf16 v[208:211], v[88:91], v[196:199], v[208:211]
	v_mfma_f32_16x16x32_bf16 v[108:111], v[92:95], v[196:199], v[108:111]
	ds_read_b128 v[196:199], v213 offset:34816
	s_waitcnt lgkmcnt(5)
	v_mfma_f32_16x16x32_bf16 v[16:19], v[80:83], v[160:163], v[16:19]
	v_mfma_f32_16x16x32_bf16 v[48:51], v[84:87], v[160:163], v[48:51]
	v_mfma_f32_16x16x32_bf16 v[232:235], v[88:91], v[160:163], v[232:235]
	v_mfma_f32_16x16x32_bf16 v[112:115], v[92:95], v[160:163], v[112:115]
	ds_read_b128 v[160:163], v213 offset:36864
	s_waitcnt lgkmcnt(5)
	v_mfma_f32_16x16x32_bf16 v[20:23], v[80:83], v[176:179], v[20:23]
	v_mfma_f32_16x16x32_bf16 v[52:55], v[84:87], v[176:179], v[52:55]
	v_mfma_f32_16x16x32_bf16 v[236:239], v[88:91], v[176:179], v[236:239]
	v_mfma_f32_16x16x32_bf16 v[116:119], v[92:95], v[176:179], v[116:119]
	ds_read_b128 v[176:179], v213 offset:38912
	s_waitcnt lgkmcnt(5)
	v_mfma_f32_16x16x32_bf16 v[24:27], v[80:83], v[180:183], v[24:27]
	v_mfma_f32_16x16x32_bf16 v[56:59], v[84:87], v[180:183], v[56:59]
	v_mfma_f32_16x16x32_bf16 v[240:243], v[88:91], v[180:183], v[240:243]
	v_mfma_f32_16x16x32_bf16 v[120:123], v[92:95], v[180:183], v[120:123]
	ds_read_b128 v[180:183], v213 offset:40960
	s_waitcnt lgkmcnt(5)
	v_mfma_f32_16x16x32_bf16 v[28:31], v[80:83], v[188:191], v[28:31]
	v_mfma_f32_16x16x32_bf16 v[60:63], v[84:87], v[188:191], v[60:63]
	v_mfma_f32_16x16x32_bf16 v[248:251], v[88:91], v[188:191], v[248:251]
	v_mfma_f32_16x16x32_bf16 v[124:127], v[92:95], v[188:191], v[124:127]
	s_waitcnt vmcnt(12)
	s_barrier
	s_waitcnt vmcnt(4)
	ds_read_b128 v[188:191], v213 offset:43008
	global_load_dwordx4 v[80:83], v142, s[84:85] offset:1024
	s_waitcnt lgkmcnt(5)
	v_mfma_f32_16x16x32_bf16 v[0:3], v[96:99], v[192:195], v[0:3]
	v_mfma_f32_16x16x32_bf16 v[32:35], v[164:167], v[192:195], v[32:35]
	v_mfma_f32_16x16x32_bf16 v[144:147], v[168:171], v[192:195], v[144:147]
	v_mfma_f32_16x16x32_bf16 v[252:255], v[172:175], v[192:195], v[252:255]
	ds_read_b128 v[192:195], v213 offset:45056
	global_load_dwordx4 v[84:87], v150, s[84:85] offset:1024
	s_waitcnt lgkmcnt(5)
	v_mfma_f32_16x16x32_bf16 v[4:7], v[96:99], v[196:199], v[4:7]
	v_mfma_f32_16x16x32_bf16 v[36:39], v[164:167], v[196:199], v[36:39]
	v_mfma_f32_16x16x32_bf16 v[184:187], v[168:171], v[196:199], v[184:187]
	v_mfma_f32_16x16x32_bf16 v[100:103], v[172:175], v[196:199], v[100:103]
	ds_read_b128 v[196:199], v213 offset:47104
	global_load_dwordx4 v[88:91], v142, s[92:93] offset:1024
	s_waitcnt lgkmcnt(5)
	v_mfma_f32_16x16x32_bf16 v[8:11], v[96:99], v[160:163], v[8:11]
	v_mfma_f32_16x16x32_bf16 v[40:43], v[164:167], v[160:163], v[40:43]
	v_mfma_f32_16x16x32_bf16 v[204:207], v[168:171], v[160:163], v[204:207]
	v_mfma_f32_16x16x32_bf16 v[104:107], v[172:175], v[160:163], v[104:107]
	ds_read_b128 v[160:163], v212 offset:49152
	global_load_dwordx4 v[92:95], v150, s[92:93] offset:1024
	s_add_u32 s84, s84, 0x800
	s_addc_u32 s85, s85, 0
	s_add_u32 s92, s92, 0x800
	s_addc_u32 s93, s93, 0
	s_waitcnt lgkmcnt(5)
	v_mfma_f32_16x16x32_bf16 v[12:15], v[96:99], v[176:179], v[12:15]
	v_mfma_f32_16x16x32_bf16 v[44:47], v[164:167], v[176:179], v[44:47]
	v_mfma_f32_16x16x32_bf16 v[208:211], v[168:171], v[176:179], v[208:211]
	v_mfma_f32_16x16x32_bf16 v[108:111], v[172:175], v[176:179], v[108:111]
	ds_read_b128 v[176:179], v212 offset:51200
	s_waitcnt lgkmcnt(5)
	v_mfma_f32_16x16x32_bf16 v[16:19], v[96:99], v[180:183], v[16:19]
	v_mfma_f32_16x16x32_bf16 v[48:51], v[164:167], v[180:183], v[48:51]
	v_mfma_f32_16x16x32_bf16 v[232:235], v[168:171], v[180:183], v[232:235]
	v_mfma_f32_16x16x32_bf16 v[112:115], v[172:175], v[180:183], v[112:115]
	ds_read_b128 v[180:183], v212 offset:53248
	s_waitcnt lgkmcnt(5)
	v_mfma_f32_16x16x32_bf16 v[20:23], v[96:99], v[188:191], v[20:23]
	v_mfma_f32_16x16x32_bf16 v[52:55], v[164:167], v[188:191], v[52:55]
	v_mfma_f32_16x16x32_bf16 v[236:239], v[168:171], v[188:191], v[236:239]
	v_mfma_f32_16x16x32_bf16 v[116:119], v[172:175], v[188:191], v[116:119]
	ds_read_b128 v[188:191], v212 offset:55296
	s_waitcnt lgkmcnt(5)
	v_mfma_f32_16x16x32_bf16 v[24:27], v[96:99], v[192:195], v[24:27]
	v_mfma_f32_16x16x32_bf16 v[56:59], v[164:167], v[192:195], v[56:59]
	v_mfma_f32_16x16x32_bf16 v[240:243], v[168:171], v[192:195], v[240:243]
	v_mfma_f32_16x16x32_bf16 v[120:123], v[172:175], v[192:195], v[120:123]
	ds_read_b128 v[192:195], v212 offset:57344
	s_waitcnt lgkmcnt(5)
	v_mfma_f32_16x16x32_bf16 v[28:31], v[96:99], v[196:199], v[28:31]
	v_mfma_f32_16x16x32_bf16 v[60:63], v[164:167], v[196:199], v[60:63]
	v_mfma_f32_16x16x32_bf16 v[248:251], v[168:171], v[196:199], v[248:251]
	v_mfma_f32_16x16x32_bf16 v[124:127], v[172:175], v[196:199], v[124:127]
	s_waitcnt vmcnt(4)
	ds_read_b128 v[196:199], v212 offset:59392
	s_waitcnt lgkmcnt(5)
	v_mfma_f32_16x16x32_bf16 v[0:3], v[64:67], v[160:163], v[0:3]
	v_mfma_f32_16x16x32_bf16 v[32:35], v[68:71], v[160:163], v[32:35]
	v_mfma_f32_16x16x32_bf16 v[144:147], v[72:75], v[160:163], v[144:147]
	v_mfma_f32_16x16x32_bf16 v[252:255], v[76:79], v[160:163], v[252:255]
	ds_read_b128 v[160:163], v212 offset:61440
	s_waitcnt lgkmcnt(5)
	v_mfma_f32_16x16x32_bf16 v[4:7], v[64:67], v[176:179], v[4:7]
	v_mfma_f32_16x16x32_bf16 v[36:39], v[68:71], v[176:179], v[36:39]
	v_mfma_f32_16x16x32_bf16 v[184:187], v[72:75], v[176:179], v[184:187]
	v_mfma_f32_16x16x32_bf16 v[100:103], v[76:79], v[176:179], v[100:103]
	ds_read_b128 v[176:179], v212 offset:63488
	s_waitcnt lgkmcnt(5)
	v_mfma_f32_16x16x32_bf16 v[8:11], v[64:67], v[180:183], v[8:11]
	v_mfma_f32_16x16x32_bf16 v[40:43], v[68:71], v[180:183], v[40:43]
	v_mfma_f32_16x16x32_bf16 v[204:207], v[72:75], v[180:183], v[204:207]
	v_mfma_f32_16x16x32_bf16 v[104:107], v[76:79], v[180:183], v[104:107]
	ds_read_b128 v[180:183], v213 offset:49152
	s_waitcnt lgkmcnt(5)
	v_mfma_f32_16x16x32_bf16 v[12:15], v[64:67], v[188:191], v[12:15]
	v_mfma_f32_16x16x32_bf16 v[44:47], v[68:71], v[188:191], v[44:47]
	v_mfma_f32_16x16x32_bf16 v[208:211], v[72:75], v[188:191], v[208:211]
	v_mfma_f32_16x16x32_bf16 v[108:111], v[76:79], v[188:191], v[108:111]
	ds_read_b128 v[188:191], v213 offset:51200
	s_waitcnt lgkmcnt(5)
	v_mfma_f32_16x16x32_bf16 v[16:19], v[64:67], v[192:195], v[16:19]
	v_mfma_f32_16x16x32_bf16 v[48:51], v[68:71], v[192:195], v[48:51]
	v_mfma_f32_16x16x32_bf16 v[232:235], v[72:75], v[192:195], v[232:235]
	v_mfma_f32_16x16x32_bf16 v[112:115], v[76:79], v[192:195], v[112:115]
	ds_read_b128 v[192:195], v213 offset:53248
	s_waitcnt lgkmcnt(5)
	v_mfma_f32_16x16x32_bf16 v[20:23], v[64:67], v[196:199], v[20:23]
	v_mfma_f32_16x16x32_bf16 v[52:55], v[68:71], v[196:199], v[52:55]
	v_mfma_f32_16x16x32_bf16 v[236:239], v[72:75], v[196:199], v[236:239]
	v_mfma_f32_16x16x32_bf16 v[116:119], v[76:79], v[196:199], v[116:119]
	ds_read_b128 v[196:199], v213 offset:55296
	s_waitcnt lgkmcnt(5)
	v_mfma_f32_16x16x32_bf16 v[24:27], v[64:67], v[160:163], v[24:27]
	v_mfma_f32_16x16x32_bf16 v[56:59], v[68:71], v[160:163], v[56:59]
	v_mfma_f32_16x16x32_bf16 v[240:243], v[72:75], v[160:163], v[240:243]
	v_mfma_f32_16x16x32_bf16 v[120:123], v[76:79], v[160:163], v[120:123]
	ds_read_b128 v[160:163], v213 offset:57344
	s_waitcnt lgkmcnt(5)
	v_mfma_f32_16x16x32_bf16 v[28:31], v[64:67], v[176:179], v[28:31]
	v_mfma_f32_16x16x32_bf16 v[60:63], v[68:71], v[176:179], v[60:63]
	v_mfma_f32_16x16x32_bf16 v[248:251], v[72:75], v[176:179], v[248:251]
	v_mfma_f32_16x16x32_bf16 v[124:127], v[76:79], v[176:179], v[124:127]
	s_waitcnt vmcnt(0)
	ds_read_b128 v[176:179], v213 offset:59392
	s_waitcnt lgkmcnt(5)
	v_mfma_f32_16x16x32_bf16 v[0:3], v[80:83], v[180:183], v[0:3]
	v_mfma_f32_16x16x32_bf16 v[32:35], v[84:87], v[180:183], v[32:35]
	v_mfma_f32_16x16x32_bf16 v[144:147], v[88:91], v[180:183], v[144:147]
	v_mfma_f32_16x16x32_bf16 v[252:255], v[92:95], v[180:183], v[252:255]
	ds_read_b128 v[180:183], v213 offset:61440
	s_waitcnt lgkmcnt(5)
	v_mfma_f32_16x16x32_bf16 v[4:7], v[80:83], v[188:191], v[4:7]
	v_mfma_f32_16x16x32_bf16 v[36:39], v[84:87], v[188:191], v[36:39]
	v_mfma_f32_16x16x32_bf16 v[184:187], v[88:91], v[188:191], v[184:187]
	v_mfma_f32_16x16x32_bf16 v[100:103], v[92:95], v[188:191], v[100:103]
	ds_read_b128 v[188:191], v213 offset:63488
	s_waitcnt lgkmcnt(5)
	v_mfma_f32_16x16x32_bf16 v[8:11], v[80:83], v[192:195], v[8:11]
	v_mfma_f32_16x16x32_bf16 v[40:43], v[84:87], v[192:195], v[40:43]
	v_mfma_f32_16x16x32_bf16 v[204:207], v[88:91], v[192:195], v[204:207]
	v_mfma_f32_16x16x32_bf16 v[104:107], v[92:95], v[192:195], v[104:107]
	s_waitcnt lgkmcnt(4)
	v_mfma_f32_16x16x32_bf16 v[12:15], v[80:83], v[196:199], v[12:15]
	v_mfma_f32_16x16x32_bf16 v[44:47], v[84:87], v[196:199], v[44:47]
	v_mfma_f32_16x16x32_bf16 v[208:211], v[88:91], v[196:199], v[208:211]
	v_mfma_f32_16x16x32_bf16 v[108:111], v[92:95], v[196:199], v[108:111]
	s_waitcnt lgkmcnt(3)
	v_mfma_f32_16x16x32_bf16 v[16:19], v[80:83], v[160:163], v[16:19]
	v_mfma_f32_16x16x32_bf16 v[48:51], v[84:87], v[160:163], v[48:51]
	v_mfma_f32_16x16x32_bf16 v[232:235], v[88:91], v[160:163], v[232:235]
	v_mfma_f32_16x16x32_bf16 v[112:115], v[92:95], v[160:163], v[112:115]
	s_waitcnt lgkmcnt(2)
	v_mfma_f32_16x16x32_bf16 v[20:23], v[80:83], v[176:179], v[20:23]
	v_mfma_f32_16x16x32_bf16 v[52:55], v[84:87], v[176:179], v[52:55]
	v_mfma_f32_16x16x32_bf16 v[236:239], v[88:91], v[176:179], v[236:239]
	v_mfma_f32_16x16x32_bf16 v[116:119], v[92:95], v[176:179], v[116:119]
	s_waitcnt lgkmcnt(1)
	v_mfma_f32_16x16x32_bf16 v[24:27], v[80:83], v[180:183], v[24:27]
	v_mfma_f32_16x16x32_bf16 v[56:59], v[84:87], v[180:183], v[56:59]
	v_mfma_f32_16x16x32_bf16 v[240:243], v[88:91], v[180:183], v[240:243]
	v_mfma_f32_16x16x32_bf16 v[120:123], v[92:95], v[180:183], v[120:123]
	s_waitcnt lgkmcnt(0)
	v_mfma_f32_16x16x32_bf16 v[28:31], v[80:83], v[188:191], v[28:31]
	v_mfma_f32_16x16x32_bf16 v[60:63], v[84:87], v[188:191], v[60:63]
	v_mfma_f32_16x16x32_bf16 v[248:251], v[88:91], v[188:191], v[248:251]
	v_mfma_f32_16x16x32_bf16 v[124:127], v[92:95], v[188:191], v[124:127]
	s_nop 7
	s_nop 7
	s_waitcnt vmcnt(0) lgkmcnt(0)
	s_barrier
	v_mov_b32_e32 v150, v100
	v_mov_b32_e32 v151, v101
	v_mov_b32_e32 v156, v102
	v_mov_b32_e32 v158, v103
	v_mov_b32_e32 v159, v104
	v_mov_b32_e32 v160, v105
	v_mov_b32_e32 v183, v106
	v_mov_b32_e32 v188, v107
	v_mov_b32_e32 v189, v108
	v_mov_b32_e32 v212, v109
	v_mov_b32_e32 v213, v110
	v_mov_b32_e32 v214, v111
	v_mov_b32_e32 v216, v112
	v_mov_b32_e32 v218, v113
	v_mov_b32_e32 v220, v114
	v_mov_b32_e32 v222, v115
	v_mov_b32_e32 v224, v116
	v_mov_b32_e32 v226, v117
	v_mov_b32_e32 v228, v118
	v_mov_b32_e32 v230, v119
	v_mov_b32_e32 v231, v120
	v_mov_b32_e32 v244, v121
	v_mov_b32_e32 v245, v122
	ds_write_b32 v140, v123 offset:40960
	ds_write_b32 v140, v124 offset:41984
	ds_write_b32 v140, v125 offset:43008
	ds_write_b32 v140, v126 offset:44032
	ds_write_b32 v140, v127 offset:45056
	v_lshlrev_b32_e32 v64, 13, v135
	v_lshl_add_u32 v65, v134, 3, v138
	v_lshl_or_b32 v66, v134, 11, v64
	v_lshlrev_b32_e32 v68, 5, v138
	v_or3_b32 v161, v64, v137, v68
	v_lshl_or_b32 v162, v65, 2, v66
	v_add_u32_e32 v68, 0x60, v65
	v_add_u32_e32 v65, 0x70, v65
	v_and_b32_e32 v68, 0x7f, v68
	v_and_b32_e32 v65, 0x7f, v65
	v_lshl_or_b32 v163, v68, 2, v66
	v_lshl_or_b32 v164, v65, 2, v66
	v_add_u32_e32 v66, 8, v133
	v_and_b32_e32 v66, 0x78, v66
	v_lshlrev_b32_e32 v65, 9, v136
	v_lshlrev_b32_e32 v66, 2, v66
	v_or3_b32 v166, v64, v65, v66
	v_add_u32_e32 v66, 16, v133
	v_and_b32_e32 v66, 0x78, v66
	v_lshlrev_b32_e32 v65, 9, v132
	v_lshlrev_b32_e32 v66, 2, v66
	v_or3_b32 v168, v64, v65, v66
	v_add_u32_e32 v66, 24, v133
	v_and_b32_e32 v66, 0x78, v66
	v_lshlrev_b32_e32 v67, 5, v135
	v_lshlrev_b32_e32 v65, 9, v130
	v_lshlrev_b32_e32 v66, 2, v66
	v_or3_b32 v170, v64, v65, v66
	v_or_b32_e32 v64, 16, v67
	v_add_u32_e32 v68, 0x100, v131
	v_add_u32_e32 v69, 0x200, v131
	v_add_u32_e32 v70, 0x300, v131
	v_add_u32_e32 v71, 0x500, v131
	v_add_u32_e32 v72, 0x600, v131
	v_add_u32_e32 v73, 0x700, v131
	v_or_b32_e32 v172, v64, v134
	v_or_b32_e32 v173, v136, v64
	v_or_b32_e32 v174, v132, v64
	v_or_b32_e32 v175, v130, v64
	v_and_b32_e32 v64, 24, v153
	s_movk_i32 s90, 0x3c0
	v_lshrrev_b32_e32 v176, 4, v68
	v_lshrrev_b32_e32 v177, 4, v69
	v_lshrrev_b32_e32 v178, 4, v70
	v_lshrrev_b32_e32 v180, 4, v71
	v_lshrrev_b32_e32 v181, 4, v72
	v_lshrrev_b32_e32 v182, 4, v73
	v_or_b32_e32 v165, v134, v67
	v_or_b32_e32 v167, v136, v67
	v_or_b32_e32 v169, v132, v67
	v_or_b32_e32 v171, v130, v67
	v_and_or_b32 v64, v131, s90, v64
	v_mul_u32_u24_e32 v65, 0x110, v138
	v_lshlrev_b32_e32 v66, 4, v138
	v_mul_u32_u24_e32 v67, 0x110, v128
	v_mul_u32_u24_e32 v68, 0x110, v176
	v_mul_u32_u24_e32 v69, 0x110, v177
	v_mul_u32_u24_e32 v70, 0x110, v178
	v_mul_u32_u24_e32 v71, 0x110, v180
	v_mul_u32_u24_e32 v72, 0x110, v181
	v_mul_u32_u24_e32 v73, 0x110, v182
	v_or_b32_e32 v179, 64, v128
	v_lshlrev_b32_e32 v190, 2, v138
	v_add_u32_e32 v191, v64, v65
	v_add_u32_e32 v192, v66, v67
	v_add_u32_e32 v193, v66, v68
	v_add_u32_e32 v194, v66, v69
	v_add_u32_e32 v195, v66, v70
	v_add_u32_e32 v196, v66, v71
	v_add_u32_e32 v197, v66, v72
	v_add_u32_e32 v198, v66, v73
	v_mbcnt_hi_u32_b32 v199, -1, v155
	s_waitcnt lgkmcnt(0)
	s_mov_b64 s[6:7], -1
	s_cmp_lt_i32 s77, 5
	s_branch .Lmy_ip0_epi

.LBB0_430:
	s_lshr_b32 s90, s64, 3
	s_lshl_b32 s90, s90, 4
	s_and_b32 s91, s64, 7
	s_or_b32 s90, s90, s91
	s_lshl_b32 s91, s89, 3
	s_add_i32 s90, s90, s91
	s_ashr_i32 s1, s90, 31
	s_lshr_b32 s1, s1, 23
	s_add_i32 s1, s90, s1
	s_ashr_i32 s1, s1, 9
	s_and_b32 s0, s90, 7
	s_lshl_b32 s1, s1, 3
	s_or_b32 s38, s1, s0
	s_mul_hi_i32 s66, s38, 0x2aaaaaab
	s_lshr_b32 s0, s66, 31
	s_add_i32 s66, s66, s0
	s_lshl_b32 s0, s66, 3
	s_bfe_u32 s1, s90, 0x30003
	s_or_b32 s0, s0, s1
	s_mul_i32 s1, s66, 6
	s_sub_i32 s65, s38, s1
	s_lshl_b32 s1, s65, 3
	s_bfe_u32 s33, s90, 0x30006
	s_or_b32 s4, s1, s33
	s_ashr_i32 s1, s0, 31
	s_ashr_i32 s5, s4, 31
	s_lshl_b64 s[54:55], s[4:5], 18
	s_lshl_b64 s[56:57], s[0:1], 18
	s_cmp_lg_u32 s89, 0
	s_cbranch_scc1 .Lmy_ip1_pass2
	s_barrier
	s_add_u32 s84, s50, 0x3a00000
	s_addc_u32 s85, s51, 0
	s_add_u32 s84, s84, s56
	s_addc_u32 s85, s85, s57
	s_add_u32 s92, s84, 0x40000
	s_addc_u32 s93, s85, 0
	s_add_u32 s86, s50, s54
	s_addc_u32 s87, s51, s55
	s_lshl_b64 s[54:55], s[0:1], 17
	v_readfirstlane_b32 s88, v129
	v_and_b32_e32 v200, 15, v131
	v_bfe_u32 v201, v131, 4, 2
	v_and_b32_e32 v202, 63, v131
	v_lshlrev_b32_e32 v202, 4, v202
	v_lshrrev_b32_e32 v203, 6, v131
	v_lshl_add_u32 v66, v203, 16, v202
	v_add_u32_e32 v67, 0x8000, v66
	v_bfe_u32 v202, v131, 1, 3
	v_xor_b32_e32 v202, v201, v202
	v_lshlrev_b32_e32 v202, 4, v202
	v_lshl_or_b32 v75, v200, 7, v202
	v_xor_b32_e32 v212, 64, v75
	v_bfe_u32 v200, v131, 4, 3
	v_and_b32_e32 v201, 7, v131
	v_xor_b32_e32 v200, v200, v201
	v_lshlrev_b32_e32 v200, 4, v200
	v_lshrrev_b32_e32 v201, 3, v131
	v_lshl_or_b32 v68, v201, 11, v200
	v_add_u32_e32 v69, 65536, v68
	v_add_u32_e32 v71, 131072, v68
	v_add_u32_e32 v74, 196608, v68
	s_add_u32 m0, s88, 0
	s_nop 0
	global_load_lds_dwordx4 v68, s[86:87]
	s_add_u32 m0, s88, 4096
	s_nop 0
	global_load_lds_dwordx4 v69, s[86:87]
	s_add_u32 m0, s88, 8192
	s_nop 0
	global_load_lds_dwordx4 v71, s[86:87]
	s_add_u32 m0, s88, 12288
	s_nop 0
	global_load_lds_dwordx4 v74, s[86:87]
	s_add_u32 s86, s86, 128
	s_addc_u32 s87, s87, 0
	global_load_dwordx4 v[76:79], v66, s[84:85] offset:0
	global_load_dwordx4 v[80:83], v67, s[84:85] offset:0
	global_load_dwordx4 v[84:87], v66, s[92:93] offset:0
	global_load_dwordx4 v[88:91], v67, s[92:93] offset:0
	global_load_dwordx4 v[140:143], v66, s[84:85] offset:1024
	global_load_dwordx4 v[144:147], v67, s[84:85] offset:1024
	global_load_dwordx4 v[148:151], v66, s[92:93] offset:1024
	global_load_dwordx4 v[204:207], v67, s[92:93] offset:1024
	s_add_u32 s84, s84, 0x800
	s_addc_u32 s85, s85, 0
	s_add_u32 s92, s92, 0x800
	s_addc_u32 s93, s93, 0
	s_add_u32 m0, s88, 16384
	s_nop 0
	global_load_lds_dwordx4 v68, s[86:87]
	s_add_u32 m0, s88, 20480
	s_nop 0
	global_load_lds_dwordx4 v69, s[86:87]
	s_add_u32 m0, s88, 24576
	s_nop 0
	global_load_lds_dwordx4 v71, s[86:87]
	s_add_u32 m0, s88, 28672
	s_nop 0
	global_load_lds_dwordx4 v74, s[86:87]
	s_add_u32 s86, s86, 128
	s_addc_u32 s87, s87, 0
	s_add_u32 m0, s88, 32768
	s_nop 0
	global_load_lds_dwordx4 v68, s[86:87]
	s_add_u32 m0, s88, 36864
	s_nop 0
	global_load_lds_dwordx4 v69, s[86:87]
	s_add_u32 m0, s88, 40960
	s_nop 0
	global_load_lds_dwordx4 v71, s[86:87]
	s_add_u32 m0, s88, 45056
	s_nop 0
	global_load_lds_dwordx4 v74, s[86:87]
	s_add_u32 s86, s86, 128
	s_addc_u32 s87, s87, 0
	s_waitcnt vmcnt(12)
	s_barrier
	ds_read_b128 v[176:179], v75 offset:0
	ds_read_b128 v[180:183], v75 offset:2048
	ds_read_b128 v[184:187], v75 offset:4096
	ds_read_b128 v[192:195], v75 offset:6144
	ds_read_b128 v[196:199], v75 offset:8192
	ds_read_b128 v[200:203], v75 offset:10240
	global_load_dwordx4 v[160:163], v66, s[84:85] offset:0
	s_waitcnt lgkmcnt(5)
	v_mfma_f32_16x16x32_bf16 v[32:35], v[76:79], v[176:179], 0
	v_mfma_f32_16x16x32_bf16 v[4:7], v[80:83], v[176:179], 0
	v_mfma_f32_16x16x32_bf16 v[188:191], v[84:87], v[176:179], 0
	v_mfma_f32_16x16x32_bf16 v[96:99], v[88:91], v[176:179], 0
	ds_read_b128 v[176:179], v75 offset:12288
	global_load_dwordx4 v[164:167], v67, s[84:85] offset:0
	s_waitcnt lgkmcnt(5)
	v_mfma_f32_16x16x32_bf16 v[36:39], v[76:79], v[180:183], 0
	v_mfma_f32_16x16x32_bf16 v[12:15], v[80:83], v[180:183], 0
	v_mfma_f32_16x16x32_bf16 v[208:211], v[84:87], v[180:183], 0
	v_mfma_f32_16x16x32_bf16 v[100:103], v[88:91], v[180:183], 0
	ds_read_b128 v[180:183], v75 offset:14336
	global_load_dwordx4 v[168:171], v66, s[92:93] offset:0
	s_waitcnt lgkmcnt(5)
	v_mfma_f32_16x16x32_bf16 v[40:43], v[76:79], v[184:187], 0
	v_mfma_f32_16x16x32_bf16 v[16:19], v[80:83], v[184:187], 0
	v_mfma_f32_16x16x32_bf16 v[232:235], v[84:87], v[184:187], 0
	v_mfma_f32_16x16x32_bf16 v[104:107], v[88:91], v[184:187], 0
	ds_read_b128 v[184:187], v212 offset:0
	global_load_dwordx4 v[172:175], v67, s[92:93] offset:0
	s_waitcnt lgkmcnt(5)
	v_mfma_f32_16x16x32_bf16 v[44:47], v[76:79], v[192:195], 0
	v_mfma_f32_16x16x32_bf16 v[20:23], v[80:83], v[192:195], 0
	v_mfma_f32_16x16x32_bf16 v[236:239], v[84:87], v[192:195], 0
	v_mfma_f32_16x16x32_bf16 v[108:111], v[88:91], v[192:195], 0
	ds_read_b128 v[192:195], v212 offset:2048
	s_waitcnt lgkmcnt(5)
	v_mfma_f32_16x16x32_bf16 v[48:51], v[76:79], v[196:199], 0
	v_mfma_f32_16x16x32_bf16 v[0:3], v[80:83], v[196:199], 0
	v_mfma_f32_16x16x32_bf16 v[240:243], v[84:87], v[196:199], 0
	v_mfma_f32_16x16x32_bf16 v[112:115], v[88:91], v[196:199], 0
	ds_read_b128 v[196:199], v212 offset:4096
	s_waitcnt lgkmcnt(5)
	v_mfma_f32_16x16x32_bf16 v[52:55], v[76:79], v[200:203], 0
	v_mfma_f32_16x16x32_bf16 v[8:11], v[80:83], v[200:203], 0
	v_mfma_f32_16x16x32_bf16 v[248:251], v[84:87], v[200:203], 0
	v_mfma_f32_16x16x32_bf16 v[116:119], v[88:91], v[200:203], 0
	ds_read_b128 v[200:203], v212 offset:6144
	s_waitcnt lgkmcnt(5)
	v_mfma_f32_16x16x32_bf16 v[56:59], v[76:79], v[176:179], 0
	v_mfma_f32_16x16x32_bf16 v[24:27], v[80:83], v[176:179], 0
	v_mfma_f32_16x16x32_bf16 v[252:255], v[84:87], v[176:179], 0
	v_mfma_f32_16x16x32_bf16 v[120:123], v[88:91], v[176:179], 0
	ds_read_b128 v[176:179], v212 offset:8192
	s_waitcnt lgkmcnt(5)
	v_mfma_f32_16x16x32_bf16 v[60:63], v[76:79], v[180:183], 0
	v_mfma_f32_16x16x32_bf16 v[28:31], v[80:83], v[180:183], 0
	v_mfma_f32_16x16x32_bf16 v[92:95], v[84:87], v[180:183], 0
	v_mfma_f32_16x16x32_bf16 v[124:127], v[88:91], v[180:183], 0
	s_waitcnt vmcnt(8)
	s_barrier
	s_waitcnt vmcnt(12)
	ds_read_b128 v[180:183], v212 offset:10240
	global_load_dwordx4 v[76:79], v66, s[84:85] offset:1024
	s_waitcnt lgkmcnt(5)
	v_mfma_f32_16x16x32_bf16 v[32:35], v[140:143], v[184:187], v[32:35]
	v_mfma_f32_16x16x32_bf16 v[4:7], v[144:147], v[184:187], v[4:7]
	v_mfma_f32_16x16x32_bf16 v[188:191], v[148:151], v[184:187], v[188:191]
	v_mfma_f32_16x16x32_bf16 v[96:99], v[204:207], v[184:187], v[96:99]
	ds_read_b128 v[184:187], v212 offset:12288
	global_load_dwordx4 v[80:83], v67, s[84:85] offset:1024
	s_waitcnt lgkmcnt(5)
	v_mfma_f32_16x16x32_bf16 v[36:39], v[140:143], v[192:195], v[36:39]
	v_mfma_f32_16x16x32_bf16 v[12:15], v[144:147], v[192:195], v[12:15]
	v_mfma_f32_16x16x32_bf16 v[208:211], v[148:151], v[192:195], v[208:211]
	v_mfma_f32_16x16x32_bf16 v[100:103], v[204:207], v[192:195], v[100:103]
	ds_read_b128 v[192:195], v212 offset:14336
	global_load_dwordx4 v[84:87], v66, s[92:93] offset:1024
	s_waitcnt lgkmcnt(5)
	v_mfma_f32_16x16x32_bf16 v[40:43], v[140:143], v[196:199], v[40:43]
	v_mfma_f32_16x16x32_bf16 v[16:19], v[144:147], v[196:199], v[16:19]
	v_mfma_f32_16x16x32_bf16 v[232:235], v[148:151], v[196:199], v[232:235]
	v_mfma_f32_16x16x32_bf16 v[104:107], v[204:207], v[196:199], v[104:107]
	ds_read_b128 v[196:199], v75 offset:16384
	global_load_dwordx4 v[88:91], v67, s[92:93] offset:1024
	s_add_u32 s84, s84, 0x800
	s_addc_u32 s85, s85, 0
	s_add_u32 s92, s92, 0x800
	s_addc_u32 s93, s93, 0
	s_waitcnt lgkmcnt(5)
	v_mfma_f32_16x16x32_bf16 v[44:47], v[140:143], v[200:203], v[44:47]
	v_mfma_f32_16x16x32_bf16 v[20:23], v[144:147], v[200:203], v[20:23]
	v_mfma_f32_16x16x32_bf16 v[236:239], v[148:151], v[200:203], v[236:239]
	v_mfma_f32_16x16x32_bf16 v[108:111], v[204:207], v[200:203], v[108:111]
	ds_read_b128 v[200:203], v75 offset:18432
	s_add_u32 m0, s88, 49152
	s_nop 0
	global_load_lds_dwordx4 v68, s[86:87]
	s_waitcnt lgkmcnt(5)
	v_mfma_f32_16x16x32_bf16 v[48:51], v[140:143], v[176:179], v[48:51]
	v_mfma_f32_16x16x32_bf16 v[0:3], v[144:147], v[176:179], v[0:3]
	v_mfma_f32_16x16x32_bf16 v[240:243], v[148:151], v[176:179], v[240:243]
	v_mfma_f32_16x16x32_bf16 v[112:115], v[204:207], v[176:179], v[112:115]
	ds_read_b128 v[176:179], v75 offset:20480
	s_add_u32 m0, s88, 53248
	s_nop 0
	global_load_lds_dwordx4 v69, s[86:87]
	s_waitcnt lgkmcnt(5)
	v_mfma_f32_16x16x32_bf16 v[52:55], v[140:143], v[180:183], v[52:55]
	v_mfma_f32_16x16x32_bf16 v[8:11], v[144:147], v[180:183], v[8:11]
	v_mfma_f32_16x16x32_bf16 v[248:251], v[148:151], v[180:183], v[248:251]
	v_mfma_f32_16x16x32_bf16 v[116:119], v[204:207], v[180:183], v[116:119]
	ds_read_b128 v[180:183], v75 offset:22528
	s_add_u32 m0, s88, 57344
	s_nop 0
	global_load_lds_dwordx4 v71, s[86:87]
	s_waitcnt lgkmcnt(5)
	v_mfma_f32_16x16x32_bf16 v[56:59], v[140:143], v[184:187], v[56:59]
	v_mfma_f32_16x16x32_bf16 v[24:27], v[144:147], v[184:187], v[24:27]
	v_mfma_f32_16x16x32_bf16 v[252:255], v[148:151], v[184:187], v[252:255]
	v_mfma_f32_16x16x32_bf16 v[120:123], v[204:207], v[184:187], v[120:123]
	ds_read_b128 v[184:187], v75 offset:24576
	s_add_u32 m0, s88, 61440
	s_nop 0
	global_load_lds_dwordx4 v74, s[86:87]
	s_add_u32 s86, s86, 128
	s_addc_u32 s87, s87, 0
	s_waitcnt lgkmcnt(5)
	v_mfma_f32_16x16x32_bf16 v[60:63], v[140:143], v[192:195], v[60:63]
	v_mfma_f32_16x16x32_bf16 v[28:31], v[144:147], v[192:195], v[28:31]
	v_mfma_f32_16x16x32_bf16 v[92:95], v[148:151], v[192:195], v[92:95]
	v_mfma_f32_16x16x32_bf16 v[124:127], v[204:207], v[192:195], v[124:127]
	s_waitcnt vmcnt(8)
	ds_read_b128 v[192:195], v75 offset:26624
	global_load_dwordx4 v[140:143], v66, s[84:85] offset:0
	s_waitcnt lgkmcnt(5)
	v_mfma_f32_16x16x32_bf16 v[32:35], v[160:163], v[196:199], v[32:35]
	v_mfma_f32_16x16x32_bf16 v[4:7], v[164:167], v[196:199], v[4:7]
	v_mfma_f32_16x16x32_bf16 v[188:191], v[168:171], v[196:199], v[188:191]
	v_mfma_f32_16x16x32_bf16 v[96:99], v[172:175], v[196:199], v[96:99]
	ds_read_b128 v[196:199], v75 offset:28672
	global_load_dwordx4 v[144:147], v67, s[84:85] offset:0
	s_waitcnt lgkmcnt(5)
	v_mfma_f32_16x16x32_bf16 v[36:39], v[160:163], v[200:203], v[36:39]
	v_mfma_f32_16x16x32_bf16 v[12:15], v[164:167], v[200:203], v[12:15]
	v_mfma_f32_16x16x32_bf16 v[208:211], v[168:171], v[200:203], v[208:211]
	v_mfma_f32_16x16x32_bf16 v[100:103], v[172:175], v[200:203], v[100:103]
	ds_read_b128 v[200:203], v75 offset:30720
	global_load_dwordx4 v[148:151], v66, s[92:93] offset:0
	s_waitcnt lgkmcnt(5)
	v_mfma_f32_16x16x32_bf16 v[40:43], v[160:163], v[176:179], v[40:43]
	v_mfma_f32_16x16x32_bf16 v[16:19], v[164:167], v[176:179], v[16:19]
	v_mfma_f32_16x16x32_bf16 v[232:235], v[168:171], v[176:179], v[232:235]
	v_mfma_f32_16x16x32_bf16 v[104:107], v[172:175], v[176:179], v[104:107]
	ds_read_b128 v[176:179], v212 offset:16384
	global_load_dwordx4 v[204:207], v67, s[92:93] offset:0
	s_waitcnt lgkmcnt(5)
	v_mfma_f32_16x16x32_bf16 v[44:47], v[160:163], v[180:183], v[44:47]
	v_mfma_f32_16x16x32_bf16 v[20:23], v[164:167], v[180:183], v[20:23]
	v_mfma_f32_16x16x32_bf16 v[236:239], v[168:171], v[180:183], v[236:239]
	v_mfma_f32_16x16x32_bf16 v[108:111], v[172:175], v[180:183], v[108:111]
	ds_read_b128 v[180:183], v212 offset:18432
	s_waitcnt lgkmcnt(5)
	v_mfma_f32_16x16x32_bf16 v[48:51], v[160:163], v[184:187], v[48:51]
	v_mfma_f32_16x16x32_bf16 v[0:3], v[164:167], v[184:187], v[0:3]
	v_mfma_f32_16x16x32_bf16 v[240:243], v[168:171], v[184:187], v[240:243]
	v_mfma_f32_16x16x32_bf16 v[112:115], v[172:175], v[184:187], v[112:115]
	ds_read_b128 v[184:187], v212 offset:20480
	s_waitcnt lgkmcnt(5)
	v_mfma_f32_16x16x32_bf16 v[52:55], v[160:163], v[192:195], v[52:55]
	v_mfma_f32_16x16x32_bf16 v[8:11], v[164:167], v[192:195], v[8:11]
	v_mfma_f32_16x16x32_bf16 v[248:251], v[168:171], v[192:195], v[248:251]
	v_mfma_f32_16x16x32_bf16 v[116:119], v[172:175], v[192:195], v[116:119]
	ds_read_b128 v[192:195], v212 offset:22528
	s_waitcnt lgkmcnt(5)
	v_mfma_f32_16x16x32_bf16 v[56:59], v[160:163], v[196:199], v[56:59]
	v_mfma_f32_16x16x32_bf16 v[24:27], v[164:167], v[196:199], v[24:27]
	v_mfma_f32_16x16x32_bf16 v[252:255], v[168:171], v[196:199], v[252:255]
	v_mfma_f32_16x16x32_bf16 v[120:123], v[172:175], v[196:199], v[120:123]
	ds_read_b128 v[196:199], v212 offset:24576
	s_waitcnt lgkmcnt(5)
	v_mfma_f32_16x16x32_bf16 v[60:63], v[160:163], v[200:203], v[60:63]
	v_mfma_f32_16x16x32_bf16 v[28:31], v[164:167], v[200:203], v[28:31]
	v_mfma_f32_16x16x32_bf16 v[92:95], v[168:171], v[200:203], v[92:95]
	v_mfma_f32_16x16x32_bf16 v[124:127], v[172:175], v[200:203], v[124:127]
	s_waitcnt vmcnt(16)
	s_barrier
	s_waitcnt vmcnt(8)
	ds_read_b128 v[200:203], v212 offset:26624
	global_load_dwordx4 v[160:163], v66, s[84:85] offset:1024
	s_waitcnt lgkmcnt(5)
	v_mfma_f32_16x16x32_bf16 v[32:35], v[76:79], v[176:179], v[32:35]
	v_mfma_f32_16x16x32_bf16 v[4:7], v[80:83], v[176:179], v[4:7]
	v_mfma_f32_16x16x32_bf16 v[188:191], v[84:87], v[176:179], v[188:191]
	v_mfma_f32_16x16x32_bf16 v[96:99], v[88:91], v[176:179], v[96:99]
	ds_read_b128 v[176:179], v212 offset:28672
	global_load_dwordx4 v[164:167], v67, s[84:85] offset:1024
	s_waitcnt lgkmcnt(5)
	v_mfma_f32_16x16x32_bf16 v[36:39], v[76:79], v[180:183], v[36:39]
	v_mfma_f32_16x16x32_bf16 v[12:15], v[80:83], v[180:183], v[12:15]
	v_mfma_f32_16x16x32_bf16 v[208:211], v[84:87], v[180:183], v[208:211]
	v_mfma_f32_16x16x32_bf16 v[100:103], v[88:91], v[180:183], v[100:103]
	ds_read_b128 v[180:183], v212 offset:30720
	global_load_dwordx4 v[168:171], v66, s[92:93] offset:1024
	s_waitcnt lgkmcnt(5)
	v_mfma_f32_16x16x32_bf16 v[40:43], v[76:79], v[184:187], v[40:43]
	v_mfma_f32_16x16x32_bf16 v[16:19], v[80:83], v[184:187], v[16:19]
	v_mfma_f32_16x16x32_bf16 v[232:235], v[84:87], v[184:187], v[232:235]
	v_mfma_f32_16x16x32_bf16 v[104:107], v[88:91], v[184:187], v[104:107]
	ds_read_b128 v[184:187], v75 offset:32768
	global_load_dwordx4 v[172:175], v67, s[92:93] offset:1024
	s_add_u32 s84, s84, 0x800
	s_addc_u32 s85, s85, 0
	s_add_u32 s92, s92, 0x800
	s_addc_u32 s93, s93, 0
	s_waitcnt lgkmcnt(5)
	v_mfma_f32_16x16x32_bf16 v[44:47], v[76:79], v[192:195], v[44:47]
	v_mfma_f32_16x16x32_bf16 v[20:23], v[80:83], v[192:195], v[20:23]
	v_mfma_f32_16x16x32_bf16 v[236:239], v[84:87], v[192:195], v[236:239]
	v_mfma_f32_16x16x32_bf16 v[108:111], v[88:91], v[192:195], v[108:111]
	ds_read_b128 v[192:195], v75 offset:34816
	s_add_u32 m0, s88, 0
	s_nop 0
	global_load_lds_dwordx4 v68, s[86:87]
	s_waitcnt lgkmcnt(5)
	v_mfma_f32_16x16x32_bf16 v[48:51], v[76:79], v[196:199], v[48:51]
	v_mfma_f32_16x16x32_bf16 v[0:3], v[80:83], v[196:199], v[0:3]
	v_mfma_f32_16x16x32_bf16 v[240:243], v[84:87], v[196:199], v[240:243]
	v_mfma_f32_16x16x32_bf16 v[112:115], v[88:91], v[196:199], v[112:115]
	ds_read_b128 v[196:199], v75 offset:36864
	s_add_u32 m0, s88, 4096
	s_nop 0
	global_load_lds_dwordx4 v69, s[86:87]
	s_waitcnt lgkmcnt(5)
	v_mfma_f32_16x16x32_bf16 v[52:55], v[76:79], v[200:203], v[52:55]
	v_mfma_f32_16x16x32_bf16 v[8:11], v[80:83], v[200:203], v[8:11]
	v_mfma_f32_16x16x32_bf16 v[248:251], v[84:87], v[200:203], v[248:251]
	v_mfma_f32_16x16x32_bf16 v[116:119], v[88:91], v[200:203], v[116:119]
	ds_read_b128 v[200:203], v75 offset:38912
	s_add_u32 m0, s88, 8192
	s_nop 0
	global_load_lds_dwordx4 v71, s[86:87]
	s_waitcnt lgkmcnt(5)
	v_mfma_f32_16x16x32_bf16 v[56:59], v[76:79], v[176:179], v[56:59]
	v_mfma_f32_16x16x32_bf16 v[24:27], v[80:83], v[176:179], v[24:27]
	v_mfma_f32_16x16x32_bf16 v[252:255], v[84:87], v[176:179], v[252:255]
	v_mfma_f32_16x16x32_bf16 v[120:123], v[88:91], v[176:179], v[120:123]
	ds_read_b128 v[176:179], v75 offset:40960
	s_add_u32 m0, s88, 12288
	s_nop 0
	global_load_lds_dwordx4 v74, s[86:87]
	s_add_u32 s86, s86, 128
	s_addc_u32 s87, s87, 0
	s_waitcnt lgkmcnt(5)
	v_mfma_f32_16x16x32_bf16 v[60:63], v[76:79], v[180:183], v[60:63]
	v_mfma_f32_16x16x32_bf16 v[28:31], v[80:83], v[180:183], v[28:31]
	v_mfma_f32_16x16x32_bf16 v[92:95], v[84:87], v[180:183], v[92:95]
	v_mfma_f32_16x16x32_bf16 v[124:127], v[88:91], v[180:183], v[124:127]
	s_waitcnt vmcnt(8)
	ds_read_b128 v[180:183], v75 offset:43008
	global_load_dwordx4 v[76:79], v66, s[84:85] offset:0
	s_waitcnt lgkmcnt(5)
	v_mfma_f32_16x16x32_bf16 v[32:35], v[140:143], v[184:187], v[32:35]
	v_mfma_f32_16x16x32_bf16 v[4:7], v[144:147], v[184:187], v[4:7]
	v_mfma_f32_16x16x32_bf16 v[188:191], v[148:151], v[184:187], v[188:191]
	v_mfma_f32_16x16x32_bf16 v[96:99], v[204:207], v[184:187], v[96:99]
	ds_read_b128 v[184:187], v75 offset:45056
	global_load_dwordx4 v[80:83], v67, s[84:85] offset:0
	s_waitcnt lgkmcnt(5)
	v_mfma_f32_16x16x32_bf16 v[36:39], v[140:143], v[192:195], v[36:39]
	v_mfma_f32_16x16x32_bf16 v[12:15], v[144:147], v[192:195], v[12:15]
	v_mfma_f32_16x16x32_bf16 v[208:211], v[148:151], v[192:195], v[208:211]
	v_mfma_f32_16x16x32_bf16 v[100:103], v[204:207], v[192:195], v[100:103]
	ds_read_b128 v[192:195], v75 offset:47104
	global_load_dwordx4 v[84:87], v66, s[92:93] offset:0
	s_waitcnt lgkmcnt(5)
	v_mfma_f32_16x16x32_bf16 v[40:43], v[140:143], v[196:199], v[40:43]
	v_mfma_f32_16x16x32_bf16 v[16:19], v[144:147], v[196:199], v[16:19]
	v_mfma_f32_16x16x32_bf16 v[232:235], v[148:151], v[196:199], v[232:235]
	v_mfma_f32_16x16x32_bf16 v[104:107], v[204:207], v[196:199], v[104:107]
	ds_read_b128 v[196:199], v212 offset:32768
	global_load_dwordx4 v[88:91], v67, s[92:93] offset:0
	s_waitcnt lgkmcnt(5)
	v_mfma_f32_16x16x32_bf16 v[44:47], v[140:143], v[200:203], v[44:47]
	v_mfma_f32_16x16x32_bf16 v[20:23], v[144:147], v[200:203], v[20:23]
	v_mfma_f32_16x16x32_bf16 v[236:239], v[148:151], v[200:203], v[236:239]
	v_mfma_f32_16x16x32_bf16 v[108:111], v[204:207], v[200:203], v[108:111]
	ds_read_b128 v[200:203], v212 offset:34816
	s_waitcnt lgkmcnt(5)
	v_mfma_f32_16x16x32_bf16 v[48:51], v[140:143], v[176:179], v[48:51]
	v_mfma_f32_16x16x32_bf16 v[0:3], v[144:147], v[176:179], v[0:3]
	v_mfma_f32_16x16x32_bf16 v[240:243], v[148:151], v[176:179], v[240:243]
	v_mfma_f32_16x16x32_bf16 v[112:115], v[204:207], v[176:179], v[112:115]
	ds_read_b128 v[176:179], v212 offset:36864
	s_waitcnt lgkmcnt(5)
	v_mfma_f32_16x16x32_bf16 v[52:55], v[140:143], v[180:183], v[52:55]
	v_mfma_f32_16x16x32_bf16 v[8:11], v[144:147], v[180:183], v[8:11]
	v_mfma_f32_16x16x32_bf16 v[248:251], v[148:151], v[180:183], v[248:251]
	v_mfma_f32_16x16x32_bf16 v[116:119], v[204:207], v[180:183], v[116:119]
	ds_read_b128 v[180:183], v212 offset:38912
	s_waitcnt lgkmcnt(5)
	v_mfma_f32_16x16x32_bf16 v[56:59], v[140:143], v[184:187], v[56:59]
	v_mfma_f32_16x16x32_bf16 v[24:27], v[144:147], v[184:187], v[24:27]
	v_mfma_f32_16x16x32_bf16 v[252:255], v[148:151], v[184:187], v[252:255]
	v_mfma_f32_16x16x32_bf16 v[120:123], v[204:207], v[184:187], v[120:123]
	ds_read_b128 v[184:187], v212 offset:40960
	s_waitcnt lgkmcnt(5)
	v_mfma_f32_16x16x32_bf16 v[60:63], v[140:143], v[192:195], v[60:63]
	v_mfma_f32_16x16x32_bf16 v[28:31], v[144:147], v[192:195], v[28:31]
	v_mfma_f32_16x16x32_bf16 v[92:95], v[148:151], v[192:195], v[92:95]
	v_mfma_f32_16x16x32_bf16 v[124:127], v[204:207], v[192:195], v[124:127]
	s_waitcnt vmcnt(16)
	s_barrier
	s_waitcnt vmcnt(8)
	ds_read_b128 v[192:195], v212 offset:43008
	global_load_dwordx4 v[140:143], v66, s[84:85] offset:1024
	s_waitcnt lgkmcnt(5)
	v_mfma_f32_16x16x32_bf16 v[32:35], v[160:163], v[196:199], v[32:35]
	v_mfma_f32_16x16x32_bf16 v[4:7], v[164:167], v[196:199], v[4:7]
	v_mfma_f32_16x16x32_bf16 v[188:191], v[168:171], v[196:199], v[188:191]
	v_mfma_f32_16x16x32_bf16 v[96:99], v[172:175], v[196:199], v[96:99]
	ds_read_b128 v[196:199], v212 offset:45056
	global_load_dwordx4 v[144:147], v67, s[84:85] offset:1024
	s_waitcnt lgkmcnt(5)
	v_mfma_f32_16x16x32_bf16 v[36:39], v[160:163], v[200:203], v[36:39]
	v_mfma_f32_16x16x32_bf16 v[12:15], v[164:167], v[200:203], v[12:15]
	v_mfma_f32_16x16x32_bf16 v[208:211], v[168:171], v[200:203], v[208:211]
	v_mfma_f32_16x16x32_bf16 v[100:103], v[172:175], v[200:203], v[100:103]
	ds_read_b128 v[200:203], v212 offset:47104
	global_load_dwordx4 v[148:151], v66, s[92:93] offset:1024
	s_waitcnt lgkmcnt(5)
	v_mfma_f32_16x16x32_bf16 v[40:43], v[160:163], v[176:179], v[40:43]
	v_mfma_f32_16x16x32_bf16 v[16:19], v[164:167], v[176:179], v[16:19]
	v_mfma_f32_16x16x32_bf16 v[232:235], v[168:171], v[176:179], v[232:235]
	v_mfma_f32_16x16x32_bf16 v[104:107], v[172:175], v[176:179], v[104:107]
	ds_read_b128 v[176:179], v75 offset:49152
	global_load_dwordx4 v[204:207], v67, s[92:93] offset:1024
	s_add_u32 s84, s84, 0x800
	s_addc_u32 s85, s85, 0
	s_add_u32 s92, s92, 0x800
	s_addc_u32 s93, s93, 0
	s_waitcnt lgkmcnt(5)
	v_mfma_f32_16x16x32_bf16 v[44:47], v[160:163], v[180:183], v[44:47]
	v_mfma_f32_16x16x32_bf16 v[20:23], v[164:167], v[180:183], v[20:23]
	v_mfma_f32_16x16x32_bf16 v[236:239], v[168:171], v[180:183], v[236:239]
	v_mfma_f32_16x16x32_bf16 v[108:111], v[172:175], v[180:183], v[108:111]
	ds_read_b128 v[180:183], v75 offset:51200
	s_add_u32 m0, s88, 16384
	s_nop 0
	global_load_lds_dwordx4 v68, s[86:87]
	s_waitcnt lgkmcnt(5)
	v_mfma_f32_16x16x32_bf16 v[48:51], v[160:163], v[184:187], v[48:51]
	v_mfma_f32_16x16x32_bf16 v[0:3], v[164:167], v[184:187], v[0:3]
	v_mfma_f32_16x16x32_bf16 v[240:243], v[168:171], v[184:187], v[240:243]
	v_mfma_f32_16x16x32_bf16 v[112:115], v[172:175], v[184:187], v[112:115]
	ds_read_b128 v[184:187], v75 offset:53248
	s_add_u32 m0, s88, 20480
	s_nop 0
	global_load_lds_dwordx4 v69, s[86:87]
	s_waitcnt lgkmcnt(5)
	v_mfma_f32_16x16x32_bf16 v[52:55], v[160:163], v[192:195], v[52:55]
	v_mfma_f32_16x16x32_bf16 v[8:11], v[164:167], v[192:195], v[8:11]
	v_mfma_f32_16x16x32_bf16 v[248:251], v[168:171], v[192:195], v[248:251]
	v_mfma_f32_16x16x32_bf16 v[116:119], v[172:175], v[192:195], v[116:119]
	ds_read_b128 v[192:195], v75 offset:55296
	s_add_u32 m0, s88, 24576
	s_nop 0
	global_load_lds_dwordx4 v71, s[86:87]
	s_waitcnt lgkmcnt(5)
	v_mfma_f32_16x16x32_bf16 v[56:59], v[160:163], v[196:199], v[56:59]
	v_mfma_f32_16x16x32_bf16 v[24:27], v[164:167], v[196:199], v[24:27]
	v_mfma_f32_16x16x32_bf16 v[252:255], v[168:171], v[196:199], v[252:255]
	v_mfma_f32_16x16x32_bf16 v[120:123], v[172:175], v[196:199], v[120:123]
	ds_read_b128 v[196:199], v75 offset:57344
	s_add_u32 m0, s88, 28672
	s_nop 0
	global_load_lds_dwordx4 v74, s[86:87]
	s_add_u32 s86, s86, 128
	s_addc_u32 s87, s87, 0
	s_waitcnt lgkmcnt(5)
	v_mfma_f32_16x16x32_bf16 v[60:63], v[160:163], v[200:203], v[60:63]
	v_mfma_f32_16x16x32_bf16 v[28:31], v[164:167], v[200:203], v[28:31]
	v_mfma_f32_16x16x32_bf16 v[92:95], v[168:171], v[200:203], v[92:95]
	v_mfma_f32_16x16x32_bf16 v[124:127], v[172:175], v[200:203], v[124:127]
	s_waitcnt vmcnt(8)
	ds_read_b128 v[200:203], v75 offset:59392
	global_load_dwordx4 v[160:163], v66, s[84:85] offset:0
	s_waitcnt lgkmcnt(5)
	v_mfma_f32_16x16x32_bf16 v[32:35], v[76:79], v[176:179], v[32:35]
	v_mfma_f32_16x16x32_bf16 v[4:7], v[80:83], v[176:179], v[4:7]
	v_mfma_f32_16x16x32_bf16 v[188:191], v[84:87], v[176:179], v[188:191]
	v_mfma_f32_16x16x32_bf16 v[96:99], v[88:91], v[176:179], v[96:99]
	ds_read_b128 v[176:179], v75 offset:61440
	global_load_dwordx4 v[164:167], v67, s[84:85] offset:0
	s_waitcnt lgkmcnt(5)
	v_mfma_f32_16x16x32_bf16 v[36:39], v[76:79], v[180:183], v[36:39]
	v_mfma_f32_16x16x32_bf16 v[12:15], v[80:83], v[180:183], v[12:15]
	v_mfma_f32_16x16x32_bf16 v[208:211], v[84:87], v[180:183], v[208:211]
	v_mfma_f32_16x16x32_bf16 v[100:103], v[88:91], v[180:183], v[100:103]
	ds_read_b128 v[180:183], v75 offset:63488
	global_load_dwordx4 v[168:171], v66, s[92:93] offset:0
	s_waitcnt lgkmcnt(5)
	v_mfma_f32_16x16x32_bf16 v[40:43], v[76:79], v[184:187], v[40:43]
	v_mfma_f32_16x16x32_bf16 v[16:19], v[80:83], v[184:187], v[16:19]
	v_mfma_f32_16x16x32_bf16 v[232:235], v[84:87], v[184:187], v[232:235]
	v_mfma_f32_16x16x32_bf16 v[104:107], v[88:91], v[184:187], v[104:107]
	ds_read_b128 v[184:187], v212 offset:49152
	global_load_dwordx4 v[172:175], v67, s[92:93] offset:0
	s_waitcnt lgkmcnt(5)
	v_mfma_f32_16x16x32_bf16 v[44:47], v[76:79], v[192:195], v[44:47]
	v_mfma_f32_16x16x32_bf16 v[20:23], v[80:83], v[192:195], v[20:23]
	v_mfma_f32_16x16x32_bf16 v[236:239], v[84:87], v[192:195], v[236:239]
	v_mfma_f32_16x16x32_bf16 v[108:111], v[88:91], v[192:195], v[108:111]
	ds_read_b128 v[192:195], v212 offset:51200
	s_waitcnt lgkmcnt(5)
	v_mfma_f32_16x16x32_bf16 v[48:51], v[76:79], v[196:199], v[48:51]
	v_mfma_f32_16x16x32_bf16 v[0:3], v[80:83], v[196:199], v[0:3]
	v_mfma_f32_16x16x32_bf16 v[240:243], v[84:87], v[196:199], v[240:243]
	v_mfma_f32_16x16x32_bf16 v[112:115], v[88:91], v[196:199], v[112:115]
	ds_read_b128 v[196:199], v212 offset:53248
	s_waitcnt lgkmcnt(5)
	v_mfma_f32_16x16x32_bf16 v[52:55], v[76:79], v[200:203], v[52:55]
	v_mfma_f32_16x16x32_bf16 v[8:11], v[80:83], v[200:203], v[8:11]
	v_mfma_f32_16x16x32_bf16 v[248:251], v[84:87], v[200:203], v[248:251]
	v_mfma_f32_16x16x32_bf16 v[116:119], v[88:91], v[200:203], v[116:119]
	ds_read_b128 v[200:203], v212 offset:55296
	s_waitcnt lgkmcnt(5)
	v_mfma_f32_16x16x32_bf16 v[56:59], v[76:79], v[176:179], v[56:59]
	v_mfma_f32_16x16x32_bf16 v[24:27], v[80:83], v[176:179], v[24:27]
	v_mfma_f32_16x16x32_bf16 v[252:255], v[84:87], v[176:179], v[252:255]
	v_mfma_f32_16x16x32_bf16 v[120:123], v[88:91], v[176:179], v[120:123]
	ds_read_b128 v[176:179], v212 offset:57344
	s_waitcnt lgkmcnt(5)
	v_mfma_f32_16x16x32_bf16 v[60:63], v[76:79], v[180:183], v[60:63]
	v_mfma_f32_16x16x32_bf16 v[28:31], v[80:83], v[180:183], v[28:31]
	v_mfma_f32_16x16x32_bf16 v[92:95], v[84:87], v[180:183], v[92:95]
	v_mfma_f32_16x16x32_bf16 v[124:127], v[88:91], v[180:183], v[124:127]
	s_waitcnt vmcnt(16)
	s_barrier
	s_waitcnt vmcnt(8)
	ds_read_b128 v[180:183], v212 offset:59392
	global_load_dwordx4 v[76:79], v66, s[84:85] offset:1024
	s_waitcnt lgkmcnt(5)
	v_mfma_f32_16x16x32_bf16 v[32:35], v[140:143], v[184:187], v[32:35]
	v_mfma_f32_16x16x32_bf16 v[4:7], v[144:147], v[184:187], v[4:7]
	v_mfma_f32_16x16x32_bf16 v[188:191], v[148:151], v[184:187], v[188:191]
	v_mfma_f32_16x16x32_bf16 v[96:99], v[204:207], v[184:187], v[96:99]
	ds_read_b128 v[184:187], v212 offset:61440
	global_load_dwordx4 v[80:83], v67, s[84:85] offset:1024
	s_waitcnt lgkmcnt(5)
	v_mfma_f32_16x16x32_bf16 v[36:39], v[140:143], v[192:195], v[36:39]
	v_mfma_f32_16x16x32_bf16 v[12:15], v[144:147], v[192:195], v[12:15]
	v_mfma_f32_16x16x32_bf16 v[208:211], v[148:151], v[192:195], v[208:211]
	v_mfma_f32_16x16x32_bf16 v[100:103], v[204:207], v[192:195], v[100:103]
	ds_read_b128 v[192:195], v212 offset:63488
	global_load_dwordx4 v[84:87], v66, s[92:93] offset:1024
	s_waitcnt lgkmcnt(5)
	v_mfma_f32_16x16x32_bf16 v[40:43], v[140:143], v[196:199], v[40:43]
	v_mfma_f32_16x16x32_bf16 v[16:19], v[144:147], v[196:199], v[16:19]
	v_mfma_f32_16x16x32_bf16 v[232:235], v[148:151], v[196:199], v[232:235]
	v_mfma_f32_16x16x32_bf16 v[104:107], v[204:207], v[196:199], v[104:107]
	ds_read_b128 v[196:199], v75 offset:0
	global_load_dwordx4 v[88:91], v67, s[92:93] offset:1024
	s_add_u32 s84, s84, 0x800
	s_addc_u32 s85, s85, 0
	s_add_u32 s92, s92, 0x800
	s_addc_u32 s93, s93, 0
	s_waitcnt lgkmcnt(5)
	v_mfma_f32_16x16x32_bf16 v[44:47], v[140:143], v[200:203], v[44:47]
	v_mfma_f32_16x16x32_bf16 v[20:23], v[144:147], v[200:203], v[20:23]
	v_mfma_f32_16x16x32_bf16 v[236:239], v[148:151], v[200:203], v[236:239]
	v_mfma_f32_16x16x32_bf16 v[108:111], v[204:207], v[200:203], v[108:111]
	ds_read_b128 v[200:203], v75 offset:2048
	s_add_u32 m0, s88, 32768
	s_nop 0
	global_load_lds_dwordx4 v68, s[86:87]
	s_waitcnt lgkmcnt(5)
	v_mfma_f32_16x16x32_bf16 v[48:51], v[140:143], v[176:179], v[48:51]
	v_mfma_f32_16x16x32_bf16 v[0:3], v[144:147], v[176:179], v[0:3]
	v_mfma_f32_16x16x32_bf16 v[240:243], v[148:151], v[176:179], v[240:243]
	v_mfma_f32_16x16x32_bf16 v[112:115], v[204:207], v[176:179], v[112:115]
	ds_read_b128 v[176:179], v75 offset:4096
	s_add_u32 m0, s88, 36864
	s_nop 0
	global_load_lds_dwordx4 v69, s[86:87]
	s_waitcnt lgkmcnt(5)
	v_mfma_f32_16x16x32_bf16 v[52:55], v[140:143], v[180:183], v[52:55]
	v_mfma_f32_16x16x32_bf16 v[8:11], v[144:147], v[180:183], v[8:11]
	v_mfma_f32_16x16x32_bf16 v[248:251], v[148:151], v[180:183], v[248:251]
	v_mfma_f32_16x16x32_bf16 v[116:119], v[204:207], v[180:183], v[116:119]
	ds_read_b128 v[180:183], v75 offset:6144
	s_add_u32 m0, s88, 40960
	s_nop 0
	global_load_lds_dwordx4 v71, s[86:87]
	s_waitcnt lgkmcnt(5)
	v_mfma_f32_16x16x32_bf16 v[56:59], v[140:143], v[184:187], v[56:59]
	v_mfma_f32_16x16x32_bf16 v[24:27], v[144:147], v[184:187], v[24:27]
	v_mfma_f32_16x16x32_bf16 v[252:255], v[148:151], v[184:187], v[252:255]
	v_mfma_f32_16x16x32_bf16 v[120:123], v[204:207], v[184:187], v[120:123]
	ds_read_b128 v[184:187], v75 offset:8192
	s_add_u32 m0, s88, 45056
	s_nop 0
	global_load_lds_dwordx4 v74, s[86:87]
	s_add_u32 s86, s86, 128
	s_addc_u32 s87, s87, 0
	s_waitcnt lgkmcnt(5)
	v_mfma_f32_16x16x32_bf16 v[60:63], v[140:143], v[192:195], v[60:63]
	v_mfma_f32_16x16x32_bf16 v[28:31], v[144:147], v[192:195], v[28:31]
	v_mfma_f32_16x16x32_bf16 v[92:95], v[148:151], v[192:195], v[92:95]
	v_mfma_f32_16x16x32_bf16 v[124:127], v[204:207], v[192:195], v[124:127]
	s_waitcnt vmcnt(8)
	ds_read_b128 v[192:195], v75 offset:10240
	global_load_dwordx4 v[140:143], v66, s[84:85] offset:0
	s_waitcnt lgkmcnt(5)
	v_mfma_f32_16x16x32_bf16 v[32:35], v[160:163], v[196:199], v[32:35]
	v_mfma_f32_16x16x32_bf16 v[4:7], v[164:167], v[196:199], v[4:7]
	v_mfma_f32_16x16x32_bf16 v[188:191], v[168:171], v[196:199], v[188:191]
	v_mfma_f32_16x16x32_bf16 v[96:99], v[172:175], v[196:199], v[96:99]
	ds_read_b128 v[196:199], v75 offset:12288
	global_load_dwordx4 v[144:147], v67, s[84:85] offset:0
	s_waitcnt lgkmcnt(5)
	v_mfma_f32_16x16x32_bf16 v[36:39], v[160:163], v[200:203], v[36:39]
	v_mfma_f32_16x16x32_bf16 v[12:15], v[164:167], v[200:203], v[12:15]
	v_mfma_f32_16x16x32_bf16 v[208:211], v[168:171], v[200:203], v[208:211]
	v_mfma_f32_16x16x32_bf16 v[100:103], v[172:175], v[200:203], v[100:103]
	ds_read_b128 v[200:203], v75 offset:14336
	global_load_dwordx4 v[148:151], v66, s[92:93] offset:0
	s_waitcnt lgkmcnt(5)
	v_mfma_f32_16x16x32_bf16 v[40:43], v[160:163], v[176:179], v[40:43]
	v_mfma_f32_16x16x32_bf16 v[16:19], v[164:167], v[176:179], v[16:19]
	v_mfma_f32_16x16x32_bf16 v[232:235], v[168:171], v[176:179], v[232:235]
	v_mfma_f32_16x16x32_bf16 v[104:107], v[172:175], v[176:179], v[104:107]
	ds_read_b128 v[176:179], v212 offset:0
	global_load_dwordx4 v[204:207], v67, s[92:93] offset:0
	s_waitcnt lgkmcnt(5)
	v_mfma_f32_16x16x32_bf16 v[44:47], v[160:163], v[180:183], v[44:47]
	v_mfma_f32_16x16x32_bf16 v[20:23], v[164:167], v[180:183], v[20:23]
	v_mfma_f32_16x16x32_bf16 v[236:239], v[168:171], v[180:183], v[236:239]
	v_mfma_f32_16x16x32_bf16 v[108:111], v[172:175], v[180:183], v[108:111]
	ds_read_b128 v[180:183], v212 offset:2048
	s_waitcnt lgkmcnt(5)
	v_mfma_f32_16x16x32_bf16 v[48:51], v[160:163], v[184:187], v[48:51]
	v_mfma_f32_16x16x32_bf16 v[0:3], v[164:167], v[184:187], v[0:3]
	v_mfma_f32_16x16x32_bf16 v[240:243], v[168:171], v[184:187], v[240:243]
	v_mfma_f32_16x16x32_bf16 v[112:115], v[172:175], v[184:187], v[112:115]
	ds_read_b128 v[184:187], v212 offset:4096
	s_waitcnt lgkmcnt(5)
	v_mfma_f32_16x16x32_bf16 v[52:55], v[160:163], v[192:195], v[52:55]
	v_mfma_f32_16x16x32_bf16 v[8:11], v[164:167], v[192:195], v[8:11]
	v_mfma_f32_16x16x32_bf16 v[248:251], v[168:171], v[192:195], v[248:251]
	v_mfma_f32_16x16x32_bf16 v[116:119], v[172:175], v[192:195], v[116:119]
	ds_read_b128 v[192:195], v212 offset:6144
	s_waitcnt lgkmcnt(5)
	v_mfma_f32_16x16x32_bf16 v[56:59], v[160:163], v[196:199], v[56:59]
	v_mfma_f32_16x16x32_bf16 v[24:27], v[164:167], v[196:199], v[24:27]
	v_mfma_f32_16x16x32_bf16 v[252:255], v[168:171], v[196:199], v[252:255]
	v_mfma_f32_16x16x32_bf16 v[120:123], v[172:175], v[196:199], v[120:123]
	ds_read_b128 v[196:199], v212 offset:8192
	s_waitcnt lgkmcnt(5)
	v_mfma_f32_16x16x32_bf16 v[60:63], v[160:163], v[200:203], v[60:63]
	v_mfma_f32_16x16x32_bf16 v[28:31], v[164:167], v[200:203], v[28:31]
	v_mfma_f32_16x16x32_bf16 v[92:95], v[168:171], v[200:203], v[92:95]
	v_mfma_f32_16x16x32_bf16 v[124:127], v[172:175], v[200:203], v[124:127]
	s_waitcnt vmcnt(16)
	s_barrier
	s_waitcnt vmcnt(8)
	ds_read_b128 v[200:203], v212 offset:10240
	global_load_dwordx4 v[160:163], v66, s[84:85] offset:1024
	s_waitcnt lgkmcnt(5)
	v_mfma_f32_16x16x32_bf16 v[32:35], v[76:79], v[176:179], v[32:35]
	v_mfma_f32_16x16x32_bf16 v[4:7], v[80:83], v[176:179], v[4:7]
	v_mfma_f32_16x16x32_bf16 v[188:191], v[84:87], v[176:179], v[188:191]
	v_mfma_f32_16x16x32_bf16 v[96:99], v[88:91], v[176:179], v[96:99]
	ds_read_b128 v[176:179], v212 offset:12288
	global_load_dwordx4 v[164:167], v67, s[84:85] offset:1024
	s_waitcnt lgkmcnt(5)
	v_mfma_f32_16x16x32_bf16 v[36:39], v[76:79], v[180:183], v[36:39]
	v_mfma_f32_16x16x32_bf16 v[12:15], v[80:83], v[180:183], v[12:15]
	v_mfma_f32_16x16x32_bf16 v[208:211], v[84:87], v[180:183], v[208:211]
	v_mfma_f32_16x16x32_bf16 v[100:103], v[88:91], v[180:183], v[100:103]
	ds_read_b128 v[180:183], v212 offset:14336
	global_load_dwordx4 v[168:171], v66, s[92:93] offset:1024
	s_waitcnt lgkmcnt(5)
	v_mfma_f32_16x16x32_bf16 v[40:43], v[76:79], v[184:187], v[40:43]
	v_mfma_f32_16x16x32_bf16 v[16:19], v[80:83], v[184:187], v[16:19]
	v_mfma_f32_16x16x32_bf16 v[232:235], v[84:87], v[184:187], v[232:235]
	v_mfma_f32_16x16x32_bf16 v[104:107], v[88:91], v[184:187], v[104:107]
	ds_read_b128 v[184:187], v75 offset:16384
	global_load_dwordx4 v[172:175], v67, s[92:93] offset:1024
	s_add_u32 s84, s84, 0x800
	s_addc_u32 s85, s85, 0
	s_add_u32 s92, s92, 0x800
	s_addc_u32 s93, s93, 0
	s_waitcnt lgkmcnt(5)
	v_mfma_f32_16x16x32_bf16 v[44:47], v[76:79], v[192:195], v[44:47]
	v_mfma_f32_16x16x32_bf16 v[20:23], v[80:83], v[192:195], v[20:23]
	v_mfma_f32_16x16x32_bf16 v[236:239], v[84:87], v[192:195], v[236:239]
	v_mfma_f32_16x16x32_bf16 v[108:111], v[88:91], v[192:195], v[108:111]
	ds_read_b128 v[192:195], v75 offset:18432
	s_add_u32 m0, s88, 49152
	s_nop 0
	global_load_lds_dwordx4 v68, s[86:87]
	s_waitcnt lgkmcnt(5)
	v_mfma_f32_16x16x32_bf16 v[48:51], v[76:79], v[196:199], v[48:51]
	v_mfma_f32_16x16x32_bf16 v[0:3], v[80:83], v[196:199], v[0:3]
	v_mfma_f32_16x16x32_bf16 v[240:243], v[84:87], v[196:199], v[240:243]
	v_mfma_f32_16x16x32_bf16 v[112:115], v[88:91], v[196:199], v[112:115]
	ds_read_b128 v[196:199], v75 offset:20480
	s_add_u32 m0, s88, 53248
	s_nop 0
	global_load_lds_dwordx4 v69, s[86:87]
	s_waitcnt lgkmcnt(5)
	v_mfma_f32_16x16x32_bf16 v[52:55], v[76:79], v[200:203], v[52:55]
	v_mfma_f32_16x16x32_bf16 v[8:11], v[80:83], v[200:203], v[8:11]
	v_mfma_f32_16x16x32_bf16 v[248:251], v[84:87], v[200:203], v[248:251]
	v_mfma_f32_16x16x32_bf16 v[116:119], v[88:91], v[200:203], v[116:119]
	ds_read_b128 v[200:203], v75 offset:22528
	s_add_u32 m0, s88, 57344
	s_nop 0
	global_load_lds_dwordx4 v71, s[86:87]
	s_waitcnt lgkmcnt(5)
	v_mfma_f32_16x16x32_bf16 v[56:59], v[76:79], v[176:179], v[56:59]
	v_mfma_f32_16x16x32_bf16 v[24:27], v[80:83], v[176:179], v[24:27]
	v_mfma_f32_16x16x32_bf16 v[252:255], v[84:87], v[176:179], v[252:255]
	v_mfma_f32_16x16x32_bf16 v[120:123], v[88:91], v[176:179], v[120:123]
	ds_read_b128 v[176:179], v75 offset:24576
	s_add_u32 m0, s88, 61440
	s_nop 0
	global_load_lds_dwordx4 v74, s[86:87]
	s_add_u32 s86, s86, 128
	s_addc_u32 s87, s87, 0
	s_waitcnt lgkmcnt(5)
	v_mfma_f32_16x16x32_bf16 v[60:63], v[76:79], v[180:183], v[60:63]
	v_mfma_f32_16x16x32_bf16 v[28:31], v[80:83], v[180:183], v[28:31]
	v_mfma_f32_16x16x32_bf16 v[92:95], v[84:87], v[180:183], v[92:95]
	v_mfma_f32_16x16x32_bf16 v[124:127], v[88:91], v[180:183], v[124:127]
	s_waitcnt vmcnt(8)
	ds_read_b128 v[180:183], v75 offset:26624
	global_load_dwordx4 v[76:79], v66, s[84:85] offset:0
	s_waitcnt lgkmcnt(5)
	v_mfma_f32_16x16x32_bf16 v[32:35], v[140:143], v[184:187], v[32:35]
	v_mfma_f32_16x16x32_bf16 v[4:7], v[144:147], v[184:187], v[4:7]
	v_mfma_f32_16x16x32_bf16 v[188:191], v[148:151], v[184:187], v[188:191]
	v_mfma_f32_16x16x32_bf16 v[96:99], v[204:207], v[184:187], v[96:99]
	ds_read_b128 v[184:187], v75 offset:28672
	global_load_dwordx4 v[80:83], v67, s[84:85] offset:0
	s_waitcnt lgkmcnt(5)
	v_mfma_f32_16x16x32_bf16 v[36:39], v[140:143], v[192:195], v[36:39]
	v_mfma_f32_16x16x32_bf16 v[12:15], v[144:147], v[192:195], v[12:15]
	v_mfma_f32_16x16x32_bf16 v[208:211], v[148:151], v[192:195], v[208:211]
	v_mfma_f32_16x16x32_bf16 v[100:103], v[204:207], v[192:195], v[100:103]
	ds_read_b128 v[192:195], v75 offset:30720
	global_load_dwordx4 v[84:87], v66, s[92:93] offset:0
	s_waitcnt lgkmcnt(5)
	v_mfma_f32_16x16x32_bf16 v[40:43], v[140:143], v[196:199], v[40:43]
	v_mfma_f32_16x16x32_bf16 v[16:19], v[144:147], v[196:199], v[16:19]
	v_mfma_f32_16x16x32_bf16 v[232:235], v[148:151], v[196:199], v[232:235]
	v_mfma_f32_16x16x32_bf16 v[104:107], v[204:207], v[196:199], v[104:107]
	ds_read_b128 v[196:199], v212 offset:16384
	global_load_dwordx4 v[88:91], v67, s[92:93] offset:0
	s_waitcnt lgkmcnt(5)
	v_mfma_f32_16x16x32_bf16 v[44:47], v[140:143], v[200:203], v[44:47]
	v_mfma_f32_16x16x32_bf16 v[20:23], v[144:147], v[200:203], v[20:23]
	v_mfma_f32_16x16x32_bf16 v[236:239], v[148:151], v[200:203], v[236:239]
	v_mfma_f32_16x16x32_bf16 v[108:111], v[204:207], v[200:203], v[108:111]
	ds_read_b128 v[200:203], v212 offset:18432
	s_waitcnt lgkmcnt(5)
	v_mfma_f32_16x16x32_bf16 v[48:51], v[140:143], v[176:179], v[48:51]
	v_mfma_f32_16x16x32_bf16 v[0:3], v[144:147], v[176:179], v[0:3]
	v_mfma_f32_16x16x32_bf16 v[240:243], v[148:151], v[176:179], v[240:243]
	v_mfma_f32_16x16x32_bf16 v[112:115], v[204:207], v[176:179], v[112:115]
	ds_read_b128 v[176:179], v212 offset:20480
	s_waitcnt lgkmcnt(5)
	v_mfma_f32_16x16x32_bf16 v[52:55], v[140:143], v[180:183], v[52:55]
	v_mfma_f32_16x16x32_bf16 v[8:11], v[144:147], v[180:183], v[8:11]
	v_mfma_f32_16x16x32_bf16 v[248:251], v[148:151], v[180:183], v[248:251]
	v_mfma_f32_16x16x32_bf16 v[116:119], v[204:207], v[180:183], v[116:119]
	ds_read_b128 v[180:183], v212 offset:22528
	s_waitcnt lgkmcnt(5)
	v_mfma_f32_16x16x32_bf16 v[56:59], v[140:143], v[184:187], v[56:59]
	v_mfma_f32_16x16x32_bf16 v[24:27], v[144:147], v[184:187], v[24:27]
	v_mfma_f32_16x16x32_bf16 v[252:255], v[148:151], v[184:187], v[252:255]
	v_mfma_f32_16x16x32_bf16 v[120:123], v[204:207], v[184:187], v[120:123]
	ds_read_b128 v[184:187], v212 offset:24576
	s_waitcnt lgkmcnt(5)
	v_mfma_f32_16x16x32_bf16 v[60:63], v[140:143], v[192:195], v[60:63]
	v_mfma_f32_16x16x32_bf16 v[28:31], v[144:147], v[192:195], v[28:31]
	v_mfma_f32_16x16x32_bf16 v[92:95], v[148:151], v[192:195], v[92:95]
	v_mfma_f32_16x16x32_bf16 v[124:127], v[204:207], v[192:195], v[124:127]
	s_waitcnt vmcnt(16)
	s_barrier
	s_waitcnt vmcnt(8)
	ds_read_b128 v[192:195], v212 offset:26624
	global_load_dwordx4 v[140:143], v66, s[84:85] offset:1024
	s_waitcnt lgkmcnt(5)
	v_mfma_f32_16x16x32_bf16 v[32:35], v[160:163], v[196:199], v[32:35]
	v_mfma_f32_16x16x32_bf16 v[4:7], v[164:167], v[196:199], v[4:7]
	v_mfma_f32_16x16x32_bf16 v[188:191], v[168:171], v[196:199], v[188:191]
	v_mfma_f32_16x16x32_bf16 v[96:99], v[172:175], v[196:199], v[96:99]
	ds_read_b128 v[196:199], v212 offset:28672
	global_load_dwordx4 v[144:147], v67, s[84:85] offset:1024
	s_waitcnt lgkmcnt(5)
	v_mfma_f32_16x16x32_bf16 v[36:39], v[160:163], v[200:203], v[36:39]
	v_mfma_f32_16x16x32_bf16 v[12:15], v[164:167], v[200:203], v[12:15]
	v_mfma_f32_16x16x32_bf16 v[208:211], v[168:171], v[200:203], v[208:211]
	v_mfma_f32_16x16x32_bf16 v[100:103], v[172:175], v[200:203], v[100:103]
	ds_read_b128 v[200:203], v212 offset:30720
	global_load_dwordx4 v[148:151], v66, s[92:93] offset:1024
	s_waitcnt lgkmcnt(5)
	v_mfma_f32_16x16x32_bf16 v[40:43], v[160:163], v[176:179], v[40:43]
	v_mfma_f32_16x16x32_bf16 v[16:19], v[164:167], v[176:179], v[16:19]
	v_mfma_f32_16x16x32_bf16 v[232:235], v[168:171], v[176:179], v[232:235]
	v_mfma_f32_16x16x32_bf16 v[104:107], v[172:175], v[176:179], v[104:107]
	ds_read_b128 v[176:179], v75 offset:32768
	global_load_dwordx4 v[204:207], v67, s[92:93] offset:1024
	s_add_u32 s84, s84, 0x800
	s_addc_u32 s85, s85, 0
	s_add_u32 s92, s92, 0x800
	s_addc_u32 s93, s93, 0
	s_waitcnt lgkmcnt(5)
	v_mfma_f32_16x16x32_bf16 v[44:47], v[160:163], v[180:183], v[44:47]
	v_mfma_f32_16x16x32_bf16 v[20:23], v[164:167], v[180:183], v[20:23]
	v_mfma_f32_16x16x32_bf16 v[236:239], v[168:171], v[180:183], v[236:239]
	v_mfma_f32_16x16x32_bf16 v[108:111], v[172:175], v[180:183], v[108:111]
	ds_read_b128 v[180:183], v75 offset:34816
	s_add_u32 m0, s88, 0
	s_nop 0
	global_load_lds_dwordx4 v68, s[86:87]
	s_waitcnt lgkmcnt(5)
	v_mfma_f32_16x16x32_bf16 v[48:51], v[160:163], v[184:187], v[48:51]
	v_mfma_f32_16x16x32_bf16 v[0:3], v[164:167], v[184:187], v[0:3]
	v_mfma_f32_16x16x32_bf16 v[240:243], v[168:171], v[184:187], v[240:243]
	v_mfma_f32_16x16x32_bf16 v[112:115], v[172:175], v[184:187], v[112:115]
	ds_read_b128 v[184:187], v75 offset:36864
	s_add_u32 m0, s88, 4096
	s_nop 0
	global_load_lds_dwordx4 v69, s[86:87]
	s_waitcnt lgkmcnt(5)
	v_mfma_f32_16x16x32_bf16 v[52:55], v[160:163], v[192:195], v[52:55]
	v_mfma_f32_16x16x32_bf16 v[8:11], v[164:167], v[192:195], v[8:11]
	v_mfma_f32_16x16x32_bf16 v[248:251], v[168:171], v[192:195], v[248:251]
	v_mfma_f32_16x16x32_bf16 v[116:119], v[172:175], v[192:195], v[116:119]
	ds_read_b128 v[192:195], v75 offset:38912
	s_add_u32 m0, s88, 8192
	s_nop 0
	global_load_lds_dwordx4 v71, s[86:87]
	s_waitcnt lgkmcnt(5)
	v_mfma_f32_16x16x32_bf16 v[56:59], v[160:163], v[196:199], v[56:59]
	v_mfma_f32_16x16x32_bf16 v[24:27], v[164:167], v[196:199], v[24:27]
	v_mfma_f32_16x16x32_bf16 v[252:255], v[168:171], v[196:199], v[252:255]
	v_mfma_f32_16x16x32_bf16 v[120:123], v[172:175], v[196:199], v[120:123]
	ds_read_b128 v[196:199], v75 offset:40960
	s_add_u32 m0, s88, 12288
	s_nop 0
	global_load_lds_dwordx4 v74, s[86:87]
	s_add_u32 s86, s86, 128
	s_addc_u32 s87, s87, 0
	s_waitcnt lgkmcnt(5)
	v_mfma_f32_16x16x32_bf16 v[60:63], v[160:163], v[200:203], v[60:63]
	v_mfma_f32_16x16x32_bf16 v[28:31], v[164:167], v[200:203], v[28:31]
	v_mfma_f32_16x16x32_bf16 v[92:95], v[168:171], v[200:203], v[92:95]
	v_mfma_f32_16x16x32_bf16 v[124:127], v[172:175], v[200:203], v[124:127]
	s_waitcnt vmcnt(8)
	ds_read_b128 v[200:203], v75 offset:43008
	global_load_dwordx4 v[160:163], v66, s[84:85] offset:0
	s_waitcnt lgkmcnt(5)
	v_mfma_f32_16x16x32_bf16 v[32:35], v[76:79], v[176:179], v[32:35]
	v_mfma_f32_16x16x32_bf16 v[4:7], v[80:83], v[176:179], v[4:7]
	v_mfma_f32_16x16x32_bf16 v[188:191], v[84:87], v[176:179], v[188:191]
	v_mfma_f32_16x16x32_bf16 v[96:99], v[88:91], v[176:179], v[96:99]
	ds_read_b128 v[176:179], v75 offset:45056
	global_load_dwordx4 v[164:167], v67, s[84:85] offset:0
	s_waitcnt lgkmcnt(5)
	v_mfma_f32_16x16x32_bf16 v[36:39], v[76:79], v[180:183], v[36:39]
	v_mfma_f32_16x16x32_bf16 v[12:15], v[80:83], v[180:183], v[12:15]
	v_mfma_f32_16x16x32_bf16 v[208:211], v[84:87], v[180:183], v[208:211]
	v_mfma_f32_16x16x32_bf16 v[100:103], v[88:91], v[180:183], v[100:103]
	ds_read_b128 v[180:183], v75 offset:47104
	global_load_dwordx4 v[168:171], v66, s[92:93] offset:0
	s_waitcnt lgkmcnt(5)
	v_mfma_f32_16x16x32_bf16 v[40:43], v[76:79], v[184:187], v[40:43]
	v_mfma_f32_16x16x32_bf16 v[16:19], v[80:83], v[184:187], v[16:19]
	v_mfma_f32_16x16x32_bf16 v[232:235], v[84:87], v[184:187], v[232:235]
	v_mfma_f32_16x16x32_bf16 v[104:107], v[88:91], v[184:187], v[104:107]
	ds_read_b128 v[184:187], v212 offset:32768
	global_load_dwordx4 v[172:175], v67, s[92:93] offset:0
	s_waitcnt lgkmcnt(5)
	v_mfma_f32_16x16x32_bf16 v[44:47], v[76:79], v[192:195], v[44:47]
	v_mfma_f32_16x16x32_bf16 v[20:23], v[80:83], v[192:195], v[20:23]
	v_mfma_f32_16x16x32_bf16 v[236:239], v[84:87], v[192:195], v[236:239]
	v_mfma_f32_16x16x32_bf16 v[108:111], v[88:91], v[192:195], v[108:111]
	ds_read_b128 v[192:195], v212 offset:34816
	s_waitcnt lgkmcnt(5)
	v_mfma_f32_16x16x32_bf16 v[48:51], v[76:79], v[196:199], v[48:51]
	v_mfma_f32_16x16x32_bf16 v[0:3], v[80:83], v[196:199], v[0:3]
	v_mfma_f32_16x16x32_bf16 v[240:243], v[84:87], v[196:199], v[240:243]
	v_mfma_f32_16x16x32_bf16 v[112:115], v[88:91], v[196:199], v[112:115]
	ds_read_b128 v[196:199], v212 offset:36864
	s_waitcnt lgkmcnt(5)
	v_mfma_f32_16x16x32_bf16 v[52:55], v[76:79], v[200:203], v[52:55]
	v_mfma_f32_16x16x32_bf16 v[8:11], v[80:83], v[200:203], v[8:11]
	v_mfma_f32_16x16x32_bf16 v[248:251], v[84:87], v[200:203], v[248:251]
	v_mfma_f32_16x16x32_bf16 v[116:119], v[88:91], v[200:203], v[116:119]
	ds_read_b128 v[200:203], v212 offset:38912
	s_waitcnt lgkmcnt(5)
	v_mfma_f32_16x16x32_bf16 v[56:59], v[76:79], v[176:179], v[56:59]
	v_mfma_f32_16x16x32_bf16 v[24:27], v[80:83], v[176:179], v[24:27]
	v_mfma_f32_16x16x32_bf16 v[252:255], v[84:87], v[176:179], v[252:255]
	v_mfma_f32_16x16x32_bf16 v[120:123], v[88:91], v[176:179], v[120:123]
	ds_read_b128 v[176:179], v212 offset:40960
	s_waitcnt lgkmcnt(5)
	v_mfma_f32_16x16x32_bf16 v[60:63], v[76:79], v[180:183], v[60:63]
	v_mfma_f32_16x16x32_bf16 v[28:31], v[80:83], v[180:183], v[28:31]
	v_mfma_f32_16x16x32_bf16 v[92:95], v[84:87], v[180:183], v[92:95]
	v_mfma_f32_16x16x32_bf16 v[124:127], v[88:91], v[180:183], v[124:127]
	s_waitcnt vmcnt(16)
	s_barrier
	s_waitcnt vmcnt(8)
	ds_read_b128 v[180:183], v212 offset:43008
	global_load_dwordx4 v[76:79], v66, s[84:85] offset:1024
	s_waitcnt lgkmcnt(5)
	v_mfma_f32_16x16x32_bf16 v[32:35], v[140:143], v[184:187], v[32:35]
	v_mfma_f32_16x16x32_bf16 v[4:7], v[144:147], v[184:187], v[4:7]
	v_mfma_f32_16x16x32_bf16 v[188:191], v[148:151], v[184:187], v[188:191]
	v_mfma_f32_16x16x32_bf16 v[96:99], v[204:207], v[184:187], v[96:99]
	ds_read_b128 v[184:187], v212 offset:45056
	global_load_dwordx4 v[80:83], v67, s[84:85] offset:1024
	s_waitcnt lgkmcnt(5)
	v_mfma_f32_16x16x32_bf16 v[36:39], v[140:143], v[192:195], v[36:39]
	v_mfma_f32_16x16x32_bf16 v[12:15], v[144:147], v[192:195], v[12:15]
	v_mfma_f32_16x16x32_bf16 v[208:211], v[148:151], v[192:195], v[208:211]
	v_mfma_f32_16x16x32_bf16 v[100:103], v[204:207], v[192:195], v[100:103]
	ds_read_b128 v[192:195], v212 offset:47104
	global_load_dwordx4 v[84:87], v66, s[92:93] offset:1024
	s_waitcnt lgkmcnt(5)
	v_mfma_f32_16x16x32_bf16 v[40:43], v[140:143], v[196:199], v[40:43]
	v_mfma_f32_16x16x32_bf16 v[16:19], v[144:147], v[196:199], v[16:19]
	v_mfma_f32_16x16x32_bf16 v[232:235], v[148:151], v[196:199], v[232:235]
	v_mfma_f32_16x16x32_bf16 v[104:107], v[204:207], v[196:199], v[104:107]
	ds_read_b128 v[196:199], v75 offset:49152
	global_load_dwordx4 v[88:91], v67, s[92:93] offset:1024
	s_add_u32 s84, s84, 0x800
	s_addc_u32 s85, s85, 0
	s_add_u32 s92, s92, 0x800
	s_addc_u32 s93, s93, 0
	s_waitcnt lgkmcnt(5)
	v_mfma_f32_16x16x32_bf16 v[44:47], v[140:143], v[200:203], v[44:47]
	v_mfma_f32_16x16x32_bf16 v[20:23], v[144:147], v[200:203], v[20:23]
	v_mfma_f32_16x16x32_bf16 v[236:239], v[148:151], v[200:203], v[236:239]
	v_mfma_f32_16x16x32_bf16 v[108:111], v[204:207], v[200:203], v[108:111]
	ds_read_b128 v[200:203], v75 offset:51200
	s_add_u32 m0, s88, 16384
	s_nop 0
	global_load_lds_dwordx4 v68, s[86:87]
	s_waitcnt lgkmcnt(5)
	v_mfma_f32_16x16x32_bf16 v[48:51], v[140:143], v[176:179], v[48:51]
	v_mfma_f32_16x16x32_bf16 v[0:3], v[144:147], v[176:179], v[0:3]
	v_mfma_f32_16x16x32_bf16 v[240:243], v[148:151], v[176:179], v[240:243]
	v_mfma_f32_16x16x32_bf16 v[112:115], v[204:207], v[176:179], v[112:115]
	ds_read_b128 v[176:179], v75 offset:53248
	s_add_u32 m0, s88, 20480
	s_nop 0
	global_load_lds_dwordx4 v69, s[86:87]
	s_waitcnt lgkmcnt(5)
	v_mfma_f32_16x16x32_bf16 v[52:55], v[140:143], v[180:183], v[52:55]
	v_mfma_f32_16x16x32_bf16 v[8:11], v[144:147], v[180:183], v[8:11]
	v_mfma_f32_16x16x32_bf16 v[248:251], v[148:151], v[180:183], v[248:251]
	v_mfma_f32_16x16x32_bf16 v[116:119], v[204:207], v[180:183], v[116:119]
	ds_read_b128 v[180:183], v75 offset:55296
	s_add_u32 m0, s88, 24576
	s_nop 0
	global_load_lds_dwordx4 v71, s[86:87]
	s_waitcnt lgkmcnt(5)
	v_mfma_f32_16x16x32_bf16 v[56:59], v[140:143], v[184:187], v[56:59]
	v_mfma_f32_16x16x32_bf16 v[24:27], v[144:147], v[184:187], v[24:27]
	v_mfma_f32_16x16x32_bf16 v[252:255], v[148:151], v[184:187], v[252:255]
	v_mfma_f32_16x16x32_bf16 v[120:123], v[204:207], v[184:187], v[120:123]
	ds_read_b128 v[184:187], v75 offset:57344
	s_add_u32 m0, s88, 28672
	s_nop 0
	global_load_lds_dwordx4 v74, s[86:87]
	s_add_u32 s86, s86, 128
	s_addc_u32 s87, s87, 0
	s_waitcnt lgkmcnt(5)
	v_mfma_f32_16x16x32_bf16 v[60:63], v[140:143], v[192:195], v[60:63]
	v_mfma_f32_16x16x32_bf16 v[28:31], v[144:147], v[192:195], v[28:31]
	v_mfma_f32_16x16x32_bf16 v[92:95], v[148:151], v[192:195], v[92:95]
	v_mfma_f32_16x16x32_bf16 v[124:127], v[204:207], v[192:195], v[124:127]
	s_waitcnt vmcnt(8)
	ds_read_b128 v[192:195], v75 offset:59392
	global_load_dwordx4 v[140:143], v66, s[84:85] offset:0
	s_waitcnt lgkmcnt(5)
	v_mfma_f32_16x16x32_bf16 v[32:35], v[160:163], v[196:199], v[32:35]
	v_mfma_f32_16x16x32_bf16 v[4:7], v[164:167], v[196:199], v[4:7]
	v_mfma_f32_16x16x32_bf16 v[188:191], v[168:171], v[196:199], v[188:191]
	v_mfma_f32_16x16x32_bf16 v[96:99], v[172:175], v[196:199], v[96:99]
	ds_read_b128 v[196:199], v75 offset:61440
	global_load_dwordx4 v[144:147], v67, s[84:85] offset:0
	s_waitcnt lgkmcnt(5)
	v_mfma_f32_16x16x32_bf16 v[36:39], v[160:163], v[200:203], v[36:39]
	v_mfma_f32_16x16x32_bf16 v[12:15], v[164:167], v[200:203], v[12:15]
	v_mfma_f32_16x16x32_bf16 v[208:211], v[168:171], v[200:203], v[208:211]
	v_mfma_f32_16x16x32_bf16 v[100:103], v[172:175], v[200:203], v[100:103]
	ds_read_b128 v[200:203], v75 offset:63488
	global_load_dwordx4 v[148:151], v66, s[92:93] offset:0
	s_waitcnt lgkmcnt(5)
	v_mfma_f32_16x16x32_bf16 v[40:43], v[160:163], v[176:179], v[40:43]
	v_mfma_f32_16x16x32_bf16 v[16:19], v[164:167], v[176:179], v[16:19]
	v_mfma_f32_16x16x32_bf16 v[232:235], v[168:171], v[176:179], v[232:235]
	v_mfma_f32_16x16x32_bf16 v[104:107], v[172:175], v[176:179], v[104:107]
	ds_read_b128 v[176:179], v212 offset:49152
	global_load_dwordx4 v[204:207], v67, s[92:93] offset:0
	s_waitcnt lgkmcnt(5)
	v_mfma_f32_16x16x32_bf16 v[44:47], v[160:163], v[180:183], v[44:47]
	v_mfma_f32_16x16x32_bf16 v[20:23], v[164:167], v[180:183], v[20:23]
	v_mfma_f32_16x16x32_bf16 v[236:239], v[168:171], v[180:183], v[236:239]
	v_mfma_f32_16x16x32_bf16 v[108:111], v[172:175], v[180:183], v[108:111]
	ds_read_b128 v[180:183], v212 offset:51200
	s_waitcnt lgkmcnt(5)
	v_mfma_f32_16x16x32_bf16 v[48:51], v[160:163], v[184:187], v[48:51]
	v_mfma_f32_16x16x32_bf16 v[0:3], v[164:167], v[184:187], v[0:3]
	v_mfma_f32_16x16x32_bf16 v[240:243], v[168:171], v[184:187], v[240:243]
	v_mfma_f32_16x16x32_bf16 v[112:115], v[172:175], v[184:187], v[112:115]
	ds_read_b128 v[184:187], v212 offset:53248
	s_waitcnt lgkmcnt(5)
	v_mfma_f32_16x16x32_bf16 v[52:55], v[160:163], v[192:195], v[52:55]
	v_mfma_f32_16x16x32_bf16 v[8:11], v[164:167], v[192:195], v[8:11]
	v_mfma_f32_16x16x32_bf16 v[248:251], v[168:171], v[192:195], v[248:251]
	v_mfma_f32_16x16x32_bf16 v[116:119], v[172:175], v[192:195], v[116:119]
	ds_read_b128 v[192:195], v212 offset:55296
	s_waitcnt lgkmcnt(5)
	v_mfma_f32_16x16x32_bf16 v[56:59], v[160:163], v[196:199], v[56:59]
	v_mfma_f32_16x16x32_bf16 v[24:27], v[164:167], v[196:199], v[24:27]
	v_mfma_f32_16x16x32_bf16 v[252:255], v[168:171], v[196:199], v[252:255]
	v_mfma_f32_16x16x32_bf16 v[120:123], v[172:175], v[196:199], v[120:123]
	ds_read_b128 v[196:199], v212 offset:57344
	s_waitcnt lgkmcnt(5)
	v_mfma_f32_16x16x32_bf16 v[60:63], v[160:163], v[200:203], v[60:63]
	v_mfma_f32_16x16x32_bf16 v[28:31], v[164:167], v[200:203], v[28:31]
	v_mfma_f32_16x16x32_bf16 v[92:95], v[168:171], v[200:203], v[92:95]
	v_mfma_f32_16x16x32_bf16 v[124:127], v[172:175], v[200:203], v[124:127]
	s_waitcnt vmcnt(16)
	s_barrier
	s_waitcnt vmcnt(8)
	ds_read_b128 v[200:203], v212 offset:59392
	global_load_dwordx4 v[160:163], v66, s[84:85] offset:1024
	s_waitcnt lgkmcnt(5)
	v_mfma_f32_16x16x32_bf16 v[32:35], v[76:79], v[176:179], v[32:35]
	v_mfma_f32_16x16x32_bf16 v[4:7], v[80:83], v[176:179], v[4:7]
	v_mfma_f32_16x16x32_bf16 v[188:191], v[84:87], v[176:179], v[188:191]
	v_mfma_f32_16x16x32_bf16 v[96:99], v[88:91], v[176:179], v[96:99]
	ds_read_b128 v[176:179], v212 offset:61440
	global_load_dwordx4 v[164:167], v67, s[84:85] offset:1024
	s_waitcnt lgkmcnt(5)
	v_mfma_f32_16x16x32_bf16 v[36:39], v[76:79], v[180:183], v[36:39]
	v_mfma_f32_16x16x32_bf16 v[12:15], v[80:83], v[180:183], v[12:15]
	v_mfma_f32_16x16x32_bf16 v[208:211], v[84:87], v[180:183], v[208:211]
	v_mfma_f32_16x16x32_bf16 v[100:103], v[88:91], v[180:183], v[100:103]
	ds_read_b128 v[180:183], v212 offset:63488
	global_load_dwordx4 v[168:171], v66, s[92:93] offset:1024
	s_waitcnt lgkmcnt(5)
	v_mfma_f32_16x16x32_bf16 v[40:43], v[76:79], v[184:187], v[40:43]
	v_mfma_f32_16x16x32_bf16 v[16:19], v[80:83], v[184:187], v[16:19]
	v_mfma_f32_16x16x32_bf16 v[232:235], v[84:87], v[184:187], v[232:235]
	v_mfma_f32_16x16x32_bf16 v[104:107], v[88:91], v[184:187], v[104:107]
	ds_read_b128 v[184:187], v75 offset:0
	global_load_dwordx4 v[172:175], v67, s[92:93] offset:1024
	s_add_u32 s84, s84, 0x800
	s_addc_u32 s85, s85, 0
	s_add_u32 s92, s92, 0x800
	s_addc_u32 s93, s93, 0
	s_waitcnt lgkmcnt(5)
	v_mfma_f32_16x16x32_bf16 v[44:47], v[76:79], v[192:195], v[44:47]
	v_mfma_f32_16x16x32_bf16 v[20:23], v[80:83], v[192:195], v[20:23]
	v_mfma_f32_16x16x32_bf16 v[236:239], v[84:87], v[192:195], v[236:239]
	v_mfma_f32_16x16x32_bf16 v[108:111], v[88:91], v[192:195], v[108:111]
	ds_read_b128 v[192:195], v75 offset:2048
	s_add_u32 m0, s88, 32768
	s_nop 0
	global_load_lds_dwordx4 v68, s[86:87]
	s_waitcnt lgkmcnt(5)
	v_mfma_f32_16x16x32_bf16 v[48:51], v[76:79], v[196:199], v[48:51]
	v_mfma_f32_16x16x32_bf16 v[0:3], v[80:83], v[196:199], v[0:3]
	v_mfma_f32_16x16x32_bf16 v[240:243], v[84:87], v[196:199], v[240:243]
	v_mfma_f32_16x16x32_bf16 v[112:115], v[88:91], v[196:199], v[112:115]
	ds_read_b128 v[196:199], v75 offset:4096
	s_add_u32 m0, s88, 36864
	s_nop 0
	global_load_lds_dwordx4 v69, s[86:87]
	s_waitcnt lgkmcnt(5)
	v_mfma_f32_16x16x32_bf16 v[52:55], v[76:79], v[200:203], v[52:55]
	v_mfma_f32_16x16x32_bf16 v[8:11], v[80:83], v[200:203], v[8:11]
	v_mfma_f32_16x16x32_bf16 v[248:251], v[84:87], v[200:203], v[248:251]
	v_mfma_f32_16x16x32_bf16 v[116:119], v[88:91], v[200:203], v[116:119]
	ds_read_b128 v[200:203], v75 offset:6144
	s_add_u32 m0, s88, 40960
	s_nop 0
	global_load_lds_dwordx4 v71, s[86:87]
	s_waitcnt lgkmcnt(5)
	v_mfma_f32_16x16x32_bf16 v[56:59], v[76:79], v[176:179], v[56:59]
	v_mfma_f32_16x16x32_bf16 v[24:27], v[80:83], v[176:179], v[24:27]
	v_mfma_f32_16x16x32_bf16 v[252:255], v[84:87], v[176:179], v[252:255]
	v_mfma_f32_16x16x32_bf16 v[120:123], v[88:91], v[176:179], v[120:123]
	ds_read_b128 v[176:179], v75 offset:8192
	s_add_u32 m0, s88, 45056
	s_nop 0
	global_load_lds_dwordx4 v74, s[86:87]
	s_add_u32 s86, s86, 128
	s_addc_u32 s87, s87, 0
	s_waitcnt lgkmcnt(5)
	v_mfma_f32_16x16x32_bf16 v[60:63], v[76:79], v[180:183], v[60:63]
	v_mfma_f32_16x16x32_bf16 v[28:31], v[80:83], v[180:183], v[28:31]
	v_mfma_f32_16x16x32_bf16 v[92:95], v[84:87], v[180:183], v[92:95]
	v_mfma_f32_16x16x32_bf16 v[124:127], v[88:91], v[180:183], v[124:127]
	s_waitcnt vmcnt(8)
	ds_read_b128 v[180:183], v75 offset:10240
	global_load_dwordx4 v[76:79], v66, s[84:85] offset:0
	s_waitcnt lgkmcnt(5)
	v_mfma_f32_16x16x32_bf16 v[32:35], v[140:143], v[184:187], v[32:35]
	v_mfma_f32_16x16x32_bf16 v[4:7], v[144:147], v[184:187], v[4:7]
	v_mfma_f32_16x16x32_bf16 v[188:191], v[148:151], v[184:187], v[188:191]
	v_mfma_f32_16x16x32_bf16 v[96:99], v[204:207], v[184:187], v[96:99]
	ds_read_b128 v[184:187], v75 offset:12288
	global_load_dwordx4 v[80:83], v67, s[84:85] offset:0
	s_waitcnt lgkmcnt(5)
	v_mfma_f32_16x16x32_bf16 v[36:39], v[140:143], v[192:195], v[36:39]
	v_mfma_f32_16x16x32_bf16 v[12:15], v[144:147], v[192:195], v[12:15]
	v_mfma_f32_16x16x32_bf16 v[208:211], v[148:151], v[192:195], v[208:211]
	v_mfma_f32_16x16x32_bf16 v[100:103], v[204:207], v[192:195], v[100:103]
	ds_read_b128 v[192:195], v75 offset:14336
	global_load_dwordx4 v[84:87], v66, s[92:93] offset:0
	s_waitcnt lgkmcnt(5)
	v_mfma_f32_16x16x32_bf16 v[40:43], v[140:143], v[196:199], v[40:43]
	v_mfma_f32_16x16x32_bf16 v[16:19], v[144:147], v[196:199], v[16:19]
	v_mfma_f32_16x16x32_bf16 v[232:235], v[148:151], v[196:199], v[232:235]
	v_mfma_f32_16x16x32_bf16 v[104:107], v[204:207], v[196:199], v[104:107]
	ds_read_b128 v[196:199], v212 offset:0
	global_load_dwordx4 v[88:91], v67, s[92:93] offset:0
	s_waitcnt lgkmcnt(5)
	v_mfma_f32_16x16x32_bf16 v[44:47], v[140:143], v[200:203], v[44:47]
	v_mfma_f32_16x16x32_bf16 v[20:23], v[144:147], v[200:203], v[20:23]
	v_mfma_f32_16x16x32_bf16 v[236:239], v[148:151], v[200:203], v[236:239]
	v_mfma_f32_16x16x32_bf16 v[108:111], v[204:207], v[200:203], v[108:111]
	ds_read_b128 v[200:203], v212 offset:2048
	s_waitcnt lgkmcnt(5)
	v_mfma_f32_16x16x32_bf16 v[48:51], v[140:143], v[176:179], v[48:51]
	v_mfma_f32_16x16x32_bf16 v[0:3], v[144:147], v[176:179], v[0:3]
	v_mfma_f32_16x16x32_bf16 v[240:243], v[148:151], v[176:179], v[240:243]
	v_mfma_f32_16x16x32_bf16 v[112:115], v[204:207], v[176:179], v[112:115]
	ds_read_b128 v[176:179], v212 offset:4096
	s_waitcnt lgkmcnt(5)
	v_mfma_f32_16x16x32_bf16 v[52:55], v[140:143], v[180:183], v[52:55]
	v_mfma_f32_16x16x32_bf16 v[8:11], v[144:147], v[180:183], v[8:11]
	v_mfma_f32_16x16x32_bf16 v[248:251], v[148:151], v[180:183], v[248:251]
	v_mfma_f32_16x16x32_bf16 v[116:119], v[204:207], v[180:183], v[116:119]
	ds_read_b128 v[180:183], v212 offset:6144
	s_waitcnt lgkmcnt(5)
	v_mfma_f32_16x16x32_bf16 v[56:59], v[140:143], v[184:187], v[56:59]
	v_mfma_f32_16x16x32_bf16 v[24:27], v[144:147], v[184:187], v[24:27]
	v_mfma_f32_16x16x32_bf16 v[252:255], v[148:151], v[184:187], v[252:255]
	v_mfma_f32_16x16x32_bf16 v[120:123], v[204:207], v[184:187], v[120:123]
	ds_read_b128 v[184:187], v212 offset:8192
	s_waitcnt lgkmcnt(5)
	v_mfma_f32_16x16x32_bf16 v[60:63], v[140:143], v[192:195], v[60:63]
	v_mfma_f32_16x16x32_bf16 v[28:31], v[144:147], v[192:195], v[28:31]
	v_mfma_f32_16x16x32_bf16 v[92:95], v[148:151], v[192:195], v[92:95]
	v_mfma_f32_16x16x32_bf16 v[124:127], v[204:207], v[192:195], v[124:127]
	s_waitcnt vmcnt(16)
	s_barrier
	s_waitcnt vmcnt(8)
	ds_read_b128 v[192:195], v212 offset:10240
	global_load_dwordx4 v[140:143], v66, s[84:85] offset:1024
	s_waitcnt lgkmcnt(5)
	v_mfma_f32_16x16x32_bf16 v[32:35], v[160:163], v[196:199], v[32:35]
	v_mfma_f32_16x16x32_bf16 v[4:7], v[164:167], v[196:199], v[4:7]
	v_mfma_f32_16x16x32_bf16 v[188:191], v[168:171], v[196:199], v[188:191]
	v_mfma_f32_16x16x32_bf16 v[96:99], v[172:175], v[196:199], v[96:99]
	ds_read_b128 v[196:199], v212 offset:12288
	global_load_dwordx4 v[144:147], v67, s[84:85] offset:1024
	s_waitcnt lgkmcnt(5)
	v_mfma_f32_16x16x32_bf16 v[36:39], v[160:163], v[200:203], v[36:39]
	v_mfma_f32_16x16x32_bf16 v[12:15], v[164:167], v[200:203], v[12:15]
	v_mfma_f32_16x16x32_bf16 v[208:211], v[168:171], v[200:203], v[208:211]
	v_mfma_f32_16x16x32_bf16 v[100:103], v[172:175], v[200:203], v[100:103]
	ds_read_b128 v[200:203], v212 offset:14336
	global_load_dwordx4 v[148:151], v66, s[92:93] offset:1024
	s_waitcnt lgkmcnt(5)
	v_mfma_f32_16x16x32_bf16 v[40:43], v[160:163], v[176:179], v[40:43]
	v_mfma_f32_16x16x32_bf16 v[16:19], v[164:167], v[176:179], v[16:19]
	v_mfma_f32_16x16x32_bf16 v[232:235], v[168:171], v[176:179], v[232:235]
	v_mfma_f32_16x16x32_bf16 v[104:107], v[172:175], v[176:179], v[104:107]
	ds_read_b128 v[176:179], v75 offset:16384
	global_load_dwordx4 v[204:207], v67, s[92:93] offset:1024
	s_add_u32 s84, s84, 0x800
	s_addc_u32 s85, s85, 0
	s_add_u32 s92, s92, 0x800
	s_addc_u32 s93, s93, 0
	s_waitcnt lgkmcnt(5)
	v_mfma_f32_16x16x32_bf16 v[44:47], v[160:163], v[180:183], v[44:47]
	v_mfma_f32_16x16x32_bf16 v[20:23], v[164:167], v[180:183], v[20:23]
	v_mfma_f32_16x16x32_bf16 v[236:239], v[168:171], v[180:183], v[236:239]
	v_mfma_f32_16x16x32_bf16 v[108:111], v[172:175], v[180:183], v[108:111]
	ds_read_b128 v[180:183], v75 offset:18432
	s_add_u32 m0, s88, 49152
	s_nop 0
	global_load_lds_dwordx4 v68, s[86:87]
	s_waitcnt lgkmcnt(5)
	v_mfma_f32_16x16x32_bf16 v[48:51], v[160:163], v[184:187], v[48:51]
	v_mfma_f32_16x16x32_bf16 v[0:3], v[164:167], v[184:187], v[0:3]
	v_mfma_f32_16x16x32_bf16 v[240:243], v[168:171], v[184:187], v[240:243]
	v_mfma_f32_16x16x32_bf16 v[112:115], v[172:175], v[184:187], v[112:115]
	ds_read_b128 v[184:187], v75 offset:20480
	s_add_u32 m0, s88, 53248
	s_nop 0
	global_load_lds_dwordx4 v69, s[86:87]
	s_waitcnt lgkmcnt(5)
	v_mfma_f32_16x16x32_bf16 v[52:55], v[160:163], v[192:195], v[52:55]
	v_mfma_f32_16x16x32_bf16 v[8:11], v[164:167], v[192:195], v[8:11]
	v_mfma_f32_16x16x32_bf16 v[248:251], v[168:171], v[192:195], v[248:251]
	v_mfma_f32_16x16x32_bf16 v[116:119], v[172:175], v[192:195], v[116:119]
	ds_read_b128 v[192:195], v75 offset:22528
	s_add_u32 m0, s88, 57344
	s_nop 0
	global_load_lds_dwordx4 v71, s[86:87]
	s_waitcnt lgkmcnt(5)
	v_mfma_f32_16x16x32_bf16 v[56:59], v[160:163], v[196:199], v[56:59]
	v_mfma_f32_16x16x32_bf16 v[24:27], v[164:167], v[196:199], v[24:27]
	v_mfma_f32_16x16x32_bf16 v[252:255], v[168:171], v[196:199], v[252:255]
	v_mfma_f32_16x16x32_bf16 v[120:123], v[172:175], v[196:199], v[120:123]
	ds_read_b128 v[196:199], v75 offset:24576
	s_add_u32 m0, s88, 61440
	s_nop 0
	global_load_lds_dwordx4 v74, s[86:87]
	s_add_u32 s86, s86, 128
	s_addc_u32 s87, s87, 0
	s_waitcnt lgkmcnt(5)
	v_mfma_f32_16x16x32_bf16 v[60:63], v[160:163], v[200:203], v[60:63]
	v_mfma_f32_16x16x32_bf16 v[28:31], v[164:167], v[200:203], v[28:31]
	v_mfma_f32_16x16x32_bf16 v[92:95], v[168:171], v[200:203], v[92:95]
	v_mfma_f32_16x16x32_bf16 v[124:127], v[172:175], v[200:203], v[124:127]
	s_waitcnt vmcnt(8)
	ds_read_b128 v[200:203], v75 offset:26624
	global_load_dwordx4 v[160:163], v66, s[84:85] offset:0
	s_waitcnt lgkmcnt(5)
	v_mfma_f32_16x16x32_bf16 v[32:35], v[76:79], v[176:179], v[32:35]
	v_mfma_f32_16x16x32_bf16 v[4:7], v[80:83], v[176:179], v[4:7]
	v_mfma_f32_16x16x32_bf16 v[188:191], v[84:87], v[176:179], v[188:191]
	v_mfma_f32_16x16x32_bf16 v[96:99], v[88:91], v[176:179], v[96:99]
	ds_read_b128 v[176:179], v75 offset:28672
	global_load_dwordx4 v[164:167], v67, s[84:85] offset:0
	s_waitcnt lgkmcnt(5)
	v_mfma_f32_16x16x32_bf16 v[36:39], v[76:79], v[180:183], v[36:39]
	v_mfma_f32_16x16x32_bf16 v[12:15], v[80:83], v[180:183], v[12:15]
	v_mfma_f32_16x16x32_bf16 v[208:211], v[84:87], v[180:183], v[208:211]
	v_mfma_f32_16x16x32_bf16 v[100:103], v[88:91], v[180:183], v[100:103]
	ds_read_b128 v[180:183], v75 offset:30720
	global_load_dwordx4 v[168:171], v66, s[92:93] offset:0
	s_waitcnt lgkmcnt(5)
	v_mfma_f32_16x16x32_bf16 v[40:43], v[76:79], v[184:187], v[40:43]
	v_mfma_f32_16x16x32_bf16 v[16:19], v[80:83], v[184:187], v[16:19]
	v_mfma_f32_16x16x32_bf16 v[232:235], v[84:87], v[184:187], v[232:235]
	v_mfma_f32_16x16x32_bf16 v[104:107], v[88:91], v[184:187], v[104:107]
	ds_read_b128 v[184:187], v212 offset:16384
	global_load_dwordx4 v[172:175], v67, s[92:93] offset:0
	s_waitcnt lgkmcnt(5)
	v_mfma_f32_16x16x32_bf16 v[44:47], v[76:79], v[192:195], v[44:47]
	v_mfma_f32_16x16x32_bf16 v[20:23], v[80:83], v[192:195], v[20:23]
	v_mfma_f32_16x16x32_bf16 v[236:239], v[84:87], v[192:195], v[236:239]
	v_mfma_f32_16x16x32_bf16 v[108:111], v[88:91], v[192:195], v[108:111]
	ds_read_b128 v[192:195], v212 offset:18432
	s_waitcnt lgkmcnt(5)
	v_mfma_f32_16x16x32_bf16 v[48:51], v[76:79], v[196:199], v[48:51]
	v_mfma_f32_16x16x32_bf16 v[0:3], v[80:83], v[196:199], v[0:3]
	v_mfma_f32_16x16x32_bf16 v[240:243], v[84:87], v[196:199], v[240:243]
	v_mfma_f32_16x16x32_bf16 v[112:115], v[88:91], v[196:199], v[112:115]
	ds_read_b128 v[196:199], v212 offset:20480
	s_waitcnt lgkmcnt(5)
	v_mfma_f32_16x16x32_bf16 v[52:55], v[76:79], v[200:203], v[52:55]
	v_mfma_f32_16x16x32_bf16 v[8:11], v[80:83], v[200:203], v[8:11]
	v_mfma_f32_16x16x32_bf16 v[248:251], v[84:87], v[200:203], v[248:251]
	v_mfma_f32_16x16x32_bf16 v[116:119], v[88:91], v[200:203], v[116:119]
	ds_read_b128 v[200:203], v212 offset:22528
	s_waitcnt lgkmcnt(5)
	v_mfma_f32_16x16x32_bf16 v[56:59], v[76:79], v[176:179], v[56:59]
	v_mfma_f32_16x16x32_bf16 v[24:27], v[80:83], v[176:179], v[24:27]
	v_mfma_f32_16x16x32_bf16 v[252:255], v[84:87], v[176:179], v[252:255]
	v_mfma_f32_16x16x32_bf16 v[120:123], v[88:91], v[176:179], v[120:123]
	ds_read_b128 v[176:179], v212 offset:24576
	s_waitcnt lgkmcnt(5)
	v_mfma_f32_16x16x32_bf16 v[60:63], v[76:79], v[180:183], v[60:63]
	v_mfma_f32_16x16x32_bf16 v[28:31], v[80:83], v[180:183], v[28:31]
	v_mfma_f32_16x16x32_bf16 v[92:95], v[84:87], v[180:183], v[92:95]
	v_mfma_f32_16x16x32_bf16 v[124:127], v[88:91], v[180:183], v[124:127]
	s_waitcnt vmcnt(16)
	s_barrier
	s_waitcnt vmcnt(8)
	ds_read_b128 v[180:183], v212 offset:26624
	global_load_dwordx4 v[76:79], v66, s[84:85] offset:1024
	s_waitcnt lgkmcnt(5)
	v_mfma_f32_16x16x32_bf16 v[32:35], v[140:143], v[184:187], v[32:35]
	v_mfma_f32_16x16x32_bf16 v[4:7], v[144:147], v[184:187], v[4:7]
	v_mfma_f32_16x16x32_bf16 v[188:191], v[148:151], v[184:187], v[188:191]
	v_mfma_f32_16x16x32_bf16 v[96:99], v[204:207], v[184:187], v[96:99]
	ds_read_b128 v[184:187], v212 offset:28672
	global_load_dwordx4 v[80:83], v67, s[84:85] offset:1024
	s_waitcnt lgkmcnt(5)
	v_mfma_f32_16x16x32_bf16 v[36:39], v[140:143], v[192:195], v[36:39]
	v_mfma_f32_16x16x32_bf16 v[12:15], v[144:147], v[192:195], v[12:15]
	v_mfma_f32_16x16x32_bf16 v[208:211], v[148:151], v[192:195], v[208:211]
	v_mfma_f32_16x16x32_bf16 v[100:103], v[204:207], v[192:195], v[100:103]
	ds_read_b128 v[192:195], v212 offset:30720
	global_load_dwordx4 v[84:87], v66, s[92:93] offset:1024
	s_waitcnt lgkmcnt(5)
	v_mfma_f32_16x16x32_bf16 v[40:43], v[140:143], v[196:199], v[40:43]
	v_mfma_f32_16x16x32_bf16 v[16:19], v[144:147], v[196:199], v[16:19]
	v_mfma_f32_16x16x32_bf16 v[232:235], v[148:151], v[196:199], v[232:235]
	v_mfma_f32_16x16x32_bf16 v[104:107], v[204:207], v[196:199], v[104:107]
	ds_read_b128 v[196:199], v75 offset:32768
	global_load_dwordx4 v[88:91], v67, s[92:93] offset:1024
	s_add_u32 s84, s84, 0x800
	s_addc_u32 s85, s85, 0
	s_add_u32 s92, s92, 0x800
	s_addc_u32 s93, s93, 0
	s_waitcnt lgkmcnt(5)
	v_mfma_f32_16x16x32_bf16 v[44:47], v[140:143], v[200:203], v[44:47]
	v_mfma_f32_16x16x32_bf16 v[20:23], v[144:147], v[200:203], v[20:23]
	v_mfma_f32_16x16x32_bf16 v[236:239], v[148:151], v[200:203], v[236:239]
	v_mfma_f32_16x16x32_bf16 v[108:111], v[204:207], v[200:203], v[108:111]
	ds_read_b128 v[200:203], v75 offset:34816
	s_add_u32 m0, s88, 0
	s_nop 0
	global_load_lds_dwordx4 v68, s[86:87]
	s_waitcnt lgkmcnt(5)
	v_mfma_f32_16x16x32_bf16 v[48:51], v[140:143], v[176:179], v[48:51]
	v_mfma_f32_16x16x32_bf16 v[0:3], v[144:147], v[176:179], v[0:3]
	v_mfma_f32_16x16x32_bf16 v[240:243], v[148:151], v[176:179], v[240:243]
	v_mfma_f32_16x16x32_bf16 v[112:115], v[204:207], v[176:179], v[112:115]
	ds_read_b128 v[176:179], v75 offset:36864
	s_add_u32 m0, s88, 4096
	s_nop 0
	global_load_lds_dwordx4 v69, s[86:87]
	s_waitcnt lgkmcnt(5)
	v_mfma_f32_16x16x32_bf16 v[52:55], v[140:143], v[180:183], v[52:55]
	v_mfma_f32_16x16x32_bf16 v[8:11], v[144:147], v[180:183], v[8:11]
	v_mfma_f32_16x16x32_bf16 v[248:251], v[148:151], v[180:183], v[248:251]
	v_mfma_f32_16x16x32_bf16 v[116:119], v[204:207], v[180:183], v[116:119]
	ds_read_b128 v[180:183], v75 offset:38912
	s_add_u32 m0, s88, 8192
	s_nop 0
	global_load_lds_dwordx4 v71, s[86:87]
	s_waitcnt lgkmcnt(5)
	v_mfma_f32_16x16x32_bf16 v[56:59], v[140:143], v[184:187], v[56:59]
	v_mfma_f32_16x16x32_bf16 v[24:27], v[144:147], v[184:187], v[24:27]
	v_mfma_f32_16x16x32_bf16 v[252:255], v[148:151], v[184:187], v[252:255]
	v_mfma_f32_16x16x32_bf16 v[120:123], v[204:207], v[184:187], v[120:123]
	ds_read_b128 v[184:187], v75 offset:40960
	s_add_u32 m0, s88, 12288
	s_nop 0
	global_load_lds_dwordx4 v74, s[86:87]
	s_add_u32 s86, s86, 128
	s_addc_u32 s87, s87, 0
	s_waitcnt lgkmcnt(5)
	v_mfma_f32_16x16x32_bf16 v[60:63], v[140:143], v[192:195], v[60:63]
	v_mfma_f32_16x16x32_bf16 v[28:31], v[144:147], v[192:195], v[28:31]
	v_mfma_f32_16x16x32_bf16 v[92:95], v[148:151], v[192:195], v[92:95]
	v_mfma_f32_16x16x32_bf16 v[124:127], v[204:207], v[192:195], v[124:127]
	s_waitcnt vmcnt(8)
	ds_read_b128 v[192:195], v75 offset:43008
	global_load_dwordx4 v[140:143], v66, s[84:85] offset:0
	s_waitcnt lgkmcnt(5)
	v_mfma_f32_16x16x32_bf16 v[32:35], v[160:163], v[196:199], v[32:35]
	v_mfma_f32_16x16x32_bf16 v[4:7], v[164:167], v[196:199], v[4:7]
	v_mfma_f32_16x16x32_bf16 v[188:191], v[168:171], v[196:199], v[188:191]
	v_mfma_f32_16x16x32_bf16 v[96:99], v[172:175], v[196:199], v[96:99]
	ds_read_b128 v[196:199], v75 offset:45056
	global_load_dwordx4 v[144:147], v67, s[84:85] offset:0
	s_waitcnt lgkmcnt(5)
	v_mfma_f32_16x16x32_bf16 v[36:39], v[160:163], v[200:203], v[36:39]
	v_mfma_f32_16x16x32_bf16 v[12:15], v[164:167], v[200:203], v[12:15]
	v_mfma_f32_16x16x32_bf16 v[208:211], v[168:171], v[200:203], v[208:211]
	v_mfma_f32_16x16x32_bf16 v[100:103], v[172:175], v[200:203], v[100:103]
	ds_read_b128 v[200:203], v75 offset:47104
	global_load_dwordx4 v[148:151], v66, s[92:93] offset:0
	s_waitcnt lgkmcnt(5)
	v_mfma_f32_16x16x32_bf16 v[40:43], v[160:163], v[176:179], v[40:43]
	v_mfma_f32_16x16x32_bf16 v[16:19], v[164:167], v[176:179], v[16:19]
	v_mfma_f32_16x16x32_bf16 v[232:235], v[168:171], v[176:179], v[232:235]
	v_mfma_f32_16x16x32_bf16 v[104:107], v[172:175], v[176:179], v[104:107]
	ds_read_b128 v[176:179], v212 offset:32768
	global_load_dwordx4 v[204:207], v67, s[92:93] offset:0
	s_waitcnt lgkmcnt(5)
	v_mfma_f32_16x16x32_bf16 v[44:47], v[160:163], v[180:183], v[44:47]
	v_mfma_f32_16x16x32_bf16 v[20:23], v[164:167], v[180:183], v[20:23]
	v_mfma_f32_16x16x32_bf16 v[236:239], v[168:171], v[180:183], v[236:239]
	v_mfma_f32_16x16x32_bf16 v[108:111], v[172:175], v[180:183], v[108:111]
	ds_read_b128 v[180:183], v212 offset:34816
	s_waitcnt lgkmcnt(5)
	v_mfma_f32_16x16x32_bf16 v[48:51], v[160:163], v[184:187], v[48:51]
	v_mfma_f32_16x16x32_bf16 v[0:3], v[164:167], v[184:187], v[0:3]
	v_mfma_f32_16x16x32_bf16 v[240:243], v[168:171], v[184:187], v[240:243]
	v_mfma_f32_16x16x32_bf16 v[112:115], v[172:175], v[184:187], v[112:115]
	ds_read_b128 v[184:187], v212 offset:36864
	s_waitcnt lgkmcnt(5)
	v_mfma_f32_16x16x32_bf16 v[52:55], v[160:163], v[192:195], v[52:55]
	v_mfma_f32_16x16x32_bf16 v[8:11], v[164:167], v[192:195], v[8:11]
	v_mfma_f32_16x16x32_bf16 v[248:251], v[168:171], v[192:195], v[248:251]
	v_mfma_f32_16x16x32_bf16 v[116:119], v[172:175], v[192:195], v[116:119]
	ds_read_b128 v[192:195], v212 offset:38912
	s_waitcnt lgkmcnt(5)
	v_mfma_f32_16x16x32_bf16 v[56:59], v[160:163], v[196:199], v[56:59]
	v_mfma_f32_16x16x32_bf16 v[24:27], v[164:167], v[196:199], v[24:27]
	v_mfma_f32_16x16x32_bf16 v[252:255], v[168:171], v[196:199], v[252:255]
	v_mfma_f32_16x16x32_bf16 v[120:123], v[172:175], v[196:199], v[120:123]
	ds_read_b128 v[196:199], v212 offset:40960
	s_waitcnt lgkmcnt(5)
	v_mfma_f32_16x16x32_bf16 v[60:63], v[160:163], v[200:203], v[60:63]
	v_mfma_f32_16x16x32_bf16 v[28:31], v[164:167], v[200:203], v[28:31]
	v_mfma_f32_16x16x32_bf16 v[92:95], v[168:171], v[200:203], v[92:95]
	v_mfma_f32_16x16x32_bf16 v[124:127], v[172:175], v[200:203], v[124:127]
	s_waitcnt vmcnt(16)
	s_barrier
	s_waitcnt vmcnt(8)
	ds_read_b128 v[200:203], v212 offset:43008
	global_load_dwordx4 v[160:163], v66, s[84:85] offset:1024
	s_waitcnt lgkmcnt(5)
	v_mfma_f32_16x16x32_bf16 v[32:35], v[76:79], v[176:179], v[32:35]
	v_mfma_f32_16x16x32_bf16 v[4:7], v[80:83], v[176:179], v[4:7]
	v_mfma_f32_16x16x32_bf16 v[188:191], v[84:87], v[176:179], v[188:191]
	v_mfma_f32_16x16x32_bf16 v[96:99], v[88:91], v[176:179], v[96:99]
	ds_read_b128 v[176:179], v212 offset:45056
	global_load_dwordx4 v[164:167], v67, s[84:85] offset:1024
	s_waitcnt lgkmcnt(5)
	v_mfma_f32_16x16x32_bf16 v[36:39], v[76:79], v[180:183], v[36:39]
	v_mfma_f32_16x16x32_bf16 v[12:15], v[80:83], v[180:183], v[12:15]
	v_mfma_f32_16x16x32_bf16 v[208:211], v[84:87], v[180:183], v[208:211]
	v_mfma_f32_16x16x32_bf16 v[100:103], v[88:91], v[180:183], v[100:103]
	ds_read_b128 v[180:183], v212 offset:47104
	global_load_dwordx4 v[168:171], v66, s[92:93] offset:1024
	s_waitcnt lgkmcnt(5)
	v_mfma_f32_16x16x32_bf16 v[40:43], v[76:79], v[184:187], v[40:43]
	v_mfma_f32_16x16x32_bf16 v[16:19], v[80:83], v[184:187], v[16:19]
	v_mfma_f32_16x16x32_bf16 v[232:235], v[84:87], v[184:187], v[232:235]
	v_mfma_f32_16x16x32_bf16 v[104:107], v[88:91], v[184:187], v[104:107]
	ds_read_b128 v[184:187], v75 offset:49152
	global_load_dwordx4 v[172:175], v67, s[92:93] offset:1024
	s_add_u32 s84, s84, 0x800
	s_addc_u32 s85, s85, 0
	s_add_u32 s92, s92, 0x800
	s_addc_u32 s93, s93, 0
	s_waitcnt lgkmcnt(5)
	v_mfma_f32_16x16x32_bf16 v[44:47], v[76:79], v[192:195], v[44:47]
	v_mfma_f32_16x16x32_bf16 v[20:23], v[80:83], v[192:195], v[20:23]
	v_mfma_f32_16x16x32_bf16 v[236:239], v[84:87], v[192:195], v[236:239]
	v_mfma_f32_16x16x32_bf16 v[108:111], v[88:91], v[192:195], v[108:111]
	ds_read_b128 v[192:195], v75 offset:51200
	s_add_u32 m0, s88, 16384
	s_nop 0
	global_load_lds_dwordx4 v68, s[86:87]
	s_waitcnt lgkmcnt(5)
	v_mfma_f32_16x16x32_bf16 v[48:51], v[76:79], v[196:199], v[48:51]
	v_mfma_f32_16x16x32_bf16 v[0:3], v[80:83], v[196:199], v[0:3]
	v_mfma_f32_16x16x32_bf16 v[240:243], v[84:87], v[196:199], v[240:243]
	v_mfma_f32_16x16x32_bf16 v[112:115], v[88:91], v[196:199], v[112:115]
	ds_read_b128 v[196:199], v75 offset:53248
	s_add_u32 m0, s88, 20480
	s_nop 0
	global_load_lds_dwordx4 v69, s[86:87]
	s_waitcnt lgkmcnt(5)
	v_mfma_f32_16x16x32_bf16 v[52:55], v[76:79], v[200:203], v[52:55]
	v_mfma_f32_16x16x32_bf16 v[8:11], v[80:83], v[200:203], v[8:11]
	v_mfma_f32_16x16x32_bf16 v[248:251], v[84:87], v[200:203], v[248:251]
	v_mfma_f32_16x16x32_bf16 v[116:119], v[88:91], v[200:203], v[116:119]
	ds_read_b128 v[200:203], v75 offset:55296
	s_add_u32 m0, s88, 24576
	s_nop 0
	global_load_lds_dwordx4 v71, s[86:87]
	s_waitcnt lgkmcnt(5)
	v_mfma_f32_16x16x32_bf16 v[56:59], v[76:79], v[176:179], v[56:59]
	v_mfma_f32_16x16x32_bf16 v[24:27], v[80:83], v[176:179], v[24:27]
	v_mfma_f32_16x16x32_bf16 v[252:255], v[84:87], v[176:179], v[252:255]
	v_mfma_f32_16x16x32_bf16 v[120:123], v[88:91], v[176:179], v[120:123]
	ds_read_b128 v[176:179], v75 offset:57344
	s_add_u32 m0, s88, 28672
	s_nop 0
	global_load_lds_dwordx4 v74, s[86:87]
	s_add_u32 s86, s86, 128
	s_addc_u32 s87, s87, 0
	s_waitcnt lgkmcnt(5)
	v_mfma_f32_16x16x32_bf16 v[60:63], v[76:79], v[180:183], v[60:63]
	v_mfma_f32_16x16x32_bf16 v[28:31], v[80:83], v[180:183], v[28:31]
	v_mfma_f32_16x16x32_bf16 v[92:95], v[84:87], v[180:183], v[92:95]
	v_mfma_f32_16x16x32_bf16 v[124:127], v[88:91], v[180:183], v[124:127]
	s_waitcnt vmcnt(8)
	ds_read_b128 v[180:183], v75 offset:59392
	global_load_dwordx4 v[76:79], v66, s[84:85] offset:0
	s_waitcnt lgkmcnt(5)
	v_mfma_f32_16x16x32_bf16 v[32:35], v[140:143], v[184:187], v[32:35]
	v_mfma_f32_16x16x32_bf16 v[4:7], v[144:147], v[184:187], v[4:7]
	v_mfma_f32_16x16x32_bf16 v[188:191], v[148:151], v[184:187], v[188:191]
	v_mfma_f32_16x16x32_bf16 v[96:99], v[204:207], v[184:187], v[96:99]
	ds_read_b128 v[184:187], v75 offset:61440
	global_load_dwordx4 v[80:83], v67, s[84:85] offset:0
	s_waitcnt lgkmcnt(5)
	v_mfma_f32_16x16x32_bf16 v[36:39], v[140:143], v[192:195], v[36:39]
	v_mfma_f32_16x16x32_bf16 v[12:15], v[144:147], v[192:195], v[12:15]
	v_mfma_f32_16x16x32_bf16 v[208:211], v[148:151], v[192:195], v[208:211]
	v_mfma_f32_16x16x32_bf16 v[100:103], v[204:207], v[192:195], v[100:103]
	ds_read_b128 v[192:195], v75 offset:63488
	global_load_dwordx4 v[84:87], v66, s[92:93] offset:0
	s_waitcnt lgkmcnt(5)
	v_mfma_f32_16x16x32_bf16 v[40:43], v[140:143], v[196:199], v[40:43]
	v_mfma_f32_16x16x32_bf16 v[16:19], v[144:147], v[196:199], v[16:19]
	v_mfma_f32_16x16x32_bf16 v[232:235], v[148:151], v[196:199], v[232:235]
	v_mfma_f32_16x16x32_bf16 v[104:107], v[204:207], v[196:199], v[104:107]
	ds_read_b128 v[196:199], v212 offset:49152
	global_load_dwordx4 v[88:91], v67, s[92:93] offset:0
	s_waitcnt lgkmcnt(5)
	v_mfma_f32_16x16x32_bf16 v[44:47], v[140:143], v[200:203], v[44:47]
	v_mfma_f32_16x16x32_bf16 v[20:23], v[144:147], v[200:203], v[20:23]
	v_mfma_f32_16x16x32_bf16 v[236:239], v[148:151], v[200:203], v[236:239]
	v_mfma_f32_16x16x32_bf16 v[108:111], v[204:207], v[200:203], v[108:111]
	ds_read_b128 v[200:203], v212 offset:51200
	s_waitcnt lgkmcnt(5)
	v_mfma_f32_16x16x32_bf16 v[48:51], v[140:143], v[176:179], v[48:51]
	v_mfma_f32_16x16x32_bf16 v[0:3], v[144:147], v[176:179], v[0:3]
	v_mfma_f32_16x16x32_bf16 v[240:243], v[148:151], v[176:179], v[240:243]
	v_mfma_f32_16x16x32_bf16 v[112:115], v[204:207], v[176:179], v[112:115]
	ds_read_b128 v[176:179], v212 offset:53248
	s_waitcnt lgkmcnt(5)
	v_mfma_f32_16x16x32_bf16 v[52:55], v[140:143], v[180:183], v[52:55]
	v_mfma_f32_16x16x32_bf16 v[8:11], v[144:147], v[180:183], v[8:11]
	v_mfma_f32_16x16x32_bf16 v[248:251], v[148:151], v[180:183], v[248:251]
	v_mfma_f32_16x16x32_bf16 v[116:119], v[204:207], v[180:183], v[116:119]
	ds_read_b128 v[180:183], v212 offset:55296
	s_waitcnt lgkmcnt(5)
	v_mfma_f32_16x16x32_bf16 v[56:59], v[140:143], v[184:187], v[56:59]
	v_mfma_f32_16x16x32_bf16 v[24:27], v[144:147], v[184:187], v[24:27]
	v_mfma_f32_16x16x32_bf16 v[252:255], v[148:151], v[184:187], v[252:255]
	v_mfma_f32_16x16x32_bf16 v[120:123], v[204:207], v[184:187], v[120:123]
	ds_read_b128 v[184:187], v212 offset:57344
	s_waitcnt lgkmcnt(5)
	v_mfma_f32_16x16x32_bf16 v[60:63], v[140:143], v[192:195], v[60:63]
	v_mfma_f32_16x16x32_bf16 v[28:31], v[144:147], v[192:195], v[28:31]
	v_mfma_f32_16x16x32_bf16 v[92:95], v[148:151], v[192:195], v[92:95]
	v_mfma_f32_16x16x32_bf16 v[124:127], v[204:207], v[192:195], v[124:127]
	s_waitcnt vmcnt(16)
	s_barrier
	s_waitcnt vmcnt(8)
	ds_read_b128 v[192:195], v212 offset:59392
	global_load_dwordx4 v[140:143], v66, s[84:85] offset:1024
	s_waitcnt lgkmcnt(5)
	v_mfma_f32_16x16x32_bf16 v[32:35], v[160:163], v[196:199], v[32:35]
	v_mfma_f32_16x16x32_bf16 v[4:7], v[164:167], v[196:199], v[4:7]
	v_mfma_f32_16x16x32_bf16 v[188:191], v[168:171], v[196:199], v[188:191]
	v_mfma_f32_16x16x32_bf16 v[96:99], v[172:175], v[196:199], v[96:99]
	ds_read_b128 v[196:199], v212 offset:61440
	global_load_dwordx4 v[144:147], v67, s[84:85] offset:1024
	s_waitcnt lgkmcnt(5)
	v_mfma_f32_16x16x32_bf16 v[36:39], v[160:163], v[200:203], v[36:39]
	v_mfma_f32_16x16x32_bf16 v[12:15], v[164:167], v[200:203], v[12:15]
	v_mfma_f32_16x16x32_bf16 v[208:211], v[168:171], v[200:203], v[208:211]
	v_mfma_f32_16x16x32_bf16 v[100:103], v[172:175], v[200:203], v[100:103]
	ds_read_b128 v[200:203], v212 offset:63488
	global_load_dwordx4 v[148:151], v66, s[92:93] offset:1024
	s_waitcnt lgkmcnt(5)
	v_mfma_f32_16x16x32_bf16 v[40:43], v[160:163], v[176:179], v[40:43]
	v_mfma_f32_16x16x32_bf16 v[16:19], v[164:167], v[176:179], v[16:19]
	v_mfma_f32_16x16x32_bf16 v[232:235], v[168:171], v[176:179], v[232:235]
	v_mfma_f32_16x16x32_bf16 v[104:107], v[172:175], v[176:179], v[104:107]
	ds_read_b128 v[176:179], v75 offset:0
	global_load_dwordx4 v[204:207], v67, s[92:93] offset:1024
	s_add_u32 s84, s84, 0x800
	s_addc_u32 s85, s85, 0
	s_add_u32 s92, s92, 0x800
	s_addc_u32 s93, s93, 0
	s_waitcnt lgkmcnt(5)
	v_mfma_f32_16x16x32_bf16 v[44:47], v[160:163], v[180:183], v[44:47]
	v_mfma_f32_16x16x32_bf16 v[20:23], v[164:167], v[180:183], v[20:23]
	v_mfma_f32_16x16x32_bf16 v[236:239], v[168:171], v[180:183], v[236:239]
	v_mfma_f32_16x16x32_bf16 v[108:111], v[172:175], v[180:183], v[108:111]
	ds_read_b128 v[180:183], v75 offset:2048
	s_add_u32 m0, s88, 32768
	s_nop 0
	global_load_lds_dwordx4 v68, s[86:87]
	s_waitcnt lgkmcnt(5)
	v_mfma_f32_16x16x32_bf16 v[48:51], v[160:163], v[184:187], v[48:51]
	v_mfma_f32_16x16x32_bf16 v[0:3], v[164:167], v[184:187], v[0:3]
	v_mfma_f32_16x16x32_bf16 v[240:243], v[168:171], v[184:187], v[240:243]
	v_mfma_f32_16x16x32_bf16 v[112:115], v[172:175], v[184:187], v[112:115]
	ds_read_b128 v[184:187], v75 offset:4096
	s_add_u32 m0, s88, 36864
	s_nop 0
	global_load_lds_dwordx4 v69, s[86:87]
	s_waitcnt lgkmcnt(5)
	v_mfma_f32_16x16x32_bf16 v[52:55], v[160:163], v[192:195], v[52:55]
	v_mfma_f32_16x16x32_bf16 v[8:11], v[164:167], v[192:195], v[8:11]
	v_mfma_f32_16x16x32_bf16 v[248:251], v[168:171], v[192:195], v[248:251]
	v_mfma_f32_16x16x32_bf16 v[116:119], v[172:175], v[192:195], v[116:119]
	ds_read_b128 v[192:195], v75 offset:6144
	s_add_u32 m0, s88, 40960
	s_nop 0
	global_load_lds_dwordx4 v71, s[86:87]
	s_waitcnt lgkmcnt(5)
	v_mfma_f32_16x16x32_bf16 v[56:59], v[160:163], v[196:199], v[56:59]
	v_mfma_f32_16x16x32_bf16 v[24:27], v[164:167], v[196:199], v[24:27]
	v_mfma_f32_16x16x32_bf16 v[252:255], v[168:171], v[196:199], v[252:255]
	v_mfma_f32_16x16x32_bf16 v[120:123], v[172:175], v[196:199], v[120:123]
	ds_read_b128 v[196:199], v75 offset:8192
	s_add_u32 m0, s88, 45056
	s_nop 0
	global_load_lds_dwordx4 v74, s[86:87]
	s_add_u32 s86, s86, 128
	s_addc_u32 s87, s87, 0
	s_waitcnt lgkmcnt(5)
	v_mfma_f32_16x16x32_bf16 v[60:63], v[160:163], v[200:203], v[60:63]
	v_mfma_f32_16x16x32_bf16 v[28:31], v[164:167], v[200:203], v[28:31]
	v_mfma_f32_16x16x32_bf16 v[92:95], v[168:171], v[200:203], v[92:95]
	v_mfma_f32_16x16x32_bf16 v[124:127], v[172:175], v[200:203], v[124:127]
	s_waitcnt vmcnt(8)
	ds_read_b128 v[200:203], v75 offset:10240
	global_load_dwordx4 v[160:163], v66, s[84:85] offset:0
	s_waitcnt lgkmcnt(5)
	v_mfma_f32_16x16x32_bf16 v[32:35], v[76:79], v[176:179], v[32:35]
	v_mfma_f32_16x16x32_bf16 v[4:7], v[80:83], v[176:179], v[4:7]
	v_mfma_f32_16x16x32_bf16 v[188:191], v[84:87], v[176:179], v[188:191]
	v_mfma_f32_16x16x32_bf16 v[96:99], v[88:91], v[176:179], v[96:99]
	ds_read_b128 v[176:179], v75 offset:12288
	global_load_dwordx4 v[164:167], v67, s[84:85] offset:0
	s_waitcnt lgkmcnt(5)
	v_mfma_f32_16x16x32_bf16 v[36:39], v[76:79], v[180:183], v[36:39]
	v_mfma_f32_16x16x32_bf16 v[12:15], v[80:83], v[180:183], v[12:15]
	v_mfma_f32_16x16x32_bf16 v[208:211], v[84:87], v[180:183], v[208:211]
	v_mfma_f32_16x16x32_bf16 v[100:103], v[88:91], v[180:183], v[100:103]
	ds_read_b128 v[180:183], v75 offset:14336
	global_load_dwordx4 v[168:171], v66, s[92:93] offset:0
	s_waitcnt lgkmcnt(5)
	v_mfma_f32_16x16x32_bf16 v[40:43], v[76:79], v[184:187], v[40:43]
	v_mfma_f32_16x16x32_bf16 v[16:19], v[80:83], v[184:187], v[16:19]
	v_mfma_f32_16x16x32_bf16 v[232:235], v[84:87], v[184:187], v[232:235]
	v_mfma_f32_16x16x32_bf16 v[104:107], v[88:91], v[184:187], v[104:107]
	ds_read_b128 v[184:187], v212 offset:0
	global_load_dwordx4 v[172:175], v67, s[92:93] offset:0
	s_waitcnt lgkmcnt(5)
	v_mfma_f32_16x16x32_bf16 v[44:47], v[76:79], v[192:195], v[44:47]
	v_mfma_f32_16x16x32_bf16 v[20:23], v[80:83], v[192:195], v[20:23]
	v_mfma_f32_16x16x32_bf16 v[236:239], v[84:87], v[192:195], v[236:239]
	v_mfma_f32_16x16x32_bf16 v[108:111], v[88:91], v[192:195], v[108:111]
	ds_read_b128 v[192:195], v212 offset:2048
	s_waitcnt lgkmcnt(5)
	v_mfma_f32_16x16x32_bf16 v[48:51], v[76:79], v[196:199], v[48:51]
	v_mfma_f32_16x16x32_bf16 v[0:3], v[80:83], v[196:199], v[0:3]
	v_mfma_f32_16x16x32_bf16 v[240:243], v[84:87], v[196:199], v[240:243]
	v_mfma_f32_16x16x32_bf16 v[112:115], v[88:91], v[196:199], v[112:115]
	ds_read_b128 v[196:199], v212 offset:4096
	s_waitcnt lgkmcnt(5)
	v_mfma_f32_16x16x32_bf16 v[52:55], v[76:79], v[200:203], v[52:55]
	v_mfma_f32_16x16x32_bf16 v[8:11], v[80:83], v[200:203], v[8:11]
	v_mfma_f32_16x16x32_bf16 v[248:251], v[84:87], v[200:203], v[248:251]
	v_mfma_f32_16x16x32_bf16 v[116:119], v[88:91], v[200:203], v[116:119]
	ds_read_b128 v[200:203], v212 offset:6144
	s_waitcnt lgkmcnt(5)
	v_mfma_f32_16x16x32_bf16 v[56:59], v[76:79], v[176:179], v[56:59]
	v_mfma_f32_16x16x32_bf16 v[24:27], v[80:83], v[176:179], v[24:27]
	v_mfma_f32_16x16x32_bf16 v[252:255], v[84:87], v[176:179], v[252:255]
	v_mfma_f32_16x16x32_bf16 v[120:123], v[88:91], v[176:179], v[120:123]
	ds_read_b128 v[176:179], v212 offset:8192
	s_waitcnt lgkmcnt(5)
	v_mfma_f32_16x16x32_bf16 v[60:63], v[76:79], v[180:183], v[60:63]
	v_mfma_f32_16x16x32_bf16 v[28:31], v[80:83], v[180:183], v[28:31]
	v_mfma_f32_16x16x32_bf16 v[92:95], v[84:87], v[180:183], v[92:95]
	v_mfma_f32_16x16x32_bf16 v[124:127], v[88:91], v[180:183], v[124:127]
	s_waitcnt vmcnt(16)
	s_barrier
	s_waitcnt vmcnt(8)
	ds_read_b128 v[180:183], v212 offset:10240
	global_load_dwordx4 v[76:79], v66, s[84:85] offset:1024
	s_waitcnt lgkmcnt(5)
	v_mfma_f32_16x16x32_bf16 v[32:35], v[140:143], v[184:187], v[32:35]
	v_mfma_f32_16x16x32_bf16 v[4:7], v[144:147], v[184:187], v[4:7]
	v_mfma_f32_16x16x32_bf16 v[188:191], v[148:151], v[184:187], v[188:191]
	v_mfma_f32_16x16x32_bf16 v[96:99], v[204:207], v[184:187], v[96:99]
	ds_read_b128 v[184:187], v212 offset:12288
	global_load_dwordx4 v[80:83], v67, s[84:85] offset:1024
	s_waitcnt lgkmcnt(5)
	v_mfma_f32_16x16x32_bf16 v[36:39], v[140:143], v[192:195], v[36:39]
	v_mfma_f32_16x16x32_bf16 v[12:15], v[144:147], v[192:195], v[12:15]
	v_mfma_f32_16x16x32_bf16 v[208:211], v[148:151], v[192:195], v[208:211]
	v_mfma_f32_16x16x32_bf16 v[100:103], v[204:207], v[192:195], v[100:103]
	ds_read_b128 v[192:195], v212 offset:14336
	global_load_dwordx4 v[84:87], v66, s[92:93] offset:1024
	s_waitcnt lgkmcnt(5)
	v_mfma_f32_16x16x32_bf16 v[40:43], v[140:143], v[196:199], v[40:43]
	v_mfma_f32_16x16x32_bf16 v[16:19], v[144:147], v[196:199], v[16:19]
	v_mfma_f32_16x16x32_bf16 v[232:235], v[148:151], v[196:199], v[232:235]
	v_mfma_f32_16x16x32_bf16 v[104:107], v[204:207], v[196:199], v[104:107]
	ds_read_b128 v[196:199], v75 offset:16384
	global_load_dwordx4 v[88:91], v67, s[92:93] offset:1024
	s_add_u32 s84, s84, 0x800
	s_addc_u32 s85, s85, 0
	s_add_u32 s92, s92, 0x800
	s_addc_u32 s93, s93, 0
	s_waitcnt lgkmcnt(5)
	v_mfma_f32_16x16x32_bf16 v[44:47], v[140:143], v[200:203], v[44:47]
	v_mfma_f32_16x16x32_bf16 v[20:23], v[144:147], v[200:203], v[20:23]
	v_mfma_f32_16x16x32_bf16 v[236:239], v[148:151], v[200:203], v[236:239]
	v_mfma_f32_16x16x32_bf16 v[108:111], v[204:207], v[200:203], v[108:111]
	ds_read_b128 v[200:203], v75 offset:18432
	s_add_u32 m0, s88, 49152
	s_nop 0
	global_load_lds_dwordx4 v68, s[86:87]
	s_waitcnt lgkmcnt(5)
	v_mfma_f32_16x16x32_bf16 v[48:51], v[140:143], v[176:179], v[48:51]
	v_mfma_f32_16x16x32_bf16 v[0:3], v[144:147], v[176:179], v[0:3]
	v_mfma_f32_16x16x32_bf16 v[240:243], v[148:151], v[176:179], v[240:243]
	v_mfma_f32_16x16x32_bf16 v[112:115], v[204:207], v[176:179], v[112:115]
	ds_read_b128 v[176:179], v75 offset:20480
	s_add_u32 m0, s88, 53248
	s_nop 0
	global_load_lds_dwordx4 v69, s[86:87]
	s_waitcnt lgkmcnt(5)
	v_mfma_f32_16x16x32_bf16 v[52:55], v[140:143], v[180:183], v[52:55]
	v_mfma_f32_16x16x32_bf16 v[8:11], v[144:147], v[180:183], v[8:11]
	v_mfma_f32_16x16x32_bf16 v[248:251], v[148:151], v[180:183], v[248:251]
	v_mfma_f32_16x16x32_bf16 v[116:119], v[204:207], v[180:183], v[116:119]
	ds_read_b128 v[180:183], v75 offset:22528
	s_add_u32 m0, s88, 57344
	s_nop 0
	global_load_lds_dwordx4 v71, s[86:87]
	s_waitcnt lgkmcnt(5)
	v_mfma_f32_16x16x32_bf16 v[56:59], v[140:143], v[184:187], v[56:59]
	v_mfma_f32_16x16x32_bf16 v[24:27], v[144:147], v[184:187], v[24:27]
	v_mfma_f32_16x16x32_bf16 v[252:255], v[148:151], v[184:187], v[252:255]
	v_mfma_f32_16x16x32_bf16 v[120:123], v[204:207], v[184:187], v[120:123]
	ds_read_b128 v[184:187], v75 offset:24576
	s_add_u32 m0, s88, 61440
	s_nop 0
	global_load_lds_dwordx4 v74, s[86:87]
	s_add_u32 s86, s86, 128
	s_addc_u32 s87, s87, 0
	s_waitcnt lgkmcnt(5)
	v_mfma_f32_16x16x32_bf16 v[60:63], v[140:143], v[192:195], v[60:63]
	v_mfma_f32_16x16x32_bf16 v[28:31], v[144:147], v[192:195], v[28:31]
	v_mfma_f32_16x16x32_bf16 v[92:95], v[148:151], v[192:195], v[92:95]
	v_mfma_f32_16x16x32_bf16 v[124:127], v[204:207], v[192:195], v[124:127]
	s_waitcnt vmcnt(8)
	ds_read_b128 v[192:195], v75 offset:26624
	global_load_dwordx4 v[140:143], v66, s[84:85] offset:0
	s_waitcnt lgkmcnt(5)
	v_mfma_f32_16x16x32_bf16 v[32:35], v[160:163], v[196:199], v[32:35]
	v_mfma_f32_16x16x32_bf16 v[4:7], v[164:167], v[196:199], v[4:7]
	v_mfma_f32_16x16x32_bf16 v[188:191], v[168:171], v[196:199], v[188:191]
	v_mfma_f32_16x16x32_bf16 v[96:99], v[172:175], v[196:199], v[96:99]
	ds_read_b128 v[196:199], v75 offset:28672
	global_load_dwordx4 v[144:147], v67, s[84:85] offset:0
	s_waitcnt lgkmcnt(5)
	v_mfma_f32_16x16x32_bf16 v[36:39], v[160:163], v[200:203], v[36:39]
	v_mfma_f32_16x16x32_bf16 v[12:15], v[164:167], v[200:203], v[12:15]
	v_mfma_f32_16x16x32_bf16 v[208:211], v[168:171], v[200:203], v[208:211]
	v_mfma_f32_16x16x32_bf16 v[100:103], v[172:175], v[200:203], v[100:103]
	ds_read_b128 v[200:203], v75 offset:30720
	global_load_dwordx4 v[148:151], v66, s[92:93] offset:0
	s_waitcnt lgkmcnt(5)
	v_mfma_f32_16x16x32_bf16 v[40:43], v[160:163], v[176:179], v[40:43]
	v_mfma_f32_16x16x32_bf16 v[16:19], v[164:167], v[176:179], v[16:19]
	v_mfma_f32_16x16x32_bf16 v[232:235], v[168:171], v[176:179], v[232:235]
	v_mfma_f32_16x16x32_bf16 v[104:107], v[172:175], v[176:179], v[104:107]
	ds_read_b128 v[176:179], v212 offset:16384
	global_load_dwordx4 v[204:207], v67, s[92:93] offset:0
	s_waitcnt lgkmcnt(5)
	v_mfma_f32_16x16x32_bf16 v[44:47], v[160:163], v[180:183], v[44:47]
	v_mfma_f32_16x16x32_bf16 v[20:23], v[164:167], v[180:183], v[20:23]
	v_mfma_f32_16x16x32_bf16 v[236:239], v[168:171], v[180:183], v[236:239]
	v_mfma_f32_16x16x32_bf16 v[108:111], v[172:175], v[180:183], v[108:111]
	ds_read_b128 v[180:183], v212 offset:18432
	s_waitcnt lgkmcnt(5)
	v_mfma_f32_16x16x32_bf16 v[48:51], v[160:163], v[184:187], v[48:51]
	v_mfma_f32_16x16x32_bf16 v[0:3], v[164:167], v[184:187], v[0:3]
	v_mfma_f32_16x16x32_bf16 v[240:243], v[168:171], v[184:187], v[240:243]
	v_mfma_f32_16x16x32_bf16 v[112:115], v[172:175], v[184:187], v[112:115]
	ds_read_b128 v[184:187], v212 offset:20480
	s_waitcnt lgkmcnt(5)
	v_mfma_f32_16x16x32_bf16 v[52:55], v[160:163], v[192:195], v[52:55]
	v_mfma_f32_16x16x32_bf16 v[8:11], v[164:167], v[192:195], v[8:11]
	v_mfma_f32_16x16x32_bf16 v[248:251], v[168:171], v[192:195], v[248:251]
	v_mfma_f32_16x16x32_bf16 v[116:119], v[172:175], v[192:195], v[116:119]
	ds_read_b128 v[192:195], v212 offset:22528
	s_waitcnt lgkmcnt(5)
	v_mfma_f32_16x16x32_bf16 v[56:59], v[160:163], v[196:199], v[56:59]
	v_mfma_f32_16x16x32_bf16 v[24:27], v[164:167], v[196:199], v[24:27]
	v_mfma_f32_16x16x32_bf16 v[252:255], v[168:171], v[196:199], v[252:255]
	v_mfma_f32_16x16x32_bf16 v[120:123], v[172:175], v[196:199], v[120:123]
	ds_read_b128 v[196:199], v212 offset:24576
	s_waitcnt lgkmcnt(5)
	v_mfma_f32_16x16x32_bf16 v[60:63], v[160:163], v[200:203], v[60:63]
	v_mfma_f32_16x16x32_bf16 v[28:31], v[164:167], v[200:203], v[28:31]
	v_mfma_f32_16x16x32_bf16 v[92:95], v[168:171], v[200:203], v[92:95]
	v_mfma_f32_16x16x32_bf16 v[124:127], v[172:175], v[200:203], v[124:127]
	s_waitcnt vmcnt(16)
	s_barrier
	s_waitcnt vmcnt(8)
	ds_read_b128 v[200:203], v212 offset:26624
	global_load_dwordx4 v[160:163], v66, s[84:85] offset:1024
	s_waitcnt lgkmcnt(5)
	v_mfma_f32_16x16x32_bf16 v[32:35], v[76:79], v[176:179], v[32:35]
	v_mfma_f32_16x16x32_bf16 v[4:7], v[80:83], v[176:179], v[4:7]
	v_mfma_f32_16x16x32_bf16 v[188:191], v[84:87], v[176:179], v[188:191]
	v_mfma_f32_16x16x32_bf16 v[96:99], v[88:91], v[176:179], v[96:99]
	ds_read_b128 v[176:179], v212 offset:28672
	global_load_dwordx4 v[164:167], v67, s[84:85] offset:1024
	s_waitcnt lgkmcnt(5)
	v_mfma_f32_16x16x32_bf16 v[36:39], v[76:79], v[180:183], v[36:39]
	v_mfma_f32_16x16x32_bf16 v[12:15], v[80:83], v[180:183], v[12:15]
	v_mfma_f32_16x16x32_bf16 v[208:211], v[84:87], v[180:183], v[208:211]
	v_mfma_f32_16x16x32_bf16 v[100:103], v[88:91], v[180:183], v[100:103]
	ds_read_b128 v[180:183], v212 offset:30720
	global_load_dwordx4 v[168:171], v66, s[92:93] offset:1024
	s_waitcnt lgkmcnt(5)
	v_mfma_f32_16x16x32_bf16 v[40:43], v[76:79], v[184:187], v[40:43]
	v_mfma_f32_16x16x32_bf16 v[16:19], v[80:83], v[184:187], v[16:19]
	v_mfma_f32_16x16x32_bf16 v[232:235], v[84:87], v[184:187], v[232:235]
	v_mfma_f32_16x16x32_bf16 v[104:107], v[88:91], v[184:187], v[104:107]
	ds_read_b128 v[184:187], v75 offset:32768
	global_load_dwordx4 v[172:175], v67, s[92:93] offset:1024
	s_add_u32 s84, s84, 0x800
	s_addc_u32 s85, s85, 0
	s_add_u32 s92, s92, 0x800
	s_addc_u32 s93, s93, 0
	s_waitcnt lgkmcnt(5)
	v_mfma_f32_16x16x32_bf16 v[44:47], v[76:79], v[192:195], v[44:47]
	v_mfma_f32_16x16x32_bf16 v[20:23], v[80:83], v[192:195], v[20:23]
	v_mfma_f32_16x16x32_bf16 v[236:239], v[84:87], v[192:195], v[236:239]
	v_mfma_f32_16x16x32_bf16 v[108:111], v[88:91], v[192:195], v[108:111]
	ds_read_b128 v[192:195], v75 offset:34816
	s_waitcnt lgkmcnt(5)
	v_mfma_f32_16x16x32_bf16 v[48:51], v[76:79], v[196:199], v[48:51]
	v_mfma_f32_16x16x32_bf16 v[0:3], v[80:83], v[196:199], v[0:3]
	v_mfma_f32_16x16x32_bf16 v[240:243], v[84:87], v[196:199], v[240:243]
	v_mfma_f32_16x16x32_bf16 v[112:115], v[88:91], v[196:199], v[112:115]
	ds_read_b128 v[196:199], v75 offset:36864
	s_waitcnt lgkmcnt(5)
	v_mfma_f32_16x16x32_bf16 v[52:55], v[76:79], v[200:203], v[52:55]
	v_mfma_f32_16x16x32_bf16 v[8:11], v[80:83], v[200:203], v[8:11]
	v_mfma_f32_16x16x32_bf16 v[248:251], v[84:87], v[200:203], v[248:251]
	v_mfma_f32_16x16x32_bf16 v[116:119], v[88:91], v[200:203], v[116:119]
	ds_read_b128 v[200:203], v75 offset:38912
	s_waitcnt lgkmcnt(5)
	v_mfma_f32_16x16x32_bf16 v[56:59], v[76:79], v[176:179], v[56:59]
	v_mfma_f32_16x16x32_bf16 v[24:27], v[80:83], v[176:179], v[24:27]
	v_mfma_f32_16x16x32_bf16 v[252:255], v[84:87], v[176:179], v[252:255]
	v_mfma_f32_16x16x32_bf16 v[120:123], v[88:91], v[176:179], v[120:123]
	ds_read_b128 v[176:179], v75 offset:40960
	s_waitcnt lgkmcnt(5)
	v_mfma_f32_16x16x32_bf16 v[60:63], v[76:79], v[180:183], v[60:63]
	v_mfma_f32_16x16x32_bf16 v[28:31], v[80:83], v[180:183], v[28:31]
	v_mfma_f32_16x16x32_bf16 v[92:95], v[84:87], v[180:183], v[92:95]
	v_mfma_f32_16x16x32_bf16 v[124:127], v[88:91], v[180:183], v[124:127]
	s_waitcnt vmcnt(4)
	ds_read_b128 v[180:183], v75 offset:43008
	global_load_dwordx4 v[76:79], v66, s[84:85] offset:0
	s_waitcnt lgkmcnt(5)
	v_mfma_f32_16x16x32_bf16 v[32:35], v[140:143], v[184:187], v[32:35]
	v_mfma_f32_16x16x32_bf16 v[4:7], v[144:147], v[184:187], v[4:7]
	v_mfma_f32_16x16x32_bf16 v[188:191], v[148:151], v[184:187], v[188:191]
	v_mfma_f32_16x16x32_bf16 v[96:99], v[204:207], v[184:187], v[96:99]
	ds_read_b128 v[184:187], v75 offset:45056
	global_load_dwordx4 v[80:83], v67, s[84:85] offset:0
	s_waitcnt lgkmcnt(5)
	v_mfma_f32_16x16x32_bf16 v[36:39], v[140:143], v[192:195], v[36:39]
	v_mfma_f32_16x16x32_bf16 v[12:15], v[144:147], v[192:195], v[12:15]
	v_mfma_f32_16x16x32_bf16 v[208:211], v[148:151], v[192:195], v[208:211]
	v_mfma_f32_16x16x32_bf16 v[100:103], v[204:207], v[192:195], v[100:103]
	ds_read_b128 v[192:195], v75 offset:47104
	global_load_dwordx4 v[84:87], v66, s[92:93] offset:0
	s_waitcnt lgkmcnt(5)
	v_mfma_f32_16x16x32_bf16 v[40:43], v[140:143], v[196:199], v[40:43]
	v_mfma_f32_16x16x32_bf16 v[16:19], v[144:147], v[196:199], v[16:19]
	v_mfma_f32_16x16x32_bf16 v[232:235], v[148:151], v[196:199], v[232:235]
	v_mfma_f32_16x16x32_bf16 v[104:107], v[204:207], v[196:199], v[104:107]
	ds_read_b128 v[196:199], v212 offset:32768
	global_load_dwordx4 v[88:91], v67, s[92:93] offset:0
	s_waitcnt lgkmcnt(5)
	v_mfma_f32_16x16x32_bf16 v[44:47], v[140:143], v[200:203], v[44:47]
	v_mfma_f32_16x16x32_bf16 v[20:23], v[144:147], v[200:203], v[20:23]
	v_mfma_f32_16x16x32_bf16 v[236:239], v[148:151], v[200:203], v[236:239]
	v_mfma_f32_16x16x32_bf16 v[108:111], v[204:207], v[200:203], v[108:111]
	ds_read_b128 v[200:203], v212 offset:34816
	s_waitcnt lgkmcnt(5)
	v_mfma_f32_16x16x32_bf16 v[48:51], v[140:143], v[176:179], v[48:51]
	v_mfma_f32_16x16x32_bf16 v[0:3], v[144:147], v[176:179], v[0:3]
	v_mfma_f32_16x16x32_bf16 v[240:243], v[148:151], v[176:179], v[240:243]
	v_mfma_f32_16x16x32_bf16 v[112:115], v[204:207], v[176:179], v[112:115]
	ds_read_b128 v[176:179], v212 offset:36864
	s_waitcnt lgkmcnt(5)
	v_mfma_f32_16x16x32_bf16 v[52:55], v[140:143], v[180:183], v[52:55]
	v_mfma_f32_16x16x32_bf16 v[8:11], v[144:147], v[180:183], v[8:11]
	v_mfma_f32_16x16x32_bf16 v[248:251], v[148:151], v[180:183], v[248:251]
	v_mfma_f32_16x16x32_bf16 v[116:119], v[204:207], v[180:183], v[116:119]
	ds_read_b128 v[180:183], v212 offset:38912
	s_waitcnt lgkmcnt(5)
	v_mfma_f32_16x16x32_bf16 v[56:59], v[140:143], v[184:187], v[56:59]
	v_mfma_f32_16x16x32_bf16 v[24:27], v[144:147], v[184:187], v[24:27]
	v_mfma_f32_16x16x32_bf16 v[252:255], v[148:151], v[184:187], v[252:255]
	v_mfma_f32_16x16x32_bf16 v[120:123], v[204:207], v[184:187], v[120:123]
	ds_read_b128 v[184:187], v212 offset:40960
	s_waitcnt lgkmcnt(5)
	v_mfma_f32_16x16x32_bf16 v[60:63], v[140:143], v[192:195], v[60:63]
	v_mfma_f32_16x16x32_bf16 v[28:31], v[144:147], v[192:195], v[28:31]
	v_mfma_f32_16x16x32_bf16 v[92:95], v[148:151], v[192:195], v[92:95]
	v_mfma_f32_16x16x32_bf16 v[124:127], v[204:207], v[192:195], v[124:127]
	s_waitcnt vmcnt(12)
	s_barrier
	s_waitcnt vmcnt(4)
	ds_read_b128 v[192:195], v212 offset:43008
	global_load_dwordx4 v[140:143], v66, s[84:85] offset:1024
	s_waitcnt lgkmcnt(5)
	v_mfma_f32_16x16x32_bf16 v[32:35], v[160:163], v[196:199], v[32:35]
	v_mfma_f32_16x16x32_bf16 v[4:7], v[164:167], v[196:199], v[4:7]
	v_mfma_f32_16x16x32_bf16 v[188:191], v[168:171], v[196:199], v[188:191]
	v_mfma_f32_16x16x32_bf16 v[96:99], v[172:175], v[196:199], v[96:99]
	ds_read_b128 v[196:199], v212 offset:45056
	global_load_dwordx4 v[144:147], v67, s[84:85] offset:1024
	s_waitcnt lgkmcnt(5)
	v_mfma_f32_16x16x32_bf16 v[36:39], v[160:163], v[200:203], v[36:39]
	v_mfma_f32_16x16x32_bf16 v[12:15], v[164:167], v[200:203], v[12:15]
	v_mfma_f32_16x16x32_bf16 v[208:211], v[168:171], v[200:203], v[208:211]
	v_mfma_f32_16x16x32_bf16 v[100:103], v[172:175], v[200:203], v[100:103]
	ds_read_b128 v[200:203], v212 offset:47104
	global_load_dwordx4 v[148:151], v66, s[92:93] offset:1024
	s_waitcnt lgkmcnt(5)
	v_mfma_f32_16x16x32_bf16 v[40:43], v[160:163], v[176:179], v[40:43]
	v_mfma_f32_16x16x32_bf16 v[16:19], v[164:167], v[176:179], v[16:19]
	v_mfma_f32_16x16x32_bf16 v[232:235], v[168:171], v[176:179], v[232:235]
	v_mfma_f32_16x16x32_bf16 v[104:107], v[172:175], v[176:179], v[104:107]
	ds_read_b128 v[176:179], v75 offset:49152
	global_load_dwordx4 v[204:207], v67, s[92:93] offset:1024
	s_add_u32 s84, s84, 0x800
	s_addc_u32 s85, s85, 0
	s_add_u32 s92, s92, 0x800
	s_addc_u32 s93, s93, 0
	s_waitcnt lgkmcnt(5)
	v_mfma_f32_16x16x32_bf16 v[44:47], v[160:163], v[180:183], v[44:47]
	v_mfma_f32_16x16x32_bf16 v[20:23], v[164:167], v[180:183], v[20:23]
	v_mfma_f32_16x16x32_bf16 v[236:239], v[168:171], v[180:183], v[236:239]
	v_mfma_f32_16x16x32_bf16 v[108:111], v[172:175], v[180:183], v[108:111]
	ds_read_b128 v[180:183], v75 offset:51200
	s_waitcnt lgkmcnt(5)
	v_mfma_f32_16x16x32_bf16 v[48:51], v[160:163], v[184:187], v[48:51]
	v_mfma_f32_16x16x32_bf16 v[0:3], v[164:167], v[184:187], v[0:3]
	v_mfma_f32_16x16x32_bf16 v[240:243], v[168:171], v[184:187], v[240:243]
	v_mfma_f32_16x16x32_bf16 v[112:115], v[172:175], v[184:187], v[112:115]
	ds_read_b128 v[184:187], v75 offset:53248
	s_waitcnt lgkmcnt(5)
	v_mfma_f32_16x16x32_bf16 v[52:55], v[160:163], v[192:195], v[52:55]
	v_mfma_f32_16x16x32_bf16 v[8:11], v[164:167], v[192:195], v[8:11]
	v_mfma_f32_16x16x32_bf16 v[248:251], v[168:171], v[192:195], v[248:251]
	v_mfma_f32_16x16x32_bf16 v[116:119], v[172:175], v[192:195], v[116:119]
	ds_read_b128 v[192:195], v75 offset:55296
	s_waitcnt lgkmcnt(5)
	v_mfma_f32_16x16x32_bf16 v[56:59], v[160:163], v[196:199], v[56:59]
	v_mfma_f32_16x16x32_bf16 v[24:27], v[164:167], v[196:199], v[24:27]
	v_mfma_f32_16x16x32_bf16 v[252:255], v[168:171], v[196:199], v[252:255]
	v_mfma_f32_16x16x32_bf16 v[120:123], v[172:175], v[196:199], v[120:123]
	ds_read_b128 v[196:199], v75 offset:57344
	s_waitcnt lgkmcnt(5)
	v_mfma_f32_16x16x32_bf16 v[60:63], v[160:163], v[200:203], v[60:63]
	v_mfma_f32_16x16x32_bf16 v[28:31], v[164:167], v[200:203], v[28:31]
	v_mfma_f32_16x16x32_bf16 v[92:95], v[168:171], v[200:203], v[92:95]
	v_mfma_f32_16x16x32_bf16 v[124:127], v[172:175], v[200:203], v[124:127]
	s_waitcnt vmcnt(4)
	ds_read_b128 v[200:203], v75 offset:59392
	s_waitcnt lgkmcnt(5)
	v_mfma_f32_16x16x32_bf16 v[32:35], v[76:79], v[176:179], v[32:35]
	v_mfma_f32_16x16x32_bf16 v[4:7], v[80:83], v[176:179], v[4:7]
	v_mfma_f32_16x16x32_bf16 v[188:191], v[84:87], v[176:179], v[188:191]
	v_mfma_f32_16x16x32_bf16 v[96:99], v[88:91], v[176:179], v[96:99]
	ds_read_b128 v[176:179], v75 offset:61440
	s_waitcnt lgkmcnt(5)
	v_mfma_f32_16x16x32_bf16 v[36:39], v[76:79], v[180:183], v[36:39]
	v_mfma_f32_16x16x32_bf16 v[12:15], v[80:83], v[180:183], v[12:15]
	v_mfma_f32_16x16x32_bf16 v[208:211], v[84:87], v[180:183], v[208:211]
	v_mfma_f32_16x16x32_bf16 v[100:103], v[88:91], v[180:183], v[100:103]
	ds_read_b128 v[180:183], v75 offset:63488
	s_waitcnt lgkmcnt(5)
	v_mfma_f32_16x16x32_bf16 v[40:43], v[76:79], v[184:187], v[40:43]
	v_mfma_f32_16x16x32_bf16 v[16:19], v[80:83], v[184:187], v[16:19]
	v_mfma_f32_16x16x32_bf16 v[232:235], v[84:87], v[184:187], v[232:235]
	v_mfma_f32_16x16x32_bf16 v[104:107], v[88:91], v[184:187], v[104:107]
	ds_read_b128 v[184:187], v212 offset:49152
	s_waitcnt lgkmcnt(5)
	v_mfma_f32_16x16x32_bf16 v[44:47], v[76:79], v[192:195], v[44:47]
	v_mfma_f32_16x16x32_bf16 v[20:23], v[80:83], v[192:195], v[20:23]
	v_mfma_f32_16x16x32_bf16 v[236:239], v[84:87], v[192:195], v[236:239]
	v_mfma_f32_16x16x32_bf16 v[108:111], v[88:91], v[192:195], v[108:111]
	ds_read_b128 v[192:195], v212 offset:51200
	s_waitcnt lgkmcnt(5)
	v_mfma_f32_16x16x32_bf16 v[48:51], v[76:79], v[196:199], v[48:51]
	v_mfma_f32_16x16x32_bf16 v[0:3], v[80:83], v[196:199], v[0:3]
	v_mfma_f32_16x16x32_bf16 v[240:243], v[84:87], v[196:199], v[240:243]
	v_mfma_f32_16x16x32_bf16 v[112:115], v[88:91], v[196:199], v[112:115]
	ds_read_b128 v[196:199], v212 offset:53248
	s_waitcnt lgkmcnt(5)
	v_mfma_f32_16x16x32_bf16 v[52:55], v[76:79], v[200:203], v[52:55]
	v_mfma_f32_16x16x32_bf16 v[8:11], v[80:83], v[200:203], v[8:11]
	v_mfma_f32_16x16x32_bf16 v[248:251], v[84:87], v[200:203], v[248:251]
	v_mfma_f32_16x16x32_bf16 v[116:119], v[88:91], v[200:203], v[116:119]
	ds_read_b128 v[200:203], v212 offset:55296
	s_waitcnt lgkmcnt(5)
	v_mfma_f32_16x16x32_bf16 v[56:59], v[76:79], v[176:179], v[56:59]
	v_mfma_f32_16x16x32_bf16 v[24:27], v[80:83], v[176:179], v[24:27]
	v_mfma_f32_16x16x32_bf16 v[252:255], v[84:87], v[176:179], v[252:255]
	v_mfma_f32_16x16x32_bf16 v[120:123], v[88:91], v[176:179], v[120:123]
	ds_read_b128 v[176:179], v212 offset:57344
	s_waitcnt lgkmcnt(5)
	v_mfma_f32_16x16x32_bf16 v[60:63], v[76:79], v[180:183], v[60:63]
	v_mfma_f32_16x16x32_bf16 v[28:31], v[80:83], v[180:183], v[28:31]
	v_mfma_f32_16x16x32_bf16 v[92:95], v[84:87], v[180:183], v[92:95]
	v_mfma_f32_16x16x32_bf16 v[124:127], v[88:91], v[180:183], v[124:127]
	s_waitcnt vmcnt(0)
	ds_read_b128 v[180:183], v212 offset:59392
	s_waitcnt lgkmcnt(5)
	v_mfma_f32_16x16x32_bf16 v[32:35], v[140:143], v[184:187], v[32:35]
	v_mfma_f32_16x16x32_bf16 v[4:7], v[144:147], v[184:187], v[4:7]
	v_mfma_f32_16x16x32_bf16 v[188:191], v[148:151], v[184:187], v[188:191]
	v_mfma_f32_16x16x32_bf16 v[96:99], v[204:207], v[184:187], v[96:99]
	ds_read_b128 v[184:187], v212 offset:61440
	s_waitcnt lgkmcnt(5)
	v_mfma_f32_16x16x32_bf16 v[36:39], v[140:143], v[192:195], v[36:39]
	v_mfma_f32_16x16x32_bf16 v[12:15], v[144:147], v[192:195], v[12:15]
	v_mfma_f32_16x16x32_bf16 v[208:211], v[148:151], v[192:195], v[208:211]
	v_mfma_f32_16x16x32_bf16 v[100:103], v[204:207], v[192:195], v[100:103]
	ds_read_b128 v[192:195], v212 offset:63488
	s_waitcnt lgkmcnt(5)
	v_mfma_f32_16x16x32_bf16 v[40:43], v[140:143], v[196:199], v[40:43]
	v_mfma_f32_16x16x32_bf16 v[16:19], v[144:147], v[196:199], v[16:19]
	v_mfma_f32_16x16x32_bf16 v[232:235], v[148:151], v[196:199], v[232:235]
	v_mfma_f32_16x16x32_bf16 v[104:107], v[204:207], v[196:199], v[104:107]
	s_waitcnt lgkmcnt(4)
	v_mfma_f32_16x16x32_bf16 v[44:47], v[140:143], v[200:203], v[44:47]
	v_mfma_f32_16x16x32_bf16 v[20:23], v[144:147], v[200:203], v[20:23]
	v_mfma_f32_16x16x32_bf16 v[236:239], v[148:151], v[200:203], v[236:239]
	v_mfma_f32_16x16x32_bf16 v[108:111], v[204:207], v[200:203], v[108:111]
	s_waitcnt lgkmcnt(3)
	v_mfma_f32_16x16x32_bf16 v[48:51], v[140:143], v[176:179], v[48:51]
	v_mfma_f32_16x16x32_bf16 v[0:3], v[144:147], v[176:179], v[0:3]
	v_mfma_f32_16x16x32_bf16 v[240:243], v[148:151], v[176:179], v[240:243]
	v_mfma_f32_16x16x32_bf16 v[112:115], v[204:207], v[176:179], v[112:115]
	s_waitcnt lgkmcnt(2)
	v_mfma_f32_16x16x32_bf16 v[52:55], v[140:143], v[180:183], v[52:55]
	v_mfma_f32_16x16x32_bf16 v[8:11], v[144:147], v[180:183], v[8:11]
	v_mfma_f32_16x16x32_bf16 v[248:251], v[148:151], v[180:183], v[248:251]
	v_mfma_f32_16x16x32_bf16 v[116:119], v[204:207], v[180:183], v[116:119]
	s_waitcnt lgkmcnt(1)
	v_mfma_f32_16x16x32_bf16 v[56:59], v[140:143], v[184:187], v[56:59]
	v_mfma_f32_16x16x32_bf16 v[24:27], v[144:147], v[184:187], v[24:27]
	v_mfma_f32_16x16x32_bf16 v[252:255], v[148:151], v[184:187], v[252:255]
	v_mfma_f32_16x16x32_bf16 v[120:123], v[204:207], v[184:187], v[120:123]
	s_waitcnt lgkmcnt(0)
	v_mfma_f32_16x16x32_bf16 v[60:63], v[140:143], v[192:195], v[60:63]
	v_mfma_f32_16x16x32_bf16 v[28:31], v[144:147], v[192:195], v[28:31]
	v_mfma_f32_16x16x32_bf16 v[92:95], v[148:151], v[192:195], v[92:95]
	v_mfma_f32_16x16x32_bf16 v[124:127], v[204:207], v[192:195], v[124:127]
	s_nop 7
	s_nop 7
	s_waitcnt vmcnt(0) lgkmcnt(0)
	s_barrier
	v_mov_b32_e32 v66, v92
	v_mov_b32_e32 v67, v93
	v_mov_b32_e32 v68, v94
	v_mov_b32_e32 v69, v95
	v_mov_b32_e32 v71, v96
	v_mov_b32_e32 v74, v97
	v_mov_b32_e32 v75, v98
	v_mov_b32_e32 v160, v99
	v_mov_b32_e32 v161, v100
	v_mov_b32_e32 v162, v101
	v_mov_b32_e32 v185, v102
	v_mov_b32_e32 v186, v103
	v_mov_b32_e32 v187, v104
	v_mov_b32_e32 v207, v105
	v_mov_b32_e32 v212, v106
	v_mov_b32_e32 v213, v107
	v_mov_b32_e32 v214, v108
	v_mov_b32_e32 v216, v109
	v_mov_b32_e32 v218, v110
	v_mov_b32_e32 v220, v111
	v_mov_b32_e32 v222, v112
	v_mov_b32_e32 v224, v113
	v_mov_b32_e32 v226, v114
	v_mov_b32_e32 v228, v115
	v_mov_b32_e32 v230, v116
	v_mov_b32_e32 v231, v117
	v_mov_b32_e32 v244, v118
	v_mov_b32_e32 v245, v119
	ds_write_b128 v129, v[120:123] offset:36864
	ds_write_b128 v129, v[124:127] offset:40960
	v_lshlrev_b32_e32 v77, 13, v135
	v_lshl_add_u32 v78, v134, 3, v138
	v_lshl_or_b32 v79, v134, 11, v77
	v_lshlrev_b32_e32 v81, 5, v138
	v_or3_b32 v163, v77, v137, v81
	v_lshl_or_b32 v164, v78, 2, v79
	v_add_u32_e32 v81, 0x60, v78
	v_add_u32_e32 v78, 0x70, v78
	v_and_b32_e32 v81, 0x7f, v81
	v_and_b32_e32 v78, 0x7f, v78
	v_lshl_or_b32 v165, v81, 2, v79
	v_lshl_or_b32 v166, v78, 2, v79
	v_add_u32_e32 v79, 8, v133
	v_and_b32_e32 v79, 0x78, v79
	v_lshlrev_b32_e32 v78, 9, v136
	v_lshlrev_b32_e32 v79, 2, v79
	v_or3_b32 v168, v77, v78, v79
	v_add_u32_e32 v79, 16, v133
	v_and_b32_e32 v79, 0x78, v79
	v_lshlrev_b32_e32 v78, 9, v132
	v_lshlrev_b32_e32 v79, 2, v79
	v_or3_b32 v170, v77, v78, v79
	v_add_u32_e32 v79, 24, v133
	v_and_b32_e32 v79, 0x78, v79
	v_lshlrev_b32_e32 v80, 5, v135
	v_lshlrev_b32_e32 v78, 9, v130
	v_lshlrev_b32_e32 v79, 2, v79
	v_or3_b32 v172, v77, v78, v79
	v_or_b32_e32 v77, 16, v80
	v_add_u32_e32 v81, 0x100, v131
	v_add_u32_e32 v82, 0x200, v131
	v_add_u32_e32 v83, 0x300, v131
	v_add_u32_e32 v84, 0x500, v131
	v_add_u32_e32 v85, 0x600, v131
	v_add_u32_e32 v86, 0x700, v131
	v_or_b32_e32 v174, v77, v134
	v_or_b32_e32 v175, v136, v77
	v_or_b32_e32 v176, v132, v77
	v_or_b32_e32 v177, v130, v77
	v_and_b32_e32 v77, 24, v153
	s_movk_i32 s94, 0x3c0
	v_lshrrev_b32_e32 v178, 4, v81
	v_lshrrev_b32_e32 v179, 4, v82
	v_lshrrev_b32_e32 v180, 4, v83
	v_lshrrev_b32_e32 v182, 4, v84
	v_lshrrev_b32_e32 v183, 4, v85
	v_lshrrev_b32_e32 v184, 4, v86
	v_or_b32_e32 v167, v134, v80
	v_or_b32_e32 v169, v136, v80
	v_or_b32_e32 v171, v132, v80
	v_or_b32_e32 v173, v130, v80
	v_and_or_b32 v77, v131, s94, v77
	v_mul_u32_u24_e32 v78, 0x110, v138
	v_lshlrev_b32_e32 v79, 4, v138
	v_mul_u32_u24_e32 v80, 0x110, v128
	v_mul_u32_u24_e32 v81, 0x110, v178
	v_mul_u32_u24_e32 v82, 0x110, v179
	v_mul_u32_u24_e32 v83, 0x110, v180
	v_mul_u32_u24_e32 v84, 0x110, v182
	v_mul_u32_u24_e32 v85, 0x110, v183
	v_mul_u32_u24_e32 v86, 0x110, v184
	v_or_b32_e32 v181, 64, v128
	v_lshlrev_b32_e32 v192, 2, v138
	v_add_u32_e32 v193, v77, v78
	v_add_u32_e32 v194, v79, v80
	v_add_u32_e32 v195, v79, v81
	v_add_u32_e32 v196, v79, v82
	v_add_u32_e32 v197, v79, v83
	v_add_u32_e32 v198, v79, v84
	v_add_u32_e32 v199, v79, v85
	v_add_u32_e32 v200, v79, v86
	v_mbcnt_hi_u32_b32 v201, -1, v155
	v_mov_b32_e32 v202, 0x3db504f3
	s_waitcnt lgkmcnt(0)
	s_mov_b64 s[58:59], -1
	s_cmp_lt_i32 s65, 4
	s_branch .Lmy_ip1_epi
